# plus: HID L0 row pitch padded (33024 B) + cached-scale lean epilogue for MLP-up L0 + residual epilogues: qss loads hoisted, row-sum atomics deferred, vmcnt recounted
# speedup vs baseline: 1.0093x; 1.0051x over previous
.LBB0_454:
	v_lshl_add_u32 v174, s26, 8, v190
	v_lshl_or_b32 v168, s28, 8, v192
	v_ashrrev_i32_e32 v169, 31, v168
	v_ashrrev_i32_e32 v175, 31, v174
	v_lshl_add_u64 v[172:173], v[168:169], 1, s[6:7]
	v_lshlrev_b64 v[112:113], 13, v[174:175]
	v_lshl_add_u64 v[170:171], v[174:175], 3, s[12:13]
	v_lshl_add_u64 v[188:189], v[172:173], 0, v[112:113]
	global_load_dwordx2 v[208:209], v[170:171], off
	global_load_dwordx2 v[232:233], v[170:171], off offset:128
	global_load_dwordx2 v[234:235], v[170:171], off offset:256
	global_load_dwordx2 v[236:237], v[170:171], off offset:384
	global_load_dwordx2 v[238:239], v[170:171], off offset:1024
	global_load_dwordx2 v[240:241], v[170:171], off offset:1152
	global_load_dwordx2 v[242:243], v[170:171], off offset:1280
	global_load_dwordx2 v[244:245], v[170:171], off offset:1408
	global_load_dwordx4 v[200:203], v[188:189], off
	v_or_b32_e32 v184, 16, v174
	v_or_b32_e32 v180, 32, v174
	v_or_b32_e32 v176, 48, v174
	v_ashrrev_i32_e32 v185, 31, v184
	v_ashrrev_i32_e32 v181, 31, v180
	v_ashrrev_i32_e32 v177, 31, v176
	v_lshlrev_b64 v[112:113], 12, v[174:175]
	v_lshlrev_b64 v[114:115], 13, v[184:185]
	v_lshlrev_b64 v[124:125], 13, v[180:181]
	v_lshlrev_b64 v[126:127], 13, v[176:177]
	v_lshl_add_u64 v[112:113], v[112:113], 0, v[168:169]
	v_lshl_add_u64 v[186:187], v[172:173], 0, v[114:115]
	v_lshl_add_u64 v[182:183], v[172:173], 0, v[124:125]
	v_lshl_add_u64 v[178:179], v[172:173], 0, v[126:127]
	v_lshl_add_u64 v[210:211], s[10:11], 0, v[112:113]
	global_load_dwordx4 v[204:207], v[188:189], off offset:256
	global_load_dwordx4 v[148:151], v[186:187], off
	global_load_dwordx4 v[144:147], v[186:187], off offset:256
	global_load_dwordx4 v[140:143], v[182:183], off
	global_load_dwordx4 v[136:139], v[182:183], off offset:256
	global_load_dwordx4 v[124:127], v[178:179], off
	global_load_dwordx4 v[112:115], v[178:179], off offset:256
	s_waitcnt vmcnt(0)
	v_ffbh_u32_e32 v199, v209
	v_min_u32_e32 v199, 32, v199
	v_lshlrev_b64 v[208:209], v199, v[208:209]
	v_min_u32_e32 v208, 1, v208
	v_or_b32_e32 v208, v209, v208
	v_cvt_f32_u32_e32 v208, v208
	v_lshlrev_b32_e32 v212, 16, v200
	v_and_b32_e32 v213, 0xffff0000, v200
	v_lshlrev_b32_e32 v200, 16, v201
	v_and_b32_e32 v201, 0xffff0000, v201
	v_lshlrev_b32_e32 v214, 16, v202
	v_and_b32_e32 v215, 0xffff0000, v202
	v_lshlrev_b32_e32 v202, 16, v203
	v_and_b32_e32 v203, 0xffff0000, v203
	v_pk_add_f32 v[134:135], v[134:135], v[200:201]
	v_pk_add_f32 v[132:133], v[132:133], v[212:213]
	v_pk_add_f32 v[200:201], v[130:131], v[202:203]
	v_pk_add_f32 v[202:203], v[128:129], v[214:215]
	v_sub_u32_e32 v199, 32, v199
	v_cvt_pk_bf16_f32 v128, v132, v133
	v_cvt_pk_bf16_f32 v129, v134, v135
	v_cvt_pk_bf16_f32 v130, v202, v203
	v_cvt_pk_bf16_f32 v131, v200, v201
	global_store_dwordx4 v[188:189], v[128:131], off
	v_mul_f32_e32 v212, v133, v133
	v_mul_f32_e32 v213, v135, v135
	v_ldexp_f32 v128, v208, v199
	v_fmamk_f32 v128, v128, 0x2f800000, v196
	v_rsq_f32_e32 v128, v128
	v_mul_f32_e32 v214, v203, v203
	v_fmac_f32_e32 v212, v132, v132
	v_fmac_f32_e32 v213, v134, v134
	v_fmac_f32_e32 v214, v202, v202
	v_add_f32_e32 v129, v212, v213
	v_mul_f32_e32 v199, 0x41ca3ab3, v128
	v_add_f32_e32 v130, v214, v129
	v_mul_f32_e32 v128, v199, v132
	v_mul_f32_e32 v129, v199, v133
	v_mul_f32_e32 v131, v199, v134
	v_mul_f32_e32 v132, v199, v135
	v_mul_f32_e32 v134, v199, v203
	v_mul_f32_e32 v133, v199, v202
	v_mul_f32_e32 v135, v199, v200
	v_mul_f32_e32 v202, v199, v201
	v_med3_f32 v128, v128, s52, v198
	v_med3_f32 v129, v129, s52, v198
	v_med3_f32 v132, v132, s52, v198
	v_med3_f32 v134, v134, s52, v198
	v_med3_f32 v131, v131, s52, v198
	v_med3_f32 v133, v133, s52, v198
	v_med3_f32 v135, v135, s52, v198
	v_med3_f32 v202, v202, s52, v198
	v_rndne_f32_e32 v128, v128
	v_rndne_f32_e32 v129, v129
	v_rndne_f32_e32 v132, v132
	v_rndne_f32_e32 v134, v134
	v_rndne_f32_e32 v131, v131
	v_rndne_f32_e32 v133, v133
	v_rndne_f32_e32 v135, v135
	v_rndne_f32_e32 v202, v202
	v_cvt_i32_f32_e32 v128, v128
	v_cvt_i32_f32_e32 v129, v129
	v_cvt_i32_f32_e32 v132, v132
	v_cvt_i32_f32_e32 v134, v134
	v_cvt_i32_f32_sdwa v131, v131 dst_sel:WORD_1 dst_unused:UNUSED_PAD src0_sel:DWORD
	v_cvt_i32_f32_e32 v133, v133
	v_cvt_i32_f32_sdwa v135, v135 dst_sel:WORD_1 dst_unused:UNUSED_PAD src0_sel:DWORD
	v_cvt_i32_f32_e32 v202, v202
	v_lshlrev_b32_e32 v129, 8, v129
	v_perm_b32 v128, v132, v128, s53
	v_lshlrev_b32_e32 v132, 8, v134
	v_and_b32_e32 v131, 0xff0000, v131
	v_and_b32_e32 v134, 0xff0000, v135
	v_perm_b32 v133, v202, v133, s53
	v_and_b32_e32 v129, 0xff00, v129
	v_and_b32_e32 v132, 0xff00, v132
	v_or3_b32 v128, v128, v129, v131
	v_or3_b32 v129, v133, v132, v134
	global_store_dwordx2 v[210:211], v[128:129], off
	v_mul_f32_e32 v128, v201, v201
	v_fmac_f32_e32 v128, v200, v200
	v_add_f32_e32 v200, v128, v130
	v_lshlrev_b32_e32 v128, 16, v204
	v_and_b32_e32 v129, 0xffff0000, v204
	v_lshlrev_b32_e32 v130, 16, v205
	v_and_b32_e32 v131, 0xffff0000, v205
	v_lshlrev_b32_e32 v132, 16, v206
	v_and_b32_e32 v133, 0xffff0000, v206
	v_lshlrev_b32_e32 v134, 16, v207
	v_and_b32_e32 v135, 0xffff0000, v207
	v_pk_add_f32 v[122:123], v[122:123], v[130:131]
	v_pk_add_f32 v[120:121], v[120:121], v[128:129]
	v_pk_add_f32 v[130:131], v[116:117], v[132:133]
	v_cvt_pk_bf16_f32 v116, v120, v121
	v_cvt_pk_bf16_f32 v117, v122, v123
	v_pk_add_f32 v[128:129], v[118:119], v[134:135]
	v_cvt_pk_bf16_f32 v118, v130, v131
	s_nop 0
	v_cvt_pk_bf16_f32 v119, v128, v129
	global_store_dwordx4 v[188:189], v[116:119], off offset:256
	s_nop 1
	v_mul_f32_e32 v117, v199, v121
	v_mul_f32_e32 v116, v199, v120
	v_mul_f32_e32 v118, v199, v122
	v_mul_f32_e32 v119, v199, v123
	v_med3_f32 v117, v117, s52, v198
	v_med3_f32 v116, v116, s52, v198
	v_rndne_f32_e32 v117, v117
	v_med3_f32 v118, v118, s52, v198
	v_med3_f32 v119, v119, s52, v198
	v_rndne_f32_e32 v116, v116
	v_cvt_i32_f32_e32 v117, v117
	v_rndne_f32_e32 v118, v118
	v_rndne_f32_e32 v119, v119
	v_cvt_i32_f32_e32 v116, v116
	v_cvt_i32_f32_sdwa v118, v118 dst_sel:WORD_1 dst_unused:UNUSED_PAD src0_sel:DWORD
	v_cvt_i32_f32_e32 v119, v119
	v_lshlrev_b32_e32 v117, 8, v117
	v_and_b32_e32 v117, 0xff00, v117
	v_and_b32_e32 v118, 0xff0000, v118
	v_perm_b32 v116, v119, v116, s53
	v_or3_b32 v132, v116, v117, v118
	v_mul_f32_e32 v117, v199, v131
	v_med3_f32 v117, v117, s52, v198
	v_rndne_f32_e32 v117, v117
	v_cvt_i32_f32_e32 v117, v117
	v_mul_f32_e32 v116, v199, v130
	v_med3_f32 v116, v116, s52, v198
	v_rndne_f32_e32 v116, v116
	v_mul_f32_e32 v118, v199, v128
	v_cvt_i32_f32_e32 v133, v116
	v_lshlrev_b32_e32 v116, 8, v117
	v_and_b32_e32 v134, 0xff00, v116
	v_med3_f32 v116, v118, s52, v198
	v_rndne_f32_e32 v117, v116
	v_mul_f32_e32 v116, v121, v121
	v_mul_f32_e32 v118, v123, v123
	v_fmac_f32_e32 v116, v120, v120
	v_fmac_f32_e32 v118, v122, v122
	v_add_f32_e32 v116, v116, v118
	v_mul_f32_e32 v118, v131, v131
	v_fmac_f32_e32 v118, v130, v130
	v_add_f32_e32 v116, v118, v116
	v_mul_f32_e32 v118, v129, v129
	v_fmac_f32_e32 v118, v128, v128
	v_add_f32_e32 v116, v118, v116
	v_and_b32_e32 v120, 64, v197
	v_add_f32_e32 v118, v200, v116
	v_xor_b32_e32 v116, 16, v197
	v_add_u32_e32 v120, 64, v120
	v_cmp_lt_i32_e32 vcc, v116, v120
	v_mul_f32_e32 v119, v199, v129
	v_cvt_i32_f32_sdwa v122, v117 dst_sel:WORD_1 dst_unused:UNUSED_PAD src0_sel:DWORD
	v_cndmask_b32_e32 v116, v197, v116, vcc
	v_lshlrev_b32_e32 v116, 2, v116
	ds_bpermute_b32 v121, v116, v118
	v_med3_f32 v117, v119, s52, v198
	v_rndne_f32_e32 v117, v117
	v_cvt_i32_f32_e32 v123, v117
	v_xor_b32_e32 v117, 32, v197
	v_cmp_lt_i32_e32 vcc, v117, v120
	s_waitcnt lgkmcnt(0)
	v_add_f32_e32 v118, v118, v121
	v_and_b32_e32 v120, 0xff0000, v122
	v_cndmask_b32_e32 v117, v197, v117, vcc
	v_lshlrev_b32_e32 v117, 2, v117
	ds_bpermute_b32 v119, v117, v118
	v_perm_b32 v121, v123, v133, s53
	v_or3_b32 v133, v121, v134, v120
	global_store_dwordx2 v[210:211], v[132:133], off offset:128
	s_and_saveexec_b64 s[26:27], s[2:3]
	s_cbranch_execz .LBB0_456
	s_waitcnt lgkmcnt(0)
	v_add_f32_e32 v118, v118, v119
	v_fma_f32 v118, v118, s54, 0.5
	v_trunc_f32_e32 v118, v118
	v_mul_f32_e32 v119, 0x2f800000, v118
	v_floor_f32_e32 v119, v119
	v_fmac_f32_e32 v118, 0xcf800000, v119
	v_cvt_u32_f32_e32 v118, v118
	v_cvt_u32_f32_e32 v119, v119
	v_lshl_add_u64 v[120:121], v[174:175], 3, s[8:9]
	v_mov_b32_e32 v228, v120
	v_mov_b32_e32 v229, v121
	v_mov_b32_e32 v246, v118
	v_mov_b32_e32 v247, v119
.LBB0_456:
	s_or_b64 exec, exec, s[26:27]
	s_waitcnt lgkmcnt(0)
	v_lshl_add_u64 v[118:119], v[184:185], 3, s[12:13]
	v_mov_b32_e32 v118, v232
	v_mov_b32_e32 v119, v233
	v_lshlrev_b32_e32 v122, 16, v148
	v_and_b32_e32 v123, 0xffff0000, v148
	v_lshlrev_b32_e32 v128, 16, v149
	v_and_b32_e32 v129, 0xffff0000, v149
	v_lshlrev_b32_e32 v148, 16, v146
	v_and_b32_e32 v149, 0xffff0000, v146
	v_lshlrev_b32_e32 v130, 16, v150
	v_and_b32_e32 v131, 0xffff0000, v150
	v_lshlrev_b32_e32 v132, 16, v151
	v_and_b32_e32 v133, 0xffff0000, v151
	v_lshlrev_b32_e32 v146, 16, v147
	v_and_b32_e32 v147, 0xffff0000, v147
	v_pk_add_f32 v[110:111], v[110:111], v[128:129]
	v_pk_add_f32 v[108:109], v[108:109], v[122:123]
	v_pk_add_f32 v[128:129], v[96:97], v[148:149]
	v_cvt_pk_bf16_f32 v96, v108, v109
	v_pk_add_f32 v[106:107], v[106:107], v[132:133]
	v_pk_add_f32 v[104:105], v[104:105], v[130:131]
	v_pk_add_f32 v[122:123], v[98:99], v[146:147]
	v_cvt_pk_bf16_f32 v97, v110, v111
	v_cvt_pk_bf16_f32 v98, v104, v105
	v_cvt_pk_bf16_f32 v99, v106, v107
	global_store_dwordx4 v[186:187], v[96:99], off
	v_mul_f32_e32 v130, v109, v109
	v_mul_f32_e32 v131, v111, v111
	v_mul_f32_e32 v132, v105, v105
	v_fmac_f32_e32 v130, v108, v108
	v_fmac_f32_e32 v131, v110, v110
	v_mul_f32_e32 v133, v107, v107
	v_fmac_f32_e32 v132, v104, v104
	v_fmac_f32_e32 v133, v106, v106
	v_lshlrev_b64 v[120:121], 12, v[184:185]
	v_lshlrev_b32_e32 v134, 16, v144
	v_and_b32_e32 v135, 0xffff0000, v144
	v_lshl_add_u64 v[120:121], v[120:121], 0, v[168:169]
	v_lshlrev_b32_e32 v144, 16, v145
	v_and_b32_e32 v145, 0xffff0000, v145
	v_pk_add_f32 v[100:101], v[100:101], v[134:135]
	v_lshl_add_u64 v[120:121], s[10:11], 0, v[120:121]
	v_pk_add_f32 v[102:103], v[102:103], v[144:145]
	v_ffbh_u32_e32 v96, v119
	v_min_u32_e32 v98, 32, v96
	v_lshlrev_b64 v[96:97], v98, v[118:119]
	v_min_u32_e32 v96, 1, v96
	v_or_b32_e32 v96, v97, v96
	v_cvt_f32_u32_e32 v96, v96
	v_sub_u32_e32 v97, 32, v98
	v_ldexp_f32 v96, v96, v97
	v_fmamk_f32 v96, v96, 0x2f800000, v196
	v_rsq_f32_e32 v96, v96
	v_add_f32_e32 v97, v130, v131
	v_add_f32_e32 v97, v132, v97
	v_add_f32_e32 v118, v133, v97
	v_mul_f32_e32 v119, 0x41ca3ab3, v96
	v_mul_f32_e32 v96, v108, v119
	v_mul_f32_e32 v97, v109, v119
	v_mul_f32_e32 v99, v111, v119
	v_mul_f32_e32 v105, v105, v119
	v_mul_f32_e32 v98, v110, v119
	v_mul_f32_e32 v104, v104, v119
	v_mul_f32_e32 v106, v106, v119
	v_mul_f32_e32 v107, v107, v119
	v_med3_f32 v96, v96, s52, v198
	v_med3_f32 v97, v97, s52, v198
	v_med3_f32 v99, v99, s52, v198
	v_med3_f32 v105, v105, s52, v198
	v_med3_f32 v98, v98, s52, v198
	v_med3_f32 v104, v104, s52, v198
	v_med3_f32 v106, v106, s52, v198
	v_med3_f32 v107, v107, s52, v198
	v_rndne_f32_e32 v96, v96
	v_rndne_f32_e32 v97, v97
	v_rndne_f32_e32 v99, v99
	v_rndne_f32_e32 v105, v105
	v_rndne_f32_e32 v98, v98
	v_rndne_f32_e32 v104, v104
	v_rndne_f32_e32 v106, v106
	v_rndne_f32_e32 v107, v107
	v_cvt_i32_f32_e32 v96, v96
	v_cvt_i32_f32_e32 v97, v97
	v_cvt_i32_f32_e32 v99, v99
	v_cvt_i32_f32_e32 v105, v105
	v_cvt_i32_f32_sdwa v98, v98 dst_sel:WORD_1 dst_unused:UNUSED_PAD src0_sel:DWORD
	v_cvt_i32_f32_e32 v104, v104
	v_cvt_i32_f32_sdwa v106, v106 dst_sel:WORD_1 dst_unused:UNUSED_PAD src0_sel:DWORD
	v_cvt_i32_f32_e32 v107, v107
	v_lshlrev_b32_e32 v97, 8, v97
	v_perm_b32 v96, v99, v96, s53
	v_lshlrev_b32_e32 v99, 8, v105
	v_and_b32_e32 v98, 0xff0000, v98
	v_and_b32_e32 v105, 0xff0000, v106
	v_perm_b32 v104, v107, v104, s53
	v_and_b32_e32 v97, 0xff00, v97
	v_and_b32_e32 v99, 0xff00, v99
	v_or3_b32 v96, v96, v97, v98
	v_or3_b32 v97, v104, v99, v105
	v_mul_f32_e32 v109, v101, v119
	global_store_dwordx2 v[120:121], v[96:97], off
	v_cvt_pk_bf16_f32 v96, v100, v101
	v_cvt_pk_bf16_f32 v97, v102, v103
	v_mul_f32_e32 v108, v100, v119
	v_mul_f32_e32 v110, v102, v119
	v_mul_f32_e32 v111, v103, v119
	v_cvt_pk_bf16_f32 v98, v128, v129
	v_cvt_pk_bf16_f32 v99, v122, v123
	global_store_dwordx4 v[186:187], v[96:99], off offset:256
	v_med3_f32 v108, v108, s52, v198
	v_mul_f32_e32 v104, v123, v119
	v_med3_f32 v97, v109, s52, v198
	v_rndne_f32_e32 v97, v97
	v_med3_f32 v98, v110, s52, v198
	v_med3_f32 v99, v111, s52, v198
	v_rndne_f32_e32 v96, v108
	v_cvt_i32_f32_e32 v97, v97
	v_rndne_f32_e32 v98, v98
	v_rndne_f32_e32 v99, v99
	v_cvt_i32_f32_e32 v96, v96
	v_cvt_i32_f32_sdwa v98, v98 dst_sel:WORD_1 dst_unused:UNUSED_PAD src0_sel:DWORD
	v_cvt_i32_f32_e32 v99, v99
	v_lshlrev_b32_e32 v97, 8, v97
	v_and_b32_e32 v97, 0xff00, v97
	v_and_b32_e32 v98, 0xff0000, v98
	v_perm_b32 v96, v99, v96, s53
	v_or3_b32 v98, v96, v97, v98
	v_mul_f32_e32 v97, v129, v119
	v_med3_f32 v97, v97, s52, v198
	v_rndne_f32_e32 v97, v97
	v_cvt_i32_f32_e32 v97, v97
	v_mul_f32_e32 v96, v128, v119
	v_med3_f32 v96, v96, s52, v198
	v_rndne_f32_e32 v96, v96
	v_mul_f32_e32 v99, v122, v119
	v_cvt_i32_f32_e32 v105, v96
	v_lshlrev_b32_e32 v96, 8, v97
	v_and_b32_e32 v106, 0xff00, v96
	v_med3_f32 v96, v99, s52, v198
	v_mul_f32_e32 v97, v101, v101
	v_mul_f32_e32 v99, v103, v103
	v_fmac_f32_e32 v97, v100, v100
	v_fmac_f32_e32 v99, v102, v102
	v_add_f32_e32 v97, v97, v99
	v_mul_f32_e32 v99, v129, v129
	v_fmac_f32_e32 v99, v128, v128
	v_add_f32_e32 v97, v99, v97
	v_mul_f32_e32 v99, v123, v123
	v_fmac_f32_e32 v99, v122, v122
	v_add_f32_e32 v97, v99, v97
	v_add_f32_e32 v97, v118, v97
	ds_bpermute_b32 v99, v116, v97
	v_rndne_f32_e32 v96, v96
	v_cvt_i32_f32_sdwa v100, v96 dst_sel:WORD_1 dst_unused:UNUSED_PAD src0_sel:DWORD
	v_med3_f32 v96, v104, s52, v198
	v_rndne_f32_e32 v96, v96
	v_cvt_i32_f32_e32 v101, v96
	s_waitcnt lgkmcnt(0)
	v_add_f32_e32 v96, v97, v99
	ds_bpermute_b32 v97, v117, v96
	v_and_b32_e32 v99, 0xff0000, v100
	v_perm_b32 v100, v101, v105, s53
	v_or3_b32 v99, v100, v106, v99
	global_store_dwordx2 v[120:121], v[98:99], off offset:128
	s_and_saveexec_b64 s[26:27], s[2:3]
	s_cbranch_execz .LBB0_458
	s_waitcnt lgkmcnt(0)
	v_add_f32_e32 v96, v96, v97
	v_fma_f32 v96, v96, s54, 0.5
	v_trunc_f32_e32 v96, v96
	v_mul_f32_e32 v97, 0x2f800000, v96
	v_floor_f32_e32 v97, v97
	v_fmac_f32_e32 v96, 0xcf800000, v97
	v_cvt_u32_f32_e32 v96, v96
	v_cvt_u32_f32_e32 v97, v97
	v_lshl_add_u64 v[98:99], v[184:185], 3, s[8:9]
	v_mov_b32_e32 v248, v96
	v_mov_b32_e32 v249, v97
.LBB0_458:
	s_or_b64 exec, exec, s[26:27]
	s_waitcnt lgkmcnt(0)
	v_lshl_add_u64 v[96:97], v[180:181], 3, s[12:13]
	v_mov_b32_e32 v96, v234
	v_mov_b32_e32 v97, v235
	v_lshlrev_b32_e32 v100, 16, v140
	v_and_b32_e32 v101, 0xffff0000, v140
	v_lshlrev_b32_e32 v102, 16, v141
	v_and_b32_e32 v103, 0xffff0000, v141
	v_lshlrev_b32_e32 v118, 16, v138
	v_and_b32_e32 v119, 0xffff0000, v138
	v_lshlrev_b32_e32 v104, 16, v142
	v_and_b32_e32 v105, 0xffff0000, v142
	v_lshlrev_b32_e32 v106, 16, v143
	v_and_b32_e32 v107, 0xffff0000, v143
	v_lshlrev_b32_e32 v120, 16, v139
	v_and_b32_e32 v121, 0xffff0000, v139
	v_pk_add_f32 v[94:95], v[94:95], v[102:103]
	v_pk_add_f32 v[92:93], v[92:93], v[100:101]
	v_pk_add_f32 v[102:103], v[80:81], v[118:119]
	v_cvt_pk_bf16_f32 v80, v92, v93
	v_pk_add_f32 v[90:91], v[90:91], v[106:107]
	v_pk_add_f32 v[88:89], v[88:89], v[104:105]
	v_pk_add_f32 v[100:101], v[82:83], v[120:121]
	v_cvt_pk_bf16_f32 v81, v94, v95
	v_cvt_pk_bf16_f32 v82, v88, v89
	v_cvt_pk_bf16_f32 v83, v90, v91
	global_store_dwordx4 v[182:183], v[80:83], off
	v_mul_f32_e32 v104, v93, v93
	v_mul_f32_e32 v105, v95, v95
	v_mul_f32_e32 v106, v89, v89
	v_fmac_f32_e32 v104, v92, v92
	v_fmac_f32_e32 v105, v94, v94
	v_mul_f32_e32 v107, v91, v91
	v_fmac_f32_e32 v106, v88, v88
	v_fmac_f32_e32 v107, v90, v90
	v_lshlrev_b64 v[98:99], 12, v[180:181]
	v_lshlrev_b32_e32 v108, 16, v136
	v_and_b32_e32 v109, 0xffff0000, v136
	v_lshl_add_u64 v[98:99], v[98:99], 0, v[168:169]
	v_lshlrev_b32_e32 v110, 16, v137
	v_and_b32_e32 v111, 0xffff0000, v137
	v_pk_add_f32 v[84:85], v[84:85], v[108:109]
	v_lshl_add_u64 v[98:99], s[10:11], 0, v[98:99]
	v_pk_add_f32 v[86:87], v[86:87], v[110:111]
	v_ffbh_u32_e32 v80, v97
	v_min_u32_e32 v82, 32, v80
	v_lshlrev_b64 v[80:81], v82, v[96:97]
	v_min_u32_e32 v80, 1, v80
	v_or_b32_e32 v80, v81, v80
	v_cvt_f32_u32_e32 v80, v80
	v_sub_u32_e32 v81, 32, v82
	v_ldexp_f32 v80, v80, v81
	v_fmamk_f32 v80, v80, 0x2f800000, v196
	v_rsq_f32_e32 v80, v80
	v_add_f32_e32 v81, v104, v105
	v_add_f32_e32 v81, v106, v81
	v_add_f32_e32 v96, v107, v81
	v_mul_f32_e32 v97, 0x41ca3ab3, v80
	v_mul_f32_e32 v80, v92, v97
	v_mul_f32_e32 v81, v93, v97
	v_mul_f32_e32 v83, v95, v97
	v_mul_f32_e32 v89, v89, v97
	v_mul_f32_e32 v82, v94, v97
	v_mul_f32_e32 v88, v88, v97
	v_mul_f32_e32 v90, v90, v97
	v_mul_f32_e32 v91, v91, v97
	v_med3_f32 v80, v80, s52, v198
	v_med3_f32 v81, v81, s52, v198
	v_med3_f32 v83, v83, s52, v198
	v_med3_f32 v89, v89, s52, v198
	v_med3_f32 v82, v82, s52, v198
	v_med3_f32 v88, v88, s52, v198
	v_med3_f32 v90, v90, s52, v198
	v_med3_f32 v91, v91, s52, v198
	v_rndne_f32_e32 v80, v80
	v_rndne_f32_e32 v81, v81
	v_rndne_f32_e32 v83, v83
	v_rndne_f32_e32 v89, v89
	v_rndne_f32_e32 v82, v82
	v_rndne_f32_e32 v88, v88
	v_rndne_f32_e32 v90, v90
	v_rndne_f32_e32 v91, v91
	v_cvt_i32_f32_e32 v80, v80
	v_cvt_i32_f32_e32 v81, v81
	v_cvt_i32_f32_e32 v83, v83
	v_cvt_i32_f32_e32 v89, v89
	v_cvt_i32_f32_sdwa v82, v82 dst_sel:WORD_1 dst_unused:UNUSED_PAD src0_sel:DWORD
	v_cvt_i32_f32_e32 v88, v88
	v_cvt_i32_f32_sdwa v90, v90 dst_sel:WORD_1 dst_unused:UNUSED_PAD src0_sel:DWORD
	v_cvt_i32_f32_e32 v91, v91
	v_lshlrev_b32_e32 v81, 8, v81
	v_perm_b32 v80, v83, v80, s53
	v_lshlrev_b32_e32 v83, 8, v89
	v_and_b32_e32 v82, 0xff0000, v82
	v_and_b32_e32 v89, 0xff0000, v90
	v_perm_b32 v88, v91, v88, s53
	v_and_b32_e32 v81, 0xff00, v81
	v_and_b32_e32 v83, 0xff00, v83
	v_or3_b32 v80, v80, v81, v82
	v_or3_b32 v81, v88, v83, v89
	v_mul_f32_e32 v93, v85, v97
	global_store_dwordx2 v[98:99], v[80:81], off
	v_cvt_pk_bf16_f32 v80, v84, v85
	v_cvt_pk_bf16_f32 v81, v86, v87
	v_mul_f32_e32 v92, v84, v97
	v_mul_f32_e32 v94, v86, v97
	v_mul_f32_e32 v95, v87, v97
	v_cvt_pk_bf16_f32 v82, v102, v103
	v_cvt_pk_bf16_f32 v83, v100, v101
	global_store_dwordx4 v[182:183], v[80:83], off offset:256
	v_med3_f32 v92, v92, s52, v198
	v_mul_f32_e32 v88, v101, v97
	v_med3_f32 v81, v93, s52, v198
	v_rndne_f32_e32 v81, v81
	v_med3_f32 v82, v94, s52, v198
	v_med3_f32 v83, v95, s52, v198
	v_rndne_f32_e32 v80, v92
	v_cvt_i32_f32_e32 v81, v81
	v_rndne_f32_e32 v82, v82
	v_rndne_f32_e32 v83, v83
	v_cvt_i32_f32_e32 v80, v80
	v_cvt_i32_f32_sdwa v82, v82 dst_sel:WORD_1 dst_unused:UNUSED_PAD src0_sel:DWORD
	v_cvt_i32_f32_e32 v83, v83
	v_lshlrev_b32_e32 v81, 8, v81
	v_and_b32_e32 v81, 0xff00, v81
	v_and_b32_e32 v82, 0xff0000, v82
	v_perm_b32 v80, v83, v80, s53
	v_or3_b32 v82, v80, v81, v82
	v_mul_f32_e32 v81, v103, v97
	v_med3_f32 v81, v81, s52, v198
	v_rndne_f32_e32 v81, v81
	v_cvt_i32_f32_e32 v81, v81
	v_mul_f32_e32 v80, v102, v97
	v_med3_f32 v80, v80, s52, v198
	v_rndne_f32_e32 v80, v80
	v_mul_f32_e32 v83, v100, v97
	v_cvt_i32_f32_e32 v89, v80
	v_lshlrev_b32_e32 v80, 8, v81
	v_and_b32_e32 v90, 0xff00, v80
	v_med3_f32 v80, v83, s52, v198
	v_mul_f32_e32 v81, v85, v85
	v_mul_f32_e32 v83, v87, v87
	v_fmac_f32_e32 v81, v84, v84
	v_fmac_f32_e32 v83, v86, v86
	v_add_f32_e32 v81, v81, v83
	v_mul_f32_e32 v83, v103, v103
	v_fmac_f32_e32 v83, v102, v102
	v_add_f32_e32 v81, v83, v81
	v_mul_f32_e32 v83, v101, v101
	v_fmac_f32_e32 v83, v100, v100
	v_add_f32_e32 v81, v83, v81
	v_add_f32_e32 v81, v96, v81
	ds_bpermute_b32 v83, v116, v81
	v_rndne_f32_e32 v80, v80
	v_cvt_i32_f32_sdwa v84, v80 dst_sel:WORD_1 dst_unused:UNUSED_PAD src0_sel:DWORD
	v_med3_f32 v80, v88, s52, v198
	v_rndne_f32_e32 v80, v80
	v_cvt_i32_f32_e32 v85, v80
	s_waitcnt lgkmcnt(0)
	v_add_f32_e32 v80, v81, v83
	ds_bpermute_b32 v81, v117, v80
	v_and_b32_e32 v83, 0xff0000, v84
	v_perm_b32 v84, v85, v89, s53
	v_or3_b32 v83, v84, v90, v83
	global_store_dwordx2 v[98:99], v[82:83], off offset:128
	s_and_saveexec_b64 s[26:27], s[2:3]
	s_cbranch_execz .LBB0_460
	s_waitcnt lgkmcnt(0)
	v_add_f32_e32 v80, v80, v81
	v_fma_f32 v80, v80, s54, 0.5
	v_trunc_f32_e32 v80, v80
	v_mul_f32_e32 v81, 0x2f800000, v80
	v_floor_f32_e32 v81, v81
	v_fmac_f32_e32 v80, 0xcf800000, v81
	v_cvt_u32_f32_e32 v80, v80
	v_cvt_u32_f32_e32 v81, v81
	v_lshl_add_u64 v[82:83], v[180:181], 3, s[8:9]
	v_mov_b32_e32 v250, v80
	v_mov_b32_e32 v251, v81
.LBB0_460:
	s_or_b64 exec, exec, s[26:27]
	s_waitcnt lgkmcnt(0)
	v_lshl_add_u64 v[80:81], v[176:177], 3, s[12:13]
	v_mov_b32_e32 v80, v236
	v_mov_b32_e32 v81, v237
	v_lshlrev_b32_e32 v84, 16, v124
	v_and_b32_e32 v85, 0xffff0000, v124
	v_lshlrev_b32_e32 v86, 16, v125
	v_and_b32_e32 v87, 0xffff0000, v125
	v_lshlrev_b32_e32 v96, 16, v114
	v_and_b32_e32 v97, 0xffff0000, v114
	v_lshlrev_b32_e32 v88, 16, v126
	v_and_b32_e32 v89, 0xffff0000, v126
	v_lshlrev_b32_e32 v90, 16, v127
	v_and_b32_e32 v91, 0xffff0000, v127
	v_lshlrev_b32_e32 v98, 16, v115
	v_and_b32_e32 v99, 0xffff0000, v115
	v_pk_add_f32 v[78:79], v[78:79], v[86:87]
	v_pk_add_f32 v[76:77], v[76:77], v[84:85]
	v_pk_add_f32 v[86:87], v[64:65], v[96:97]
	v_cvt_pk_bf16_f32 v64, v76, v77
	v_pk_add_f32 v[74:75], v[74:75], v[90:91]
	v_pk_add_f32 v[72:73], v[72:73], v[88:89]
	v_pk_add_f32 v[84:85], v[66:67], v[98:99]
	v_cvt_pk_bf16_f32 v65, v78, v79
	v_cvt_pk_bf16_f32 v66, v72, v73
	v_cvt_pk_bf16_f32 v67, v74, v75
	global_store_dwordx4 v[178:179], v[64:67], off
	v_mul_f32_e32 v88, v77, v77
	v_mul_f32_e32 v89, v79, v79
	v_mul_f32_e32 v90, v73, v73
	v_fmac_f32_e32 v88, v76, v76
	v_fmac_f32_e32 v89, v78, v78
	v_mul_f32_e32 v91, v75, v75
	v_fmac_f32_e32 v90, v72, v72
	v_fmac_f32_e32 v91, v74, v74
	v_lshlrev_b64 v[82:83], 12, v[176:177]
	v_lshlrev_b32_e32 v92, 16, v112
	v_and_b32_e32 v93, 0xffff0000, v112
	v_lshl_add_u64 v[82:83], v[82:83], 0, v[168:169]
	v_lshlrev_b32_e32 v94, 16, v113
	v_and_b32_e32 v95, 0xffff0000, v113
	v_pk_add_f32 v[68:69], v[68:69], v[92:93]
	v_lshl_add_u64 v[82:83], s[10:11], 0, v[82:83]
	v_pk_add_f32 v[70:71], v[70:71], v[94:95]
	v_ffbh_u32_e32 v64, v81
	v_min_u32_e32 v66, 32, v64
	v_lshlrev_b64 v[64:65], v66, v[80:81]
	v_min_u32_e32 v64, 1, v64
	v_or_b32_e32 v64, v65, v64
	v_cvt_f32_u32_e32 v64, v64
	v_sub_u32_e32 v65, 32, v66
	v_ldexp_f32 v64, v64, v65
	v_fmamk_f32 v64, v64, 0x2f800000, v196
	v_rsq_f32_e32 v64, v64
	v_add_f32_e32 v65, v88, v89
	v_add_f32_e32 v65, v90, v65
	v_add_f32_e32 v80, v91, v65
	v_mul_f32_e32 v81, 0x41ca3ab3, v64
	v_mul_f32_e32 v64, v76, v81
	v_mul_f32_e32 v65, v77, v81
	v_mul_f32_e32 v67, v79, v81
	v_mul_f32_e32 v73, v73, v81
	v_mul_f32_e32 v66, v78, v81
	v_mul_f32_e32 v72, v72, v81
	v_mul_f32_e32 v74, v74, v81
	v_mul_f32_e32 v75, v75, v81
	v_med3_f32 v64, v64, s52, v198
	v_med3_f32 v65, v65, s52, v198
	v_med3_f32 v67, v67, s52, v198
	v_med3_f32 v73, v73, s52, v198
	v_med3_f32 v66, v66, s52, v198
	v_med3_f32 v72, v72, s52, v198
	v_med3_f32 v74, v74, s52, v198
	v_med3_f32 v75, v75, s52, v198
	v_rndne_f32_e32 v64, v64
	v_rndne_f32_e32 v65, v65
	v_rndne_f32_e32 v67, v67
	v_rndne_f32_e32 v73, v73
	v_rndne_f32_e32 v66, v66
	v_rndne_f32_e32 v72, v72
	v_rndne_f32_e32 v74, v74
	v_rndne_f32_e32 v75, v75
	v_cvt_i32_f32_e32 v64, v64
	v_cvt_i32_f32_e32 v65, v65
	v_cvt_i32_f32_e32 v67, v67
	v_cvt_i32_f32_e32 v73, v73
	v_cvt_i32_f32_sdwa v66, v66 dst_sel:WORD_1 dst_unused:UNUSED_PAD src0_sel:DWORD
	v_cvt_i32_f32_e32 v72, v72
	v_cvt_i32_f32_sdwa v74, v74 dst_sel:WORD_1 dst_unused:UNUSED_PAD src0_sel:DWORD
	v_cvt_i32_f32_e32 v75, v75
	v_lshlrev_b32_e32 v65, 8, v65
	v_perm_b32 v64, v67, v64, s53
	v_lshlrev_b32_e32 v67, 8, v73
	v_and_b32_e32 v66, 0xff0000, v66
	v_and_b32_e32 v73, 0xff0000, v74
	v_perm_b32 v72, v75, v72, s53
	v_and_b32_e32 v65, 0xff00, v65
	v_and_b32_e32 v67, 0xff00, v67
	v_or3_b32 v64, v64, v65, v66
	v_or3_b32 v65, v72, v67, v73
	v_mul_f32_e32 v77, v69, v81
	global_store_dwordx2 v[82:83], v[64:65], off
	v_cvt_pk_bf16_f32 v64, v68, v69
	v_cvt_pk_bf16_f32 v65, v70, v71
	v_mul_f32_e32 v76, v68, v81
	v_mul_f32_e32 v78, v70, v81
	v_mul_f32_e32 v79, v71, v81
	v_cvt_pk_bf16_f32 v66, v86, v87
	v_cvt_pk_bf16_f32 v67, v84, v85
	global_store_dwordx4 v[178:179], v[64:67], off offset:256
	v_med3_f32 v76, v76, s52, v198
	v_mul_f32_e32 v72, v85, v81
	v_med3_f32 v65, v77, s52, v198
	v_rndne_f32_e32 v65, v65
	v_med3_f32 v66, v78, s52, v198
	v_med3_f32 v67, v79, s52, v198
	v_rndne_f32_e32 v64, v76
	v_cvt_i32_f32_e32 v65, v65
	v_rndne_f32_e32 v66, v66
	v_rndne_f32_e32 v67, v67
	v_cvt_i32_f32_e32 v64, v64
	v_cvt_i32_f32_sdwa v66, v66 dst_sel:WORD_1 dst_unused:UNUSED_PAD src0_sel:DWORD
	v_cvt_i32_f32_e32 v67, v67
	v_lshlrev_b32_e32 v65, 8, v65
	v_and_b32_e32 v65, 0xff00, v65
	v_and_b32_e32 v66, 0xff0000, v66
	v_perm_b32 v64, v67, v64, s53
	v_or3_b32 v66, v64, v65, v66
	v_mul_f32_e32 v65, v87, v81
	v_med3_f32 v65, v65, s52, v198
	v_rndne_f32_e32 v65, v65
	v_cvt_i32_f32_e32 v65, v65
	v_mul_f32_e32 v64, v86, v81
	v_med3_f32 v64, v64, s52, v198
	v_rndne_f32_e32 v64, v64
	v_mul_f32_e32 v67, v84, v81
	v_cvt_i32_f32_e32 v73, v64
	v_lshlrev_b32_e32 v64, 8, v65
	v_and_b32_e32 v74, 0xff00, v64
	v_med3_f32 v64, v67, s52, v198
	v_mul_f32_e32 v65, v69, v69
	v_mul_f32_e32 v67, v71, v71
	v_fmac_f32_e32 v65, v68, v68
	v_fmac_f32_e32 v67, v70, v70
	v_add_f32_e32 v65, v65, v67
	v_mul_f32_e32 v67, v87, v87
	v_fmac_f32_e32 v67, v86, v86
	v_add_f32_e32 v65, v67, v65
	v_mul_f32_e32 v67, v85, v85
	v_fmac_f32_e32 v67, v84, v84
	v_add_f32_e32 v65, v67, v65
	v_add_f32_e32 v65, v80, v65
	ds_bpermute_b32 v67, v116, v65
	v_rndne_f32_e32 v64, v64
	v_cvt_i32_f32_sdwa v68, v64 dst_sel:WORD_1 dst_unused:UNUSED_PAD src0_sel:DWORD
	v_med3_f32 v64, v72, s52, v198
	v_rndne_f32_e32 v64, v64
	v_cvt_i32_f32_e32 v69, v64
	s_waitcnt lgkmcnt(0)
	v_add_f32_e32 v64, v65, v67
	ds_bpermute_b32 v65, v117, v64
	v_and_b32_e32 v67, 0xff0000, v68
	v_perm_b32 v68, v69, v73, s53
	v_or3_b32 v67, v68, v74, v67
	global_store_dwordx2 v[82:83], v[66:67], off offset:128
	s_and_saveexec_b64 s[26:27], s[2:3]
	s_cbranch_execz .LBB0_462
	s_waitcnt lgkmcnt(0)
	v_add_f32_e32 v64, v64, v65
	v_fma_f32 v64, v64, s54, 0.5
	v_trunc_f32_e32 v64, v64
	v_mul_f32_e32 v65, 0x2f800000, v64
	v_floor_f32_e32 v65, v65
	v_fmac_f32_e32 v64, 0xcf800000, v65
	v_cvt_u32_f32_e32 v64, v64
	v_cvt_u32_f32_e32 v65, v65
	v_lshl_add_u64 v[66:67], v[176:177], 3, s[8:9]
	v_mov_b32_e32 v252, v64
	v_mov_b32_e32 v253, v65
.LBB0_462:
	s_or_b64 exec, exec, s[26:27]
	v_add_u32_e32 v100, 0x80, v174
	v_ashrrev_i32_e32 v101, 31, v100
	s_waitcnt lgkmcnt(0)
	v_lshlrev_b64 v[64:65], 13, v[100:101]
	v_lshl_add_u64 v[102:103], v[172:173], 0, v[64:65]
	v_mov_b32_e32 v112, v238
	v_mov_b32_e32 v113, v239
	global_load_dwordx4 v[104:107], v[102:103], off
	v_add_u32_e32 v96, 0x90, v174
	v_add_u32_e32 v92, 0xa0, v174
	v_add_u32_e32 v88, 0xb0, v174
	v_ashrrev_i32_e32 v97, 31, v96
	v_ashrrev_i32_e32 v93, 31, v92
	v_ashrrev_i32_e32 v89, 31, v88
	v_lshlrev_b64 v[64:65], 13, v[96:97]
	v_lshlrev_b64 v[66:67], 13, v[92:93]
	v_lshlrev_b64 v[68:69], 13, v[88:89]
	v_lshlrev_b64 v[70:71], 12, v[100:101]
	v_lshl_add_u64 v[98:99], v[172:173], 0, v[64:65]
	v_lshl_add_u64 v[94:95], v[172:173], 0, v[66:67]
	v_lshl_add_u64 v[90:91], v[172:173], 0, v[68:69]
	v_lshl_add_u64 v[114:115], v[70:71], 0, v[168:169]
	global_load_dwordx4 v[108:111], v[102:103], off offset:256
	global_load_dwordx4 v[84:87], v[98:99], off
	global_load_dwordx4 v[80:83], v[98:99], off offset:256
	global_load_dwordx4 v[76:79], v[94:95], off
	global_load_dwordx4 v[72:75], v[94:95], off offset:256
	global_load_dwordx4 v[68:71], v[90:91], off
	global_load_dwordx4 v[64:67], v[90:91], off offset:256
	s_and_saveexec_b64 s[96:97], s[2:3]
	global_atomic_add_x2 v[228:229], v[246:247], off
	global_atomic_add_x2 v[228:229], v[248:249], off offset:128
	global_atomic_add_x2 v[228:229], v[250:251], off offset:256
	global_atomic_add_x2 v[228:229], v[252:253], off offset:384
	s_mov_b64 exec, s[96:97]
	v_lshl_add_u64 v[114:115], s[10:11], 0, v[114:115]
	v_ffbh_u32_e32 v122, v113
	v_min_u32_e32 v122, 32, v122
	s_waitcnt vmcnt(11)
	v_lshlrev_b32_e32 v118, 16, v104
	v_and_b32_e32 v119, 0xffff0000, v104
	v_lshlrev_b32_e32 v104, 16, v105
	v_and_b32_e32 v105, 0xffff0000, v105
	v_lshlrev_b32_e32 v120, 16, v106
	v_and_b32_e32 v121, 0xffff0000, v106
	v_lshlrev_b32_e32 v106, 16, v107
	v_and_b32_e32 v107, 0xffff0000, v107
	v_lshlrev_b64 v[112:113], v122, v[112:113]
	v_pk_add_f32 v[62:63], v[62:63], v[104:105]
	v_pk_add_f32 v[60:61], v[60:61], v[118:119]
	v_pk_add_f32 v[104:105], v[58:59], v[106:107]
	v_pk_add_f32 v[106:107], v[56:57], v[120:121]
	v_cvt_pk_bf16_f32 v56, v60, v61
	v_min_u32_e32 v112, 1, v112
	v_cvt_pk_bf16_f32 v57, v62, v63
	v_cvt_pk_bf16_f32 v58, v106, v107
	v_cvt_pk_bf16_f32 v59, v104, v105
	global_store_dwordx4 v[102:103], v[56:59], off
	v_sub_u32_e32 v118, 32, v122
	v_mul_f32_e32 v119, v61, v61
	v_or_b32_e32 v56, v113, v112
	v_cvt_f32_u32_e32 v56, v56
	v_mul_f32_e32 v120, v63, v63
	v_mul_f32_e32 v121, v107, v107
	v_fmac_f32_e32 v119, v60, v60
	v_ldexp_f32 v56, v56, v118
	v_fmamk_f32 v56, v56, 0x2f800000, v196
	v_rsq_f32_e32 v56, v56
	v_fmac_f32_e32 v120, v62, v62
	v_mul_f32_e32 v122, v105, v105
	v_fmac_f32_e32 v121, v106, v106
	v_add_f32_e32 v57, v119, v120
	v_fmac_f32_e32 v122, v104, v104
	v_add_f32_e32 v57, v121, v57
	v_mul_f32_e32 v113, 0x41ca3ab3, v56
	v_add_f32_e32 v112, v122, v57
	v_mul_f32_e32 v56, v113, v60
	v_mul_f32_e32 v57, v113, v61
	v_mul_f32_e32 v59, v113, v63
	v_mul_f32_e32 v61, v113, v107
	v_mul_f32_e32 v58, v113, v62
	v_mul_f32_e32 v60, v113, v106
	v_mul_f32_e32 v62, v113, v104
	v_mul_f32_e32 v63, v113, v105
	v_med3_f32 v56, v56, s52, v198
	v_med3_f32 v57, v57, s52, v198
	v_med3_f32 v59, v59, s52, v198
	v_med3_f32 v61, v61, s52, v198
	v_med3_f32 v58, v58, s52, v198
	v_med3_f32 v60, v60, s52, v198
	v_med3_f32 v62, v62, s52, v198
	v_med3_f32 v63, v63, s52, v198
	v_rndne_f32_e32 v56, v56
	v_rndne_f32_e32 v57, v57
	v_rndne_f32_e32 v59, v59
	v_rndne_f32_e32 v61, v61
	v_rndne_f32_e32 v58, v58
	v_rndne_f32_e32 v60, v60
	v_rndne_f32_e32 v62, v62
	v_rndne_f32_e32 v63, v63
	v_cvt_i32_f32_e32 v56, v56
	v_cvt_i32_f32_e32 v57, v57
	v_cvt_i32_f32_e32 v59, v59
	v_cvt_i32_f32_e32 v61, v61
	v_cvt_i32_f32_sdwa v58, v58 dst_sel:WORD_1 dst_unused:UNUSED_PAD src0_sel:DWORD
	v_cvt_i32_f32_e32 v60, v60
	v_cvt_i32_f32_sdwa v62, v62 dst_sel:WORD_1 dst_unused:UNUSED_PAD src0_sel:DWORD
	v_cvt_i32_f32_e32 v63, v63
	v_lshlrev_b32_e32 v57, 8, v57
	v_perm_b32 v56, v59, v56, s53
	v_lshlrev_b32_e32 v59, 8, v61
	v_and_b32_e32 v58, 0xff0000, v58
	v_and_b32_e32 v61, 0xff0000, v62
	v_perm_b32 v60, v63, v60, s53
	v_and_b32_e32 v57, 0xff00, v57
	v_and_b32_e32 v59, 0xff00, v59
	v_or3_b32 v56, v56, v57, v58
	v_or3_b32 v57, v60, v59, v61
	global_store_dwordx2 v[114:115], v[56:57], off
	s_waitcnt vmcnt(12)
	v_lshlrev_b32_e32 v56, 16, v108
	v_and_b32_e32 v57, 0xffff0000, v108
	v_lshlrev_b32_e32 v58, 16, v109
	v_and_b32_e32 v59, 0xffff0000, v109
	v_lshlrev_b32_e32 v60, 16, v110
	v_and_b32_e32 v61, 0xffff0000, v110
	v_lshlrev_b32_e32 v62, 16, v111
	v_and_b32_e32 v63, 0xffff0000, v111
	v_pk_add_f32 v[54:55], v[54:55], v[58:59]
	v_pk_add_f32 v[52:53], v[52:53], v[56:57]
	v_pk_add_f32 v[58:59], v[48:49], v[60:61]
	v_cvt_pk_bf16_f32 v48, v52, v53
	v_cvt_pk_bf16_f32 v49, v54, v55
	v_pk_add_f32 v[56:57], v[50:51], v[62:63]
	v_cvt_pk_bf16_f32 v50, v58, v59
	s_nop 0
	v_cvt_pk_bf16_f32 v51, v56, v57
	global_store_dwordx4 v[102:103], v[48:51], off offset:256
	v_mul_f32_e32 v60, v113, v57
	s_nop 0
	v_mul_f32_e32 v49, v113, v53
	v_mul_f32_e32 v48, v113, v52
	v_mul_f32_e32 v50, v113, v54
	v_mul_f32_e32 v51, v113, v55
	v_med3_f32 v49, v49, s52, v198
	v_med3_f32 v48, v48, s52, v198
	v_rndne_f32_e32 v49, v49
	v_med3_f32 v50, v50, s52, v198
	v_med3_f32 v51, v51, s52, v198
	v_rndne_f32_e32 v48, v48
	v_cvt_i32_f32_e32 v49, v49
	v_rndne_f32_e32 v50, v50
	v_rndne_f32_e32 v51, v51
	v_cvt_i32_f32_e32 v48, v48
	v_cvt_i32_f32_sdwa v50, v50 dst_sel:WORD_1 dst_unused:UNUSED_PAD src0_sel:DWORD
	v_cvt_i32_f32_e32 v51, v51
	v_lshlrev_b32_e32 v49, 8, v49
	v_and_b32_e32 v49, 0xff00, v49
	v_and_b32_e32 v50, 0xff0000, v50
	v_perm_b32 v48, v51, v48, s53
	v_or3_b32 v50, v48, v49, v50
	v_mul_f32_e32 v49, v113, v59
	v_med3_f32 v49, v49, s52, v198
	v_rndne_f32_e32 v49, v49
	v_cvt_i32_f32_e32 v49, v49
	v_mul_f32_e32 v48, v113, v58
	v_med3_f32 v48, v48, s52, v198
	v_rndne_f32_e32 v48, v48
	v_mul_f32_e32 v51, v113, v56
	v_cvt_i32_f32_e32 v61, v48
	v_lshlrev_b32_e32 v48, 8, v49
	v_and_b32_e32 v62, 0xff00, v48
	v_med3_f32 v48, v51, s52, v198
	v_mul_f32_e32 v49, v53, v53
	v_mul_f32_e32 v51, v55, v55
	v_fmac_f32_e32 v49, v52, v52
	v_fmac_f32_e32 v51, v54, v54
	v_add_f32_e32 v49, v49, v51
	v_mul_f32_e32 v51, v59, v59
	v_fmac_f32_e32 v51, v58, v58
	v_add_f32_e32 v49, v51, v49
	v_mul_f32_e32 v51, v57, v57
	v_fmac_f32_e32 v51, v56, v56
	v_add_f32_e32 v49, v51, v49
	v_add_f32_e32 v49, v112, v49
	ds_bpermute_b32 v51, v116, v49
	v_rndne_f32_e32 v48, v48
	v_cvt_i32_f32_sdwa v52, v48 dst_sel:WORD_1 dst_unused:UNUSED_PAD src0_sel:DWORD
	v_med3_f32 v48, v60, s52, v198
	v_rndne_f32_e32 v48, v48
	v_cvt_i32_f32_e32 v53, v48
	s_waitcnt lgkmcnt(0)
	v_add_f32_e32 v48, v49, v51
	ds_bpermute_b32 v49, v117, v48
	v_and_b32_e32 v51, 0xff0000, v52
	v_perm_b32 v52, v53, v61, s53
	v_or3_b32 v51, v52, v62, v51
	global_store_dwordx2 v[114:115], v[50:51], off offset:128
	s_and_saveexec_b64 s[26:27], s[2:3]
	s_cbranch_execz .LBB0_464
	s_waitcnt lgkmcnt(0)
	v_add_f32_e32 v48, v48, v49
	v_fma_f32 v48, v48, s54, 0.5
	v_trunc_f32_e32 v48, v48
	v_mul_f32_e32 v49, 0x2f800000, v48
	v_floor_f32_e32 v49, v49
	v_fmac_f32_e32 v48, 0xcf800000, v49
	v_cvt_u32_f32_e32 v48, v48
	v_cvt_u32_f32_e32 v49, v49
	v_lshl_add_u64 v[50:51], v[100:101], 3, s[8:9]
	v_mov_b32_e32 v228, v50
	v_mov_b32_e32 v229, v51
	v_mov_b32_e32 v246, v48
	v_mov_b32_e32 v247, v49
.LBB0_464:
	s_or_b64 exec, exec, s[26:27]
	s_waitcnt lgkmcnt(0)
	v_mov_b32_e32 v48, v240
	v_mov_b32_e32 v49, v241
	s_waitcnt vmcnt(12)
	v_lshlrev_b32_e32 v52, 16, v84
	v_and_b32_e32 v53, 0xffff0000, v84
	v_lshlrev_b32_e32 v54, 16, v85
	v_and_b32_e32 v55, 0xffff0000, v85
	s_waitcnt vmcnt(11)
	v_lshlrev_b32_e32 v60, 16, v80
	v_and_b32_e32 v61, 0xffff0000, v80
	v_lshlrev_b32_e32 v62, 16, v81
	v_and_b32_e32 v63, 0xffff0000, v81
	v_lshlrev_b32_e32 v80, 16, v82
	v_and_b32_e32 v81, 0xffff0000, v82
	v_lshlrev_b32_e32 v56, 16, v86
	v_and_b32_e32 v57, 0xffff0000, v86
	v_lshlrev_b32_e32 v58, 16, v87
	v_and_b32_e32 v59, 0xffff0000, v87
	v_lshlrev_b32_e32 v82, 16, v83
	v_and_b32_e32 v83, 0xffff0000, v83
	v_pk_add_f32 v[46:47], v[46:47], v[54:55]
	v_pk_add_f32 v[44:45], v[44:45], v[52:53]
	v_pk_add_f32 v[54:55], v[32:33], v[80:81]
	v_cvt_pk_bf16_f32 v32, v44, v45
	v_pk_add_f32 v[42:43], v[42:43], v[58:59]
	v_pk_add_f32 v[40:41], v[40:41], v[56:57]
	v_pk_add_f32 v[52:53], v[34:35], v[82:83]
	v_cvt_pk_bf16_f32 v33, v46, v47
	v_cvt_pk_bf16_f32 v34, v40, v41
	v_cvt_pk_bf16_f32 v35, v42, v43
	global_store_dwordx4 v[98:99], v[32:35], off
	v_mul_f32_e32 v56, v45, v45
	v_mul_f32_e32 v57, v47, v47
	v_mul_f32_e32 v58, v41, v41
	v_fmac_f32_e32 v56, v44, v44
	v_fmac_f32_e32 v57, v46, v46
	v_mul_f32_e32 v59, v43, v43
	v_fmac_f32_e32 v58, v40, v40
	v_fmac_f32_e32 v59, v42, v42
	v_lshlrev_b64 v[50:51], 12, v[96:97]
	v_lshl_add_u64 v[50:51], v[50:51], 0, v[168:169]
	v_pk_add_f32 v[36:37], v[36:37], v[60:61]
	v_lshl_add_u64 v[50:51], s[10:11], 0, v[50:51]
	v_pk_add_f32 v[38:39], v[38:39], v[62:63]
	s_waitcnt vmcnt(9)
	v_ffbh_u32_e32 v32, v49
	v_min_u32_e32 v34, 32, v32
	v_lshlrev_b64 v[32:33], v34, v[48:49]
	v_min_u32_e32 v32, 1, v32
	v_or_b32_e32 v32, v33, v32
	v_cvt_f32_u32_e32 v32, v32
	v_sub_u32_e32 v33, 32, v34
	v_ldexp_f32 v32, v32, v33
	v_fmamk_f32 v32, v32, 0x2f800000, v196
	v_rsq_f32_e32 v32, v32
	v_add_f32_e32 v33, v56, v57
	v_add_f32_e32 v33, v58, v33
	v_add_f32_e32 v48, v59, v33
	v_mul_f32_e32 v49, 0x41ca3ab3, v32
	v_mul_f32_e32 v32, v44, v49
	v_mul_f32_e32 v33, v45, v49
	v_mul_f32_e32 v35, v47, v49
	v_mul_f32_e32 v41, v41, v49
	v_mul_f32_e32 v34, v46, v49
	v_mul_f32_e32 v40, v40, v49
	v_mul_f32_e32 v42, v42, v49
	v_mul_f32_e32 v43, v43, v49
	v_med3_f32 v32, v32, s52, v198
	v_med3_f32 v33, v33, s52, v198
	v_med3_f32 v35, v35, s52, v198
	v_med3_f32 v41, v41, s52, v198
	v_med3_f32 v34, v34, s52, v198
	v_med3_f32 v40, v40, s52, v198
	v_med3_f32 v42, v42, s52, v198
	v_med3_f32 v43, v43, s52, v198
	v_rndne_f32_e32 v32, v32
	v_rndne_f32_e32 v33, v33
	v_rndne_f32_e32 v35, v35
	v_rndne_f32_e32 v41, v41
	v_rndne_f32_e32 v34, v34
	v_rndne_f32_e32 v40, v40
	v_rndne_f32_e32 v42, v42
	v_rndne_f32_e32 v43, v43
	v_cvt_i32_f32_e32 v32, v32
	v_cvt_i32_f32_e32 v33, v33
	v_cvt_i32_f32_e32 v35, v35
	v_cvt_i32_f32_e32 v41, v41
	v_cvt_i32_f32_sdwa v34, v34 dst_sel:WORD_1 dst_unused:UNUSED_PAD src0_sel:DWORD
	v_cvt_i32_f32_e32 v40, v40
	v_cvt_i32_f32_sdwa v42, v42 dst_sel:WORD_1 dst_unused:UNUSED_PAD src0_sel:DWORD
	v_cvt_i32_f32_e32 v43, v43
	v_lshlrev_b32_e32 v33, 8, v33
	v_perm_b32 v32, v35, v32, s53
	v_lshlrev_b32_e32 v35, 8, v41
	v_and_b32_e32 v34, 0xff0000, v34
	v_and_b32_e32 v41, 0xff0000, v42
	v_perm_b32 v40, v43, v40, s53
	v_and_b32_e32 v33, 0xff00, v33
	v_and_b32_e32 v35, 0xff00, v35
	v_or3_b32 v32, v32, v33, v34
	v_or3_b32 v33, v40, v35, v41
	v_mul_f32_e32 v45, v37, v49
	global_store_dwordx2 v[50:51], v[32:33], off
	v_cvt_pk_bf16_f32 v32, v36, v37
	v_cvt_pk_bf16_f32 v33, v38, v39
	v_mul_f32_e32 v44, v36, v49
	v_mul_f32_e32 v46, v38, v49
	v_mul_f32_e32 v47, v39, v49
	v_cvt_pk_bf16_f32 v34, v54, v55
	v_cvt_pk_bf16_f32 v35, v52, v53
	global_store_dwordx4 v[98:99], v[32:35], off offset:256
	v_med3_f32 v44, v44, s52, v198
	v_mul_f32_e32 v40, v53, v49
	v_med3_f32 v33, v45, s52, v198
	v_rndne_f32_e32 v33, v33
	v_med3_f32 v34, v46, s52, v198
	v_med3_f32 v35, v47, s52, v198
	v_rndne_f32_e32 v32, v44
	v_cvt_i32_f32_e32 v33, v33
	v_rndne_f32_e32 v34, v34
	v_rndne_f32_e32 v35, v35
	v_cvt_i32_f32_e32 v32, v32
	v_cvt_i32_f32_sdwa v34, v34 dst_sel:WORD_1 dst_unused:UNUSED_PAD src0_sel:DWORD
	v_cvt_i32_f32_e32 v35, v35
	v_lshlrev_b32_e32 v33, 8, v33
	v_and_b32_e32 v33, 0xff00, v33
	v_and_b32_e32 v34, 0xff0000, v34
	v_perm_b32 v32, v35, v32, s53
	v_or3_b32 v34, v32, v33, v34
	v_mul_f32_e32 v33, v55, v49
	v_med3_f32 v33, v33, s52, v198
	v_rndne_f32_e32 v33, v33
	v_cvt_i32_f32_e32 v33, v33
	v_mul_f32_e32 v32, v54, v49
	v_med3_f32 v32, v32, s52, v198
	v_rndne_f32_e32 v32, v32
	v_mul_f32_e32 v35, v52, v49
	v_cvt_i32_f32_e32 v41, v32
	v_lshlrev_b32_e32 v32, 8, v33
	v_and_b32_e32 v42, 0xff00, v32
	v_med3_f32 v32, v35, s52, v198
	v_mul_f32_e32 v33, v37, v37
	v_mul_f32_e32 v35, v39, v39
	v_fmac_f32_e32 v33, v36, v36
	v_fmac_f32_e32 v35, v38, v38
	v_add_f32_e32 v33, v33, v35
	v_mul_f32_e32 v35, v55, v55
	v_fmac_f32_e32 v35, v54, v54
	v_add_f32_e32 v33, v35, v33
	v_mul_f32_e32 v35, v53, v53
	v_fmac_f32_e32 v35, v52, v52
	v_add_f32_e32 v33, v35, v33
	v_add_f32_e32 v33, v48, v33
	ds_bpermute_b32 v35, v116, v33
	v_rndne_f32_e32 v32, v32
	v_cvt_i32_f32_sdwa v36, v32 dst_sel:WORD_1 dst_unused:UNUSED_PAD src0_sel:DWORD
	v_med3_f32 v32, v40, s52, v198
	v_rndne_f32_e32 v32, v32
	v_cvt_i32_f32_e32 v37, v32
	s_waitcnt lgkmcnt(0)
	v_add_f32_e32 v32, v33, v35
	ds_bpermute_b32 v33, v117, v32
	v_and_b32_e32 v35, 0xff0000, v36
	v_perm_b32 v36, v37, v41, s53
	v_or3_b32 v35, v36, v42, v35
	global_store_dwordx2 v[50:51], v[34:35], off offset:128
	s_and_saveexec_b64 s[26:27], s[2:3]
	s_cbranch_execz .LBB0_466
	s_waitcnt lgkmcnt(0)
	v_add_f32_e32 v32, v32, v33
	v_fma_f32 v32, v32, s54, 0.5
	v_trunc_f32_e32 v32, v32
	v_mul_f32_e32 v33, 0x2f800000, v32
	v_floor_f32_e32 v33, v33
	v_fmac_f32_e32 v32, 0xcf800000, v33
	v_cvt_u32_f32_e32 v32, v32
	v_cvt_u32_f32_e32 v33, v33
	v_lshl_add_u64 v[34:35], v[96:97], 3, s[8:9]
	v_mov_b32_e32 v248, v32
	v_mov_b32_e32 v249, v33
.LBB0_466:
	s_or_b64 exec, exec, s[26:27]
	s_waitcnt lgkmcnt(0)
	v_mov_b32_e32 v32, v242
	v_mov_b32_e32 v33, v243
	v_lshlrev_b32_e32 v36, 16, v76
	v_and_b32_e32 v37, 0xffff0000, v76
	v_lshlrev_b32_e32 v38, 16, v77
	v_and_b32_e32 v39, 0xffff0000, v77
	v_lshlrev_b32_e32 v48, 16, v74
	v_and_b32_e32 v49, 0xffff0000, v74
	v_lshlrev_b32_e32 v40, 16, v78
	v_and_b32_e32 v41, 0xffff0000, v78
	v_lshlrev_b32_e32 v42, 16, v79
	v_and_b32_e32 v43, 0xffff0000, v79
	v_lshlrev_b32_e32 v50, 16, v75
	v_and_b32_e32 v51, 0xffff0000, v75
	v_pk_add_f32 v[30:31], v[30:31], v[38:39]
	v_pk_add_f32 v[28:29], v[28:29], v[36:37]
	v_pk_add_f32 v[38:39], v[16:17], v[48:49]
	v_cvt_pk_bf16_f32 v16, v28, v29
	v_pk_add_f32 v[26:27], v[26:27], v[42:43]
	v_pk_add_f32 v[24:25], v[24:25], v[40:41]
	v_pk_add_f32 v[36:37], v[18:19], v[50:51]
	v_cvt_pk_bf16_f32 v17, v30, v31
	v_cvt_pk_bf16_f32 v18, v24, v25
	v_cvt_pk_bf16_f32 v19, v26, v27
	global_store_dwordx4 v[94:95], v[16:19], off
	v_mul_f32_e32 v40, v29, v29
	v_mul_f32_e32 v41, v31, v31
	v_mul_f32_e32 v42, v25, v25
	v_fmac_f32_e32 v40, v28, v28
	v_fmac_f32_e32 v41, v30, v30
	v_mul_f32_e32 v43, v27, v27
	v_fmac_f32_e32 v42, v24, v24
	v_fmac_f32_e32 v43, v26, v26
	v_lshlrev_b64 v[34:35], 12, v[92:93]
	v_lshlrev_b32_e32 v44, 16, v72
	v_and_b32_e32 v45, 0xffff0000, v72
	v_lshl_add_u64 v[34:35], v[34:35], 0, v[168:169]
	v_lshlrev_b32_e32 v46, 16, v73
	v_and_b32_e32 v47, 0xffff0000, v73
	v_pk_add_f32 v[20:21], v[20:21], v[44:45]
	v_lshl_add_u64 v[34:35], s[10:11], 0, v[34:35]
	v_pk_add_f32 v[22:23], v[22:23], v[46:47]
	s_waitcnt vmcnt(13)
	v_ffbh_u32_e32 v16, v33
	v_min_u32_e32 v18, 32, v16
	v_lshlrev_b64 v[16:17], v18, v[32:33]
	v_min_u32_e32 v16, 1, v16
	v_or_b32_e32 v16, v17, v16
	v_cvt_f32_u32_e32 v16, v16
	v_sub_u32_e32 v17, 32, v18
	v_ldexp_f32 v16, v16, v17
	v_fmamk_f32 v16, v16, 0x2f800000, v196
	v_rsq_f32_e32 v16, v16
	v_add_f32_e32 v17, v40, v41
	v_add_f32_e32 v17, v42, v17
	v_add_f32_e32 v32, v43, v17
	v_mul_f32_e32 v33, 0x41ca3ab3, v16
	v_mul_f32_e32 v16, v28, v33
	v_mul_f32_e32 v17, v29, v33
	v_mul_f32_e32 v19, v31, v33
	v_mul_f32_e32 v25, v25, v33
	v_mul_f32_e32 v18, v30, v33
	v_mul_f32_e32 v24, v24, v33
	v_mul_f32_e32 v26, v26, v33
	v_mul_f32_e32 v27, v27, v33
	v_med3_f32 v16, v16, s52, v198
	v_med3_f32 v17, v17, s52, v198
	v_med3_f32 v19, v19, s52, v198
	v_med3_f32 v25, v25, s52, v198
	v_med3_f32 v18, v18, s52, v198
	v_med3_f32 v24, v24, s52, v198
	v_med3_f32 v26, v26, s52, v198
	v_med3_f32 v27, v27, s52, v198
	v_rndne_f32_e32 v16, v16
	v_rndne_f32_e32 v17, v17
	v_rndne_f32_e32 v19, v19
	v_rndne_f32_e32 v25, v25
	v_rndne_f32_e32 v18, v18
	v_rndne_f32_e32 v24, v24
	v_rndne_f32_e32 v26, v26
	v_rndne_f32_e32 v27, v27
	v_cvt_i32_f32_e32 v16, v16
	v_cvt_i32_f32_e32 v17, v17
	v_cvt_i32_f32_e32 v19, v19
	v_cvt_i32_f32_e32 v25, v25
	v_cvt_i32_f32_sdwa v18, v18 dst_sel:WORD_1 dst_unused:UNUSED_PAD src0_sel:DWORD
	v_cvt_i32_f32_e32 v24, v24
	v_cvt_i32_f32_sdwa v26, v26 dst_sel:WORD_1 dst_unused:UNUSED_PAD src0_sel:DWORD
	v_cvt_i32_f32_e32 v27, v27
	v_lshlrev_b32_e32 v17, 8, v17
	v_perm_b32 v16, v19, v16, s53
	v_lshlrev_b32_e32 v19, 8, v25
	v_and_b32_e32 v18, 0xff0000, v18
	v_and_b32_e32 v25, 0xff0000, v26
	v_perm_b32 v24, v27, v24, s53
	v_and_b32_e32 v17, 0xff00, v17
	v_and_b32_e32 v19, 0xff00, v19
	v_or3_b32 v16, v16, v17, v18
	v_or3_b32 v17, v24, v19, v25
	v_mul_f32_e32 v29, v21, v33
	global_store_dwordx2 v[34:35], v[16:17], off
	v_cvt_pk_bf16_f32 v16, v20, v21
	v_cvt_pk_bf16_f32 v17, v22, v23
	v_mul_f32_e32 v28, v20, v33
	v_mul_f32_e32 v30, v22, v33
	v_mul_f32_e32 v31, v23, v33
	v_cvt_pk_bf16_f32 v18, v38, v39
	v_cvt_pk_bf16_f32 v19, v36, v37
	global_store_dwordx4 v[94:95], v[16:19], off offset:256
	v_med3_f32 v28, v28, s52, v198
	v_mul_f32_e32 v24, v37, v33
	v_med3_f32 v17, v29, s52, v198
	v_rndne_f32_e32 v17, v17
	v_med3_f32 v18, v30, s52, v198
	v_med3_f32 v19, v31, s52, v198
	v_rndne_f32_e32 v16, v28
	v_cvt_i32_f32_e32 v17, v17
	v_rndne_f32_e32 v18, v18
	v_rndne_f32_e32 v19, v19
	v_cvt_i32_f32_e32 v16, v16
	v_cvt_i32_f32_sdwa v18, v18 dst_sel:WORD_1 dst_unused:UNUSED_PAD src0_sel:DWORD
	v_cvt_i32_f32_e32 v19, v19
	v_lshlrev_b32_e32 v17, 8, v17
	v_and_b32_e32 v17, 0xff00, v17
	v_and_b32_e32 v18, 0xff0000, v18
	v_perm_b32 v16, v19, v16, s53
	v_or3_b32 v18, v16, v17, v18
	v_mul_f32_e32 v17, v39, v33
	v_med3_f32 v17, v17, s52, v198
	v_rndne_f32_e32 v17, v17
	v_cvt_i32_f32_e32 v17, v17
	v_mul_f32_e32 v16, v38, v33
	v_med3_f32 v16, v16, s52, v198
	v_rndne_f32_e32 v16, v16
	v_mul_f32_e32 v19, v36, v33
	v_cvt_i32_f32_e32 v25, v16
	v_lshlrev_b32_e32 v16, 8, v17
	v_and_b32_e32 v26, 0xff00, v16
	v_med3_f32 v16, v19, s52, v198
	v_mul_f32_e32 v17, v21, v21
	v_mul_f32_e32 v19, v23, v23
	v_fmac_f32_e32 v17, v20, v20
	v_fmac_f32_e32 v19, v22, v22
	v_add_f32_e32 v17, v17, v19
	v_mul_f32_e32 v19, v39, v39
	v_fmac_f32_e32 v19, v38, v38
	v_add_f32_e32 v17, v19, v17
	v_mul_f32_e32 v19, v37, v37
	v_fmac_f32_e32 v19, v36, v36
	v_add_f32_e32 v17, v19, v17
	v_add_f32_e32 v17, v32, v17
	ds_bpermute_b32 v19, v116, v17
	v_rndne_f32_e32 v16, v16
	v_cvt_i32_f32_sdwa v20, v16 dst_sel:WORD_1 dst_unused:UNUSED_PAD src0_sel:DWORD
	v_med3_f32 v16, v24, s52, v198
	v_rndne_f32_e32 v16, v16
	v_cvt_i32_f32_e32 v21, v16
	s_waitcnt lgkmcnt(0)
	v_add_f32_e32 v16, v17, v19
	ds_bpermute_b32 v17, v117, v16
	v_and_b32_e32 v19, 0xff0000, v20
	v_perm_b32 v20, v21, v25, s53
	v_or3_b32 v19, v20, v26, v19
	global_store_dwordx2 v[34:35], v[18:19], off offset:128
	s_and_saveexec_b64 s[26:27], s[2:3]
	s_cbranch_execz .LBB0_468
	s_waitcnt lgkmcnt(0)
	v_add_f32_e32 v16, v16, v17
	v_fma_f32 v16, v16, s54, 0.5
	v_trunc_f32_e32 v16, v16
	v_mul_f32_e32 v17, 0x2f800000, v16
	v_floor_f32_e32 v17, v17
	v_fmac_f32_e32 v16, 0xcf800000, v17
	v_cvt_u32_f32_e32 v16, v16
	v_cvt_u32_f32_e32 v17, v17
	v_lshl_add_u64 v[18:19], v[92:93], 3, s[8:9]
	v_mov_b32_e32 v250, v16
	v_mov_b32_e32 v251, v17
.LBB0_468:
	s_or_b64 exec, exec, s[26:27]
	s_waitcnt lgkmcnt(0)
	v_mov_b32_e32 v16, v244
	v_mov_b32_e32 v17, v245
	v_lshlrev_b32_e32 v20, 16, v68
	v_and_b32_e32 v21, 0xffff0000, v68
	v_lshlrev_b32_e32 v22, 16, v69
	v_and_b32_e32 v23, 0xffff0000, v69
	v_lshlrev_b32_e32 v32, 16, v66
	v_and_b32_e32 v33, 0xffff0000, v66
	v_lshlrev_b32_e32 v24, 16, v70
	v_and_b32_e32 v25, 0xffff0000, v70
	v_lshlrev_b32_e32 v26, 16, v71
	v_and_b32_e32 v27, 0xffff0000, v71
	v_lshlrev_b32_e32 v34, 16, v67
	v_and_b32_e32 v35, 0xffff0000, v67
	v_pk_add_f32 v[14:15], v[14:15], v[22:23]
	v_pk_add_f32 v[12:13], v[12:13], v[20:21]
	v_pk_add_f32 v[22:23], v[0:1], v[32:33]
	v_cvt_pk_bf16_f32 v0, v12, v13
	v_pk_add_f32 v[10:11], v[10:11], v[26:27]
	v_pk_add_f32 v[8:9], v[8:9], v[24:25]
	v_pk_add_f32 v[20:21], v[2:3], v[34:35]
	v_cvt_pk_bf16_f32 v1, v14, v15
	v_cvt_pk_bf16_f32 v2, v8, v9
	v_cvt_pk_bf16_f32 v3, v10, v11
	global_store_dwordx4 v[90:91], v[0:3], off
	v_mul_f32_e32 v24, v13, v13
	v_mul_f32_e32 v25, v15, v15
	v_mul_f32_e32 v26, v9, v9
	v_fmac_f32_e32 v24, v12, v12
	v_fmac_f32_e32 v25, v14, v14
	v_mul_f32_e32 v27, v11, v11
	v_fmac_f32_e32 v26, v8, v8
	v_fmac_f32_e32 v27, v10, v10
	v_lshlrev_b64 v[18:19], 12, v[88:89]
	v_lshlrev_b32_e32 v28, 16, v64
	v_and_b32_e32 v29, 0xffff0000, v64
	v_lshl_add_u64 v[18:19], v[18:19], 0, v[168:169]
	v_lshlrev_b32_e32 v30, 16, v65
	v_and_b32_e32 v31, 0xffff0000, v65
	v_pk_add_f32 v[4:5], v[4:5], v[28:29]
	v_lshl_add_u64 v[18:19], s[10:11], 0, v[18:19]
	v_pk_add_f32 v[6:7], v[6:7], v[30:31]
	s_waitcnt vmcnt(17)
	v_ffbh_u32_e32 v0, v17
	v_min_u32_e32 v2, 32, v0
	v_lshlrev_b64 v[0:1], v2, v[16:17]
	v_min_u32_e32 v0, 1, v0
	v_or_b32_e32 v0, v1, v0
	v_cvt_f32_u32_e32 v0, v0
	v_sub_u32_e32 v1, 32, v2
	v_ldexp_f32 v0, v0, v1
	v_fmamk_f32 v0, v0, 0x2f800000, v196
	v_rsq_f32_e32 v0, v0
	v_add_f32_e32 v1, v24, v25
	v_add_f32_e32 v1, v26, v1
	v_add_f32_e32 v16, v27, v1
	v_mul_f32_e32 v17, 0x41ca3ab3, v0
	v_mul_f32_e32 v0, v12, v17
	v_mul_f32_e32 v1, v13, v17
	v_mul_f32_e32 v3, v15, v17
	v_mul_f32_e32 v9, v9, v17
	v_mul_f32_e32 v2, v14, v17
	v_mul_f32_e32 v8, v8, v17
	v_mul_f32_e32 v10, v10, v17
	v_mul_f32_e32 v11, v11, v17
	v_med3_f32 v0, v0, s52, v198
	v_med3_f32 v1, v1, s52, v198
	v_med3_f32 v3, v3, s52, v198
	v_med3_f32 v9, v9, s52, v198
	v_med3_f32 v2, v2, s52, v198
	v_med3_f32 v8, v8, s52, v198
	v_med3_f32 v10, v10, s52, v198
	v_med3_f32 v11, v11, s52, v198
	v_rndne_f32_e32 v0, v0
	v_rndne_f32_e32 v1, v1
	v_rndne_f32_e32 v3, v3
	v_rndne_f32_e32 v9, v9
	v_rndne_f32_e32 v2, v2
	v_rndne_f32_e32 v8, v8
	v_rndne_f32_e32 v10, v10
	v_rndne_f32_e32 v11, v11
	v_cvt_i32_f32_e32 v0, v0
	v_cvt_i32_f32_e32 v1, v1
	v_cvt_i32_f32_e32 v3, v3
	v_cvt_i32_f32_e32 v9, v9
	v_cvt_i32_f32_sdwa v2, v2 dst_sel:WORD_1 dst_unused:UNUSED_PAD src0_sel:DWORD
	v_cvt_i32_f32_e32 v8, v8
	v_cvt_i32_f32_sdwa v10, v10 dst_sel:WORD_1 dst_unused:UNUSED_PAD src0_sel:DWORD
	v_cvt_i32_f32_e32 v11, v11
	v_lshlrev_b32_e32 v1, 8, v1
	v_perm_b32 v0, v3, v0, s53
	v_lshlrev_b32_e32 v3, 8, v9
	v_and_b32_e32 v2, 0xff0000, v2
	v_and_b32_e32 v9, 0xff0000, v10
	v_perm_b32 v8, v11, v8, s53
	v_and_b32_e32 v1, 0xff00, v1
	v_and_b32_e32 v3, 0xff00, v3
	v_or3_b32 v0, v0, v1, v2
	v_or3_b32 v1, v8, v3, v9
	v_mul_f32_e32 v13, v5, v17
	global_store_dwordx2 v[18:19], v[0:1], off
	v_cvt_pk_bf16_f32 v0, v4, v5
	v_cvt_pk_bf16_f32 v1, v6, v7
	v_mul_f32_e32 v12, v4, v17
	v_mul_f32_e32 v14, v6, v17
	v_mul_f32_e32 v15, v7, v17
	v_cvt_pk_bf16_f32 v2, v22, v23
	v_cvt_pk_bf16_f32 v3, v20, v21
	global_store_dwordx4 v[90:91], v[0:3], off offset:256
	v_med3_f32 v12, v12, s52, v198
	v_mul_f32_e32 v8, v21, v17
	v_med3_f32 v1, v13, s52, v198
	v_rndne_f32_e32 v1, v1
	v_med3_f32 v2, v14, s52, v198
	v_med3_f32 v3, v15, s52, v198
	v_rndne_f32_e32 v0, v12
	v_cvt_i32_f32_e32 v1, v1
	v_rndne_f32_e32 v2, v2
	v_rndne_f32_e32 v3, v3
	v_cvt_i32_f32_e32 v0, v0
	v_cvt_i32_f32_sdwa v2, v2 dst_sel:WORD_1 dst_unused:UNUSED_PAD src0_sel:DWORD
	v_cvt_i32_f32_e32 v3, v3
	v_lshlrev_b32_e32 v1, 8, v1
	v_and_b32_e32 v1, 0xff00, v1
	v_and_b32_e32 v2, 0xff0000, v2
	v_perm_b32 v0, v3, v0, s53
	v_or3_b32 v2, v0, v1, v2
	v_mul_f32_e32 v1, v23, v17
	v_med3_f32 v1, v1, s52, v198
	v_rndne_f32_e32 v1, v1
	v_cvt_i32_f32_e32 v1, v1
	v_mul_f32_e32 v0, v22, v17
	v_med3_f32 v0, v0, s52, v198
	v_rndne_f32_e32 v0, v0
	v_mul_f32_e32 v3, v20, v17
	v_cvt_i32_f32_e32 v9, v0
	v_lshlrev_b32_e32 v0, 8, v1
	v_and_b32_e32 v10, 0xff00, v0
	v_med3_f32 v0, v3, s52, v198
	v_mul_f32_e32 v1, v5, v5
	v_mul_f32_e32 v3, v7, v7
	v_fmac_f32_e32 v1, v4, v4
	v_fmac_f32_e32 v3, v6, v6
	v_add_f32_e32 v1, v1, v3
	v_mul_f32_e32 v3, v23, v23
	v_fmac_f32_e32 v3, v22, v22
	v_add_f32_e32 v1, v3, v1
	v_mul_f32_e32 v3, v21, v21
	v_fmac_f32_e32 v3, v20, v20
	v_add_f32_e32 v1, v3, v1
	v_add_f32_e32 v1, v16, v1
	ds_bpermute_b32 v3, v116, v1
	v_rndne_f32_e32 v0, v0
	v_cvt_i32_f32_sdwa v4, v0 dst_sel:WORD_1 dst_unused:UNUSED_PAD src0_sel:DWORD
	v_med3_f32 v0, v8, s52, v198
	v_rndne_f32_e32 v0, v0
	v_cvt_i32_f32_e32 v5, v0
	s_waitcnt lgkmcnt(0)
	v_add_f32_e32 v0, v1, v3
	ds_bpermute_b32 v1, v117, v0
	v_and_b32_e32 v3, 0xff0000, v4
	v_perm_b32 v4, v5, v9, s53
	v_or3_b32 v3, v4, v10, v3
	global_store_dwordx2 v[18:19], v[2:3], off offset:128
	s_and_saveexec_b64 s[26:27], s[2:3]
	s_cbranch_execz .LBB0_470
	s_waitcnt lgkmcnt(0)
	v_add_f32_e32 v0, v0, v1
	v_fma_f32 v0, v0, s54, 0.5
	v_trunc_f32_e32 v0, v0
	v_mul_f32_e32 v1, 0x2f800000, v0
	v_floor_f32_e32 v1, v1
	v_fmac_f32_e32 v0, 0xcf800000, v1
	v_cvt_u32_f32_e32 v0, v0
	v_cvt_u32_f32_e32 v1, v1
	v_lshl_add_u64 v[2:3], v[88:89], 3, s[8:9]
	v_mov_b32_e32 v252, v0
	v_mov_b32_e32 v253, v1
.LBB0_470:
	s_or_b64 exec, exec, s[26:27]
	s_and_saveexec_b64 s[96:97], s[2:3]
	global_atomic_add_x2 v[228:229], v[246:247], off
	global_atomic_add_x2 v[228:229], v[248:249], off offset:128
	global_atomic_add_x2 v[228:229], v[250:251], off offset:256
	global_atomic_add_x2 v[228:229], v[252:253], off offset:384
	s_mov_b64 exec, s[96:97]
	s_andn2_b64 vcc, exec, s[4:5]
	s_mov_b64 s[4:5], -1
	s_cbranch_vccnz .LBB0_443
	s_andn2_b64 vcc, exec, s[0:1]
	s_cbranch_vccnz .LBB0_442
	s_barrier
	s_branch .LBB0_442

.LBB0_531:
	s_mov_b64 s[0:1], s[78:79]
	s_load_dword s0, s[0:1], 0xa8
	s_waitcnt lgkmcnt(0)
	s_cmp_gt_i32 s0, 5
	s_cbranch_scc1 .LBB0_557
	s_mov_b64 s[0:1], s[78:79]
	s_load_dword s0, s[0:1], 0xac
	s_waitcnt lgkmcnt(0)
	s_cmp_lt_i32 s0, 6
	s_cbranch_scc1 .LBB0_557
	s_mov_b32 s95, -1
	s_mov_b64 s[0:1], s[78:79]
	s_mov_b32 s5, -1
	s_cmpk_gt_i32 s87, 0xfff
	s_cbranch_scc1 .LBB0_557
	s_ashr_i32 s33, s87, 31
	s_load_dwordx2 s[2:3], s[0:1], 0xa0
	s_lshr_b32 s0, s33, 29
	s_add_i32 s6, s87, s0
	s_and_b32 s0, s6, -8
	s_sub_i32 s7, s87, s0
	s_cmp_gt_i32 s7, -1
	s_cbranch_scc0 .LBB0_536
	s_lshl_b32 s4, s7, 9
	s_cbranch_execz .LBB0_537
	s_branch .LBB0_538

.LBB0_540:
	s_add_u32 s10, s2, 0x46200000
	s_addc_u32 s11, s3, 0
	s_add_u32 s12, s2, 0x40000
	s_addc_u32 s13, s3, 0
	s_add_u32 s14, s2, 0x380000
	s_addc_u32 s15, s3, 0
	s_lshl_b32 s2, s81, 5
	s_mov_b64 s[16:17], 0x80
	s_and_b32 s20, s2, 0x60
	s_add_i32 m0, s45, 0x18000
	v_lshl_add_u64 v[6:7], v[6:7], 0, s[16:17]
	s_lshl_b32 s1, s19, 13
	s_lshr_b32 s21, s20, 3
	s_waitcnt vmcnt(2)
	s_barrier
	global_load_lds_dwordx4 v[6:7], off
	v_lshl_add_u64 v[4:5], v[4:5], 0, s[16:17]
	s_add_i32 m0, s45, 0x1a000
	s_add_i32 s50, s45, 0x8000
	s_add_i32 s51, s45, 0xa000
	global_load_lds_dwordx4 v[4:5], off
	v_lshl_add_u64 v[0:1], v[0:1], 0, s[16:17]
	s_mov_b32 m0, s50
	s_add_u32 s2, s4, 0x80080
	global_load_lds_dwordx4 v[0:1], off
	v_lshl_add_u64 v[0:1], v[2:3], 0, s[16:17]
	s_mov_b32 m0, s51
	s_addc_u32 s3, s5, 0
	global_load_lds_dwordx4 v[0:1], off
	s_add_i32 m0, s45, 0x1c000
	v_lshl_add_u64 v[0:1], s[2:3], 0, v[130:131]
	global_load_lds_dwordx4 v[0:1], off
	v_lshl_add_u64 v[0:1], s[2:3], 0, v[134:135]
	s_add_i32 m0, s45, 0x1e000
	v_lshrrev_b32_e32 v2, 6, v11
	global_load_lds_dwordx4 v[0:1], off
	v_and_b32_e32 v0, 15, v11
	v_lshlrev_b32_e32 v5, 2, v11
	v_lshl_or_b32 v155, s19, 6, v0
	v_and_b32_e32 v3, 48, v11
	v_lshlrev_b32_e32 v4, 10, v2
	v_lshlrev_b32_e32 v0, 6, v0
	v_and_b32_e32 v5, 32, v5
	v_or_b32_e32 v2, s21, v2
	v_bitop3_b32 v6, v0, v5, v3 bitop3:0x36
	v_or_b32_e32 v0, v0, v3
	v_lshlrev_b32_e32 v2, 10, v2
	v_lshrrev_b32_e32 v1, 1, v11
	v_bitop3_b32 v157, v0, v2, v5 bitop3:0xde
	v_lshlrev_b32_e32 v0, 15, v12
	v_and_b32_e32 v1, 56, v1
	v_and_b32_e32 v0, 0xffff0000, v0
	v_add_u32_e32 v159, s20, v1
	v_lshl_add_u32 v0, v13, 12, v0
	v_and_b32_e32 v1, 1, v12
	v_lshl_or_b32 v0, v1, 6, v0
	v_lshl_add_u32 v136, v14, 1, v0
	v_lshlrev_b32_e32 v0, 15, v8
	v_and_b32_e32 v0, 0xffff0000, v0
	s_waitcnt vmcnt(6)
	s_cmpk_lt_u32 s92, 0x100
	v_lshl_add_u32 v0, v9, 12, v0
	v_and_b32_e32 v1, 1, v8
	s_sext_i32_i16 s60, s18
	v_or3_b32 v4, v4, s1, v6
	s_cselect_b64 s[18:19], -1, 0
	v_lshl_or_b32 v0, v1, 6, v0
	s_add_i32 s53, 0, 0x10000
	s_add_i32 s54, 0, 0x14000
	s_ashr_i32 s52, s77, 31
	v_mov_b32_e32 v137, v131
	v_lshl_add_u32 v138, v10, 1, v0
	v_mov_b32_e32 v139, v131
	v_mov_b64_e32 v[140:141], 0x1000
	v_mov_b64_e32 v[142:143], 0xfff
	v_add_u32_e32 v161, s53, v157
	v_add_u32_e32 v163, s54, v157
	v_add_u32_e32 v166, 0, v4
	v_mov_b32_e32 v167, 0x358637bd
	s_mov_b32 s55, 0xf800000
	v_mov_b32_e32 v168, 0x260
	s_mov_b64 s[20:21], 0x408000
	s_mov_b32 s56, 0x408000
	s_mov_b64 s[22:23], 0x489000
	s_mov_b32 s57, 0x489000
	s_mov_b64 s[24:25], 0x50a000
	s_mov_b32 s58, 0x50a000
	s_mov_b64 s[26:27], 0x58b000
	s_mov_b32 s59, 0x58b000
	s_barrier
	s_branch .LBB0_543

.LBB0_553:
	s_cmp_eq_u32 s95, s0
	s_cbranch_scc1 .Llean_p5
	s_mov_b32 s95, s0
	v_lshl_add_u32 v144, s0, 8, v155
	v_ashrrev_i32_e32 v145, 31, v144
	v_lshlrev_b64 v[146:147], 3, v[144:145]
	v_lshl_add_u64 v[148:149], s[12:13], 0, v[146:147]
	global_load_dwordx2 v[164:165], v[148:149], off
	v_lshl_add_u64 v[146:147], s[14:15], 0, v[146:147]
	global_load_dwordx2 v[170:171], v[146:147], off
	global_load_dwordx2 v[172:173], v[148:149], off offset:128
	global_load_dwordx2 v[174:175], v[146:147], off offset:128
	global_load_dwordx2 v[176:177], v[148:149], off offset:256
	global_load_dwordx2 v[178:179], v[146:147], off offset:256
	global_load_dwordx2 v[180:181], v[148:149], off offset:384
	global_load_dwordx2 v[182:183], v[146:147], off offset:384
	global_load_dwordx2 v[152:153], v[148:149], off offset:1024
	global_load_dwordx2 v[150:151], v[146:147], off offset:1024
	v_cvt_f32_i32_e32 v121, v121
	v_cvt_f32_i32_e32 v120, v120
	v_cvt_f32_i32_e32 v125, v125
	v_cvt_f32_i32_e32 v124, v124
	v_cvt_f32_i32_e32 v123, v123
	v_cvt_f32_i32_e32 v122, v122
	v_cvt_f32_i32_e32 v127, v127
	v_cvt_f32_i32_e32 v126, v126
	v_cvt_f32_i32_e32 v113, v113
	v_cvt_f32_i32_e32 v112, v112
	v_cvt_f32_i32_e32 v117, v117
	v_cvt_f32_i32_e32 v116, v116
	v_cvt_f32_i32_e32 v115, v115
	v_cvt_f32_i32_e32 v114, v114
	v_cvt_f32_i32_e32 v119, v119
	v_cvt_f32_i32_e32 v118, v118
	v_cvt_f32_i32_e32 v105, v105
	v_cvt_f32_i32_e32 v104, v104
	v_cvt_f32_i32_e32 v109, v109
	v_cvt_f32_i32_e32 v108, v108
	v_cvt_f32_i32_e32 v107, v107
	v_cvt_f32_i32_e32 v106, v106
	v_cvt_f32_i32_e32 v111, v111
	v_cvt_f32_i32_e32 v110, v110
	v_cvt_f32_i32_e32 v97, v97
	v_cvt_f32_i32_e32 v96, v96
	v_cvt_f32_i32_e32 v101, v101
	v_cvt_f32_i32_e32 v100, v100
	v_cvt_f32_i32_e32 v99, v99
	v_cvt_f32_i32_e32 v98, v98
	v_cvt_f32_i32_e32 v103, v103
	v_cvt_f32_i32_e32 v102, v102
	v_cvt_f32_i32_e32 v89, v89
	v_cvt_f32_i32_e32 v88, v88
	v_cvt_f32_i32_e32 v93, v93
	v_cvt_f32_i32_e32 v92, v92
	v_cvt_f32_i32_e32 v91, v91
	v_cvt_f32_i32_e32 v90, v90
	v_cvt_f32_i32_e32 v95, v95
	v_cvt_f32_i32_e32 v94, v94
	v_cvt_f32_i32_e32 v81, v81
	v_cvt_f32_i32_e32 v80, v80
	v_cvt_f32_i32_e32 v85, v85
	v_cvt_f32_i32_e32 v84, v84
	v_cvt_f32_i32_e32 v83, v83
	v_cvt_f32_i32_e32 v82, v82
	v_cvt_f32_i32_e32 v87, v87
	v_cvt_f32_i32_e32 v86, v86
	v_cvt_f32_i32_e32 v73, v73
	v_cvt_f32_i32_e32 v72, v72
	v_cvt_f32_i32_e32 v77, v77
	v_cvt_f32_i32_e32 v76, v76
	v_cvt_f32_i32_e32 v75, v75
	v_cvt_f32_i32_e32 v74, v74
	v_cvt_f32_i32_e32 v79, v79
	v_cvt_f32_i32_e32 v78, v78
	v_cvt_f32_i32_e32 v65, v65
	v_cvt_f32_i32_e32 v67, v67
	v_cvt_f32_i32_e32 v66, v66
	v_cvt_f32_i32_e32 v64, v64
	v_cvt_f32_i32_e32 v69, v69
	v_cvt_f32_i32_e32 v68, v68
	v_cvt_f32_i32_e32 v71, v71
	v_cvt_f32_i32_e32 v70, v70
	v_cvt_f32_i32_e32 v57, v57
	v_cvt_f32_i32_e32 v56, v56
	v_cvt_f32_i32_e32 v61, v61
	v_cvt_f32_i32_e32 v60, v60
	v_cvt_f32_i32_e32 v59, v59
	v_cvt_f32_i32_e32 v58, v58
	v_cvt_f32_i32_e32 v63, v63
	s_waitcnt vmcnt(0)
	v_ffbh_u32_e32 v156, v171
	v_ffbh_u32_e32 v158, v173
	v_ffbh_u32_e32 v160, v175
	v_ffbh_u32_e32 v162, v177
	v_ffbh_u32_e32 v169, v179
	v_min_u32_e32 v156, 32, v156
	v_ffbh_u32_e32 v154, v165
	v_min_u32_e32 v154, 32, v154
	v_min_u32_e32 v158, 32, v158
	v_min_u32_e32 v160, 32, v160
	v_min_u32_e32 v162, 32, v162
	v_min_u32_e32 v169, 32, v169
	v_lshlrev_b64 v[164:165], v154, v[164:165]
	v_lshlrev_b64 v[170:171], v156, v[170:171]
	v_lshlrev_b64 v[172:173], v158, v[172:173]
	v_lshlrev_b64 v[174:175], v160, v[174:175]
	v_lshlrev_b64 v[176:177], v162, v[176:177]
	v_lshlrev_b64 v[178:179], v169, v[178:179]
	v_min_u32_e32 v164, 1, v164
	v_min_u32_e32 v170, 1, v170
	v_min_u32_e32 v172, 1, v172
	v_min_u32_e32 v174, 1, v174
	v_min_u32_e32 v176, 1, v176
	v_min_u32_e32 v178, 1, v178
	v_or_b32_e32 v164, v165, v164
	v_or_b32_e32 v165, v171, v170
	v_or_b32_e32 v170, v173, v172
	v_or_b32_e32 v171, v175, v174
	v_or_b32_e32 v172, v177, v176
	v_or_b32_e32 v173, v179, v178
	v_cvt_f32_u32_e32 v165, v165
	v_cvt_f32_u32_e32 v164, v164
	v_cvt_f32_u32_e32 v171, v171
	v_cvt_f32_u32_e32 v172, v172
	v_cvt_f32_u32_e32 v173, v173
	v_sub_u32_e32 v156, 32, v156
	v_cvt_f32_u32_e32 v170, v170
	v_sub_u32_e32 v154, 32, v154
	v_sub_u32_e32 v160, 32, v160
	v_sub_u32_e32 v162, 32, v162
	v_sub_u32_e32 v169, 32, v169
	v_ldexp_f32 v156, v165, v156
	v_ldexp_f32 v154, v164, v154
	v_ldexp_f32 v160, v171, v160
	v_ldexp_f32 v162, v172, v162
	v_ldexp_f32 v164, v173, v169
	v_fmamk_f32 v156, v156, 0x2f800000, v167
	v_sub_u32_e32 v158, 32, v158
	v_fmamk_f32 v160, v160, 0x2f800000, v167
	v_fmamk_f32 v162, v162, 0x2f800000, v167
	v_fmamk_f32 v164, v164, 0x2f800000, v167
	v_mul_f32_e32 v165, 0x4f800000, v156
	v_cmp_gt_f32_e32 vcc, s55, v156
	v_ldexp_f32 v158, v170, v158
	v_mul_f32_e32 v169, 0x4f800000, v160
	v_rsq_f32_e32 v170, v162
	v_mul_f32_e32 v162, 0x4f800000, v164
	v_cndmask_b32_e32 v156, v156, v165, vcc
	v_cmp_gt_f32_e64 s[0:1], s55, v160
	v_cmp_gt_f32_e64 s[4:5], s55, v164
	v_fmamk_f32 v154, v154, 0x2f800000, v167
	v_cndmask_b32_e64 v160, v160, v169, s[0:1]
	v_cndmask_b32_e64 v169, v164, v162, s[4:5]
	v_sqrt_f32_e32 v162, v156
	v_sqrt_f32_e32 v164, v160
	v_fmamk_f32 v158, v158, 0x2f800000, v167
	v_rsq_f32_e32 v154, v154
	v_add_u32_e32 v171, -1, v162
	v_add_u32_e32 v173, -1, v164
	v_fma_f32 v175, -v171, v162, v156
	v_add_u32_e32 v172, 1, v162
	v_fma_f32 v177, -v173, v164, v160
	v_cmp_ge_f32_e64 s[6:7], 0, v175
	v_add_u32_e32 v174, 1, v164
	v_fma_f32 v176, -v172, v162, v156
	v_cndmask_b32_e64 v162, v162, v171, s[6:7]
	v_cmp_ge_f32_e64 s[6:7], 0, v177
	v_fma_f32 v178, -v174, v164, v160
	v_rsq_f32_e32 v158, v158
	v_cndmask_b32_e64 v164, v164, v173, s[6:7]
	v_cmp_lt_f32_e64 s[6:7], 0, v176
	v_sqrt_f32_e32 v165, v169
	v_mul_f32_e32 v154, 0x37a34f4c, v154
	v_cndmask_b32_e64 v162, v162, v172, s[6:7]
	v_cmp_lt_f32_e64 s[6:7], 0, v178
	v_mul_f32_e32 v171, 0x37800000, v162
	v_cndmask_b32_e32 v162, v162, v171, vcc
	v_cndmask_b32_e64 v164, v164, v174, s[6:7]
	v_mul_f32_e32 v172, 0x37800000, v164
	v_cmp_class_f32_e32 vcc, v156, v168
	v_cndmask_b32_e64 v164, v164, v172, s[0:1]
	v_mul_f32_e32 v158, 0x37a34f4c, v158
	v_cndmask_b32_e32 v156, v162, v156, vcc
	v_cmp_class_f32_e32 vcc, v160, v168
	v_mul_f32_e32 v162, v154, v156
	v_add_u32_e32 v156, -1, v165
	v_cndmask_b32_e32 v154, v164, v160, vcc
	v_mul_f32_e32 v160, v158, v154
	v_fma_f32 v158, -v156, v165, v169
	v_cmp_ge_f32_e32 vcc, 0, v158
	v_add_u32_e32 v158, 1, v165
	v_fma_f32 v164, -v158, v165, v169
	v_cndmask_b32_e32 v156, v165, v156, vcc
	v_cmp_lt_f32_e32 vcc, 0, v164
	global_load_dwordx2 v[164:165], v[148:149], off offset:1152
	v_mul_f32_e32 v154, 0x37a34f4c, v170
	v_ffbh_u32_e32 v170, v181
	v_min_u32_e32 v172, 32, v170
	v_lshlrev_b64 v[170:171], v172, v[180:181]
	v_min_u32_e32 v170, 1, v170
	v_or_b32_e32 v170, v171, v170
	v_cndmask_b32_e32 v156, v156, v158, vcc
	v_cvt_f32_u32_e32 v173, v170
	v_mul_f32_e32 v158, 0x37800000, v156
	global_load_dwordx2 v[170:171], v[146:147], off offset:1152
	v_cndmask_b32_e64 v156, v156, v158, s[4:5]
	v_sub_u32_e32 v158, 32, v172
	v_ffbh_u32_e32 v172, v183
	v_min_u32_e32 v174, 32, v172
	v_ldexp_f32 v158, v173, v158
	v_lshlrev_b64 v[172:173], v174, v[182:183]
	v_min_u32_e32 v172, 1, v172
	v_or_b32_e32 v172, v173, v172
	v_cvt_f32_u32_e32 v172, v172
	v_sub_u32_e32 v173, 32, v174
	v_fmamk_f32 v158, v158, 0x2f800000, v167
	v_rsq_f32_e32 v158, v158
	v_ldexp_f32 v172, v172, v173
	v_fmamk_f32 v172, v172, 0x2f800000, v167
	v_mul_f32_e32 v173, 0x4f800000, v172
	v_cmp_gt_f32_e32 vcc, s55, v172
	v_cmp_class_f32_e64 s[0:1], v169, v168
	v_mov_b32_e32 v232, v162
	v_pk_mul_f32 v[120:121], v[162:163], v[120:121] op_sel_hi:[0,1]
	v_cndmask_b32_e32 v174, v172, v173, vcc
	v_sqrt_f32_e32 v172, v174
	v_cndmask_b32_e64 v156, v156, v169, s[0:1]
	v_mul_f32_e32 v156, v154, v156
	v_mul_f32_e32 v154, 0x37a34f4c, v158
	v_add_u32_e32 v158, -1, v172
	v_fma_f32 v169, -v158, v172, v174
	v_cmp_ge_f32_e64 s[0:1], 0, v169
	v_add_u32_e32 v169, 1, v172
	v_fma_f32 v175, -v169, v172, v174
	v_cndmask_b32_e64 v158, v172, v158, s[0:1]
	global_load_dwordx2 v[172:173], v[148:149], off offset:1280
	v_cmp_lt_f32_e64 s[0:1], 0, v175
	v_pk_mul_f32 v[124:125], v[162:163], v[124:125] op_sel_hi:[0,1]
	v_pk_mul_f32 v[122:123], v[162:163], v[122:123] op_sel_hi:[0,1]
	v_cndmask_b32_e64 v158, v158, v169, s[0:1]
	v_ffbh_u32_e32 v169, v153
	v_min_u32_e32 v169, 32, v169
	v_lshlrev_b64 v[152:153], v169, v[152:153]
	v_min_u32_e32 v152, 1, v152
	v_or_b32_e32 v152, v153, v152
	v_cvt_f32_u32_e32 v175, v152
	global_load_dwordx2 v[152:153], v[146:147], off offset:1280
	v_sub_u32_e32 v169, 32, v169
	global_load_dwordx2 v[146:147], v[146:147], off offset:1408
	v_ldexp_f32 v169, v175, v169
	v_ffbh_u32_e32 v175, v151
	v_min_u32_e32 v175, 32, v175
	global_load_dwordx2 v[148:149], v[148:149], off offset:1408
	v_lshlrev_b64 v[150:151], v175, v[150:151]
	v_min_u32_e32 v150, 1, v150
	v_or_b32_e32 v150, v151, v150
	v_cvt_f32_u32_e32 v150, v150
	v_fmamk_f32 v151, v169, 0x2f800000, v167
	v_sub_u32_e32 v169, 32, v175
	v_mul_f32_e32 v176, 0x37800000, v158
	v_ldexp_f32 v150, v150, v169
	v_fmamk_f32 v150, v150, 0x2f800000, v167
	v_cndmask_b32_e32 v158, v158, v176, vcc
	v_mul_f32_e32 v169, 0x4f800000, v150
	v_cmp_gt_f32_e32 vcc, s55, v150
	v_rsq_f32_e32 v151, v151
	v_cmp_class_f32_e64 s[0:1], v174, v168
	v_cndmask_b32_e32 v169, v150, v169, vcc
	v_sqrt_f32_e32 v150, v169
	v_cndmask_b32_e64 v158, v158, v174, s[0:1]
	v_mul_f32_e32 v158, v154, v158
	v_mul_f32_e32 v154, 0x37a34f4c, v151
	v_add_u32_e32 v151, -1, v150
	v_fma_f32 v174, -v151, v150, v169
	v_cmp_ge_f32_e64 s[0:1], 0, v174
	v_add_u32_e32 v174, 1, v150
	v_max_f32_e32 v120, 0, v120
	v_cndmask_b32_e64 v151, v150, v151, s[0:1]
	v_fma_f32 v150, -v174, v150, v169
	v_cmp_lt_f32_e64 s[0:1], 0, v150
	s_waitcnt vmcnt(5)
	v_ffbh_u32_e32 v150, v165
	v_min_u32_e32 v175, 32, v150
	v_cndmask_b32_e64 v174, v151, v174, s[0:1]
	v_lshlrev_b64 v[150:151], v175, v[164:165]
	v_min_u32_e32 v150, 1, v150
	v_or_b32_e32 v150, v151, v150
	v_cvt_f32_u32_e32 v150, v150
	v_mul_f32_e32 v151, 0x37800000, v174
	v_cndmask_b32_e32 v164, v174, v151, vcc
	v_sub_u32_e32 v151, 32, v175
	v_ldexp_f32 v165, v150, v151
	s_waitcnt vmcnt(4)
	v_ffbh_u32_e32 v150, v171
	v_min_u32_e32 v174, 32, v150
	v_lshlrev_b64 v[150:151], v174, v[170:171]
	v_min_u32_e32 v150, 1, v150
	v_or_b32_e32 v150, v151, v150
	v_cvt_f32_u32_e32 v150, v150
	v_fmamk_f32 v151, v165, 0x2f800000, v167
	v_sub_u32_e32 v165, 32, v174
	v_rsq_f32_e32 v151, v151
	v_ldexp_f32 v150, v150, v165
	v_fmamk_f32 v150, v150, 0x2f800000, v167
	v_mul_f32_e32 v165, 0x4f800000, v150
	v_cmp_gt_f32_e32 vcc, s55, v150
	v_cmp_class_f32_e64 s[0:1], v169, v168
	v_pk_mul_f32 v[126:127], v[162:163], v[126:127] op_sel_hi:[0,1]
	v_cndmask_b32_e32 v165, v150, v165, vcc
	v_sqrt_f32_e32 v150, v165
	v_cndmask_b32_e64 v164, v164, v169, s[0:1]
	v_mul_f32_e32 v154, v154, v164
	v_mul_f32_e32 v164, 0x37a34f4c, v151
	v_add_u32_e32 v151, -1, v150
	v_fma_f32 v169, -v151, v150, v165
	v_cmp_ge_f32_e64 s[0:1], 0, v169
	v_add_u32_e32 v169, 1, v150
	v_max_f32_e32 v121, 0, v121
	v_cndmask_b32_e64 v151, v150, v151, s[0:1]
	v_fma_f32 v150, -v169, v150, v165
	v_cmp_lt_f32_e64 s[0:1], 0, v150
	s_waitcnt vmcnt(3)
	v_ffbh_u32_e32 v150, v173
	v_min_u32_e32 v170, 32, v150
	v_cndmask_b32_e64 v169, v151, v169, s[0:1]
	v_lshlrev_b64 v[150:151], v170, v[172:173]
	v_min_u32_e32 v150, 1, v150
	v_or_b32_e32 v150, v151, v150
	v_cvt_f32_u32_e32 v150, v150
	v_mul_f32_e32 v151, 0x37800000, v169
	v_cndmask_b32_e32 v169, v169, v151, vcc
	v_sub_u32_e32 v151, 32, v170
	v_ldexp_f32 v170, v150, v151
	s_waitcnt vmcnt(2)
	v_ffbh_u32_e32 v150, v153
	v_min_u32_e32 v171, 32, v150
	v_lshlrev_b64 v[150:151], v171, v[152:153]
	v_min_u32_e32 v150, 1, v150
	v_or_b32_e32 v150, v151, v150
	v_cvt_f32_u32_e32 v150, v150
	v_sub_u32_e32 v152, 32, v171
	v_cmp_class_f32_e64 s[0:1], v165, v168
	v_fmamk_f32 v151, v170, 0x2f800000, v167
	v_ldexp_f32 v150, v150, v152
	v_fmamk_f32 v150, v150, 0x2f800000, v167
	v_mul_f32_e32 v152, 0x4f800000, v150
	v_cmp_gt_f32_e32 vcc, s55, v150
	v_rsq_f32_e32 v151, v151
	v_max_f32_e32 v122, 0, v122
	v_cndmask_b32_e32 v150, v150, v152, vcc
	v_sqrt_f32_e32 v153, v150
	v_cndmask_b32_e64 v152, v169, v165, s[0:1]
	v_mul_f32_e32 v152, v164, v152
	v_mul_f32_e32 v151, 0x37a34f4c, v151
	v_add_u32_e32 v164, -1, v153
	v_fma_f32 v165, -v164, v153, v150
	v_cmp_ge_f32_e64 s[0:1], 0, v165
	v_add_u32_e32 v165, 1, v153
	v_max_f32_e32 v124, 0, v124
	v_cndmask_b32_e64 v164, v153, v164, s[0:1]
	v_fma_f32 v153, -v165, v153, v150
	v_cmp_lt_f32_e64 s[0:1], 0, v153
	v_max_f32_e32 v123, 0, v123
	v_pk_mul_f32 v[112:113], v[162:163], v[112:113] op_sel_hi:[0,1]
	v_cndmask_b32_e64 v153, v164, v165, s[0:1]
	s_waitcnt vmcnt(0)
	v_ffbh_u32_e32 v164, v149
	v_min_u32_e32 v164, 32, v164
	v_lshlrev_b64 v[148:149], v164, v[148:149]
	v_min_u32_e32 v148, 1, v148
	v_or_b32_e32 v148, v149, v148
	v_cvt_f32_u32_e32 v148, v148
	v_mul_f32_e32 v149, 0x37800000, v153
	v_cndmask_b32_e32 v149, v153, v149, vcc
	v_sub_u32_e32 v153, 32, v164
	v_ldexp_f32 v148, v148, v153
	v_ffbh_u32_e32 v153, v147
	v_min_u32_e32 v153, 32, v153
	v_lshlrev_b64 v[146:147], v153, v[146:147]
	v_min_u32_e32 v146, 1, v146
	v_or_b32_e32 v146, v147, v146
	v_cvt_f32_u32_e32 v146, v146
	v_fmamk_f32 v147, v148, 0x2f800000, v167
	v_sub_u32_e32 v148, 32, v153
	v_cmp_class_f32_e64 s[0:1], v150, v168
	v_ldexp_f32 v146, v146, v148
	v_fmamk_f32 v146, v146, 0x2f800000, v167
	v_mul_f32_e32 v148, 0x4f800000, v146
	v_cmp_gt_f32_e32 vcc, s55, v146
	v_cndmask_b32_e64 v149, v149, v150, s[0:1]
	v_mul_f32_e32 v150, v151, v149
	v_cndmask_b32_e32 v146, v146, v148, vcc
	v_sqrt_f32_e32 v148, v146
	v_mov_b32_e32 v249, 0x8100
	v_mad_u64_u32 v[250:251], s[96:97], v144, v249, 0
	v_mov_b32_e32 v164, v250
	v_mov_b32_e32 v165, v251
	v_mul_f32_e32 v145, v120, v120
	v_max_f32_e32 v120, 0, v125
	v_add_u32_e32 v149, -1, v148
	v_fma_f32 v151, -v149, v148, v146
	v_cmp_ge_f32_e64 s[0:1], 0, v151
	v_add_u32_e32 v151, 1, v148
	v_lshl_add_u64 v[170:171], s[10:11], 0, v[164:165]
	v_cndmask_b32_e64 v149, v148, v149, s[0:1]
	v_fma_f32 v148, -v151, v148, v146
	v_cmp_lt_f32_e64 s[0:1], 0, v148
	v_mul_f32_e32 v120, v120, v120
	v_mul_f32_e32 v125, v121, v121
	v_cndmask_b32_e64 v148, v149, v151, s[0:1]
	v_mul_f32_e32 v149, 0x37800000, v148
	v_cndmask_b32_e32 v148, v148, v149, vcc
	v_cmp_class_f32_e32 vcc, v146, v168
	v_max_f32_e32 v121, 0, v126
	v_mul_f32_e32 v126, v122, v122
	v_cndmask_b32_e32 v146, v148, v146, vcc
	v_lshl_or_b32 v148, s60, 8, v159
	v_ashrrev_i32_e32 v149, 31, v148
	v_lshlrev_b64 v[164:165], 1, v[148:149]
	v_max_f32_e32 v122, 0, v127
	v_lshl_add_u64 v[148:149], v[170:171], 0, v[164:165]
	v_mul_f32_e32 v124, v124, v124
	v_mul_f32_e32 v121, v121, v121
	v_mul_f32_e32 v122, v122, v122
	v_mul_f32_e32 v123, v123, v123
	v_cvt_pk_bf16_f32 v120, v124, v120
	v_pk_mul_f32 v[116:117], v[162:163], v[116:117] op_sel_hi:[0,1]
	v_pk_mul_f32 v[114:115], v[162:163], v[114:115] op_sel_hi:[0,1]
	v_max_f32_e32 v112, 0, v112
	v_cvt_pk_bf16_f32 v121, v121, v122
	v_cvt_pk_bf16_f32 v122, v145, v125
	v_cvt_pk_bf16_f32 v123, v126, v123
	global_store_dwordx4 v[148:149], v[120:123], off
	v_pk_mul_f32 v[118:119], v[162:163], v[118:119] op_sel_hi:[0,1]
	v_max_f32_e32 v113, 0, v113
	v_mul_f32_e32 v120, v112, v112
	v_max_f32_e32 v112, 0, v117
	v_max_f32_e32 v114, 0, v114
	v_max_f32_e32 v116, 0, v116
	v_mul_f32_e32 v112, v112, v112
	v_mul_f32_e32 v117, v113, v113
	v_max_f32_e32 v113, 0, v118
	v_mul_f32_e32 v118, v114, v114
	v_max_f32_e32 v114, 0, v119
	v_max_f32_e32 v115, 0, v115
	v_mul_f32_e32 v116, v116, v116
	v_mul_f32_e32 v113, v113, v113
	v_mul_f32_e32 v114, v114, v114
	v_mul_f32_e32 v115, v115, v115
	v_cvt_pk_bf16_f32 v112, v116, v112
	v_cvt_pk_bf16_f32 v113, v113, v114
	v_cvt_pk_bf16_f32 v114, v120, v117
	v_cvt_pk_bf16_f32 v115, v118, v115
	global_store_dwordx4 v[148:149], v[112:115], off offset:256
	v_mov_b32_e32 v234, v160
	v_pk_mul_f32 v[104:105], v[160:161], v[104:105] op_sel_hi:[0,1]
	v_pk_mul_f32 v[108:109], v[160:161], v[108:109] op_sel_hi:[0,1]
	v_or_b32_e32 v112, 16, v144
	v_ashrrev_i32_e32 v113, 31, v112
	v_pk_mul_f32 v[106:107], v[160:161], v[106:107] op_sel_hi:[0,1]
	v_max_f32_e32 v104, 0, v104
	v_mov_b32_e32 v249, 0x8100
	v_mad_u64_u32 v[250:251], s[96:97], v112, v249, 0
	v_mov_b32_e32 v112, v250
	v_mov_b32_e32 v113, v251
	v_pk_mul_f32 v[110:111], v[160:161], v[110:111] op_sel_hi:[0,1]
	v_mul_f32_e32 v114, v104, v104
	v_max_f32_e32 v104, 0, v109
	v_max_f32_e32 v105, 0, v105
	v_max_f32_e32 v106, 0, v106
	v_lshl_add_u64 v[112:113], s[10:11], 0, v[112:113]
	v_max_f32_e32 v108, 0, v108
	v_mul_f32_e32 v104, v104, v104
	v_mul_f32_e32 v109, v105, v105
	v_max_f32_e32 v105, 0, v110
	v_mul_f32_e32 v110, v106, v106
	v_max_f32_e32 v106, 0, v111
	v_max_f32_e32 v107, 0, v107
	v_pk_mul_f32 v[96:97], v[160:161], v[96:97] op_sel_hi:[0,1]
	v_lshl_add_u64 v[112:113], v[112:113], 0, v[164:165]
	v_mul_f32_e32 v108, v108, v108
	v_mul_f32_e32 v105, v105, v105
	v_mul_f32_e32 v106, v106, v106
	v_mul_f32_e32 v107, v107, v107
	v_cvt_pk_bf16_f32 v104, v108, v104
	v_pk_mul_f32 v[100:101], v[160:161], v[100:101] op_sel_hi:[0,1]
	v_pk_mul_f32 v[98:99], v[160:161], v[98:99] op_sel_hi:[0,1]
	v_max_f32_e32 v96, 0, v96
	v_cvt_pk_bf16_f32 v105, v105, v106
	v_cvt_pk_bf16_f32 v106, v114, v109
	v_cvt_pk_bf16_f32 v107, v110, v107
	global_store_dwordx4 v[112:113], v[104:107], off
	v_pk_mul_f32 v[102:103], v[160:161], v[102:103] op_sel_hi:[0,1]
	v_max_f32_e32 v97, 0, v97
	v_mul_f32_e32 v104, v96, v96
	v_max_f32_e32 v96, 0, v101
	v_max_f32_e32 v98, 0, v98
	v_max_f32_e32 v100, 0, v100
	v_mul_f32_e32 v96, v96, v96
	v_mul_f32_e32 v101, v97, v97
	v_max_f32_e32 v97, 0, v102
	v_mul_f32_e32 v102, v98, v98
	v_max_f32_e32 v98, 0, v103
	v_max_f32_e32 v99, 0, v99
	v_mul_f32_e32 v100, v100, v100
	v_mul_f32_e32 v97, v97, v97
	v_mul_f32_e32 v98, v98, v98
	v_mul_f32_e32 v99, v99, v99
	v_cvt_pk_bf16_f32 v96, v100, v96
	v_cvt_pk_bf16_f32 v97, v97, v98
	v_cvt_pk_bf16_f32 v98, v104, v101
	v_cvt_pk_bf16_f32 v99, v102, v99
	global_store_dwordx4 v[112:113], v[96:99], off offset:256
	v_mov_b32_e32 v236, v156
	v_pk_mul_f32 v[88:89], v[156:157], v[88:89] op_sel_hi:[0,1]
	v_pk_mul_f32 v[92:93], v[156:157], v[92:93] op_sel_hi:[0,1]
	v_or_b32_e32 v96, 32, v144
	v_ashrrev_i32_e32 v97, 31, v96
	v_pk_mul_f32 v[90:91], v[156:157], v[90:91] op_sel_hi:[0,1]
	v_max_f32_e32 v88, 0, v88
	v_mov_b32_e32 v249, 0x8100
	v_mad_u64_u32 v[250:251], s[96:97], v96, v249, 0
	v_mov_b32_e32 v96, v250
	v_mov_b32_e32 v97, v251
	v_pk_mul_f32 v[94:95], v[156:157], v[94:95] op_sel_hi:[0,1]
	v_mul_f32_e32 v98, v88, v88
	v_max_f32_e32 v88, 0, v93
	v_max_f32_e32 v89, 0, v89
	v_max_f32_e32 v90, 0, v90
	v_lshl_add_u64 v[96:97], s[10:11], 0, v[96:97]
	v_max_f32_e32 v92, 0, v92
	v_mul_f32_e32 v88, v88, v88
	v_mul_f32_e32 v93, v89, v89
	v_max_f32_e32 v89, 0, v94
	v_mul_f32_e32 v94, v90, v90
	v_max_f32_e32 v90, 0, v95
	v_max_f32_e32 v91, 0, v91
	v_pk_mul_f32 v[80:81], v[156:157], v[80:81] op_sel_hi:[0,1]
	v_lshl_add_u64 v[96:97], v[96:97], 0, v[164:165]
	v_mul_f32_e32 v92, v92, v92
	v_mul_f32_e32 v89, v89, v89
	v_mul_f32_e32 v90, v90, v90
	v_mul_f32_e32 v91, v91, v91
	v_cvt_pk_bf16_f32 v88, v92, v88
	v_pk_mul_f32 v[84:85], v[156:157], v[84:85] op_sel_hi:[0,1]
	v_pk_mul_f32 v[82:83], v[156:157], v[82:83] op_sel_hi:[0,1]
	v_max_f32_e32 v80, 0, v80
	v_cvt_pk_bf16_f32 v89, v89, v90
	v_cvt_pk_bf16_f32 v90, v98, v93
	v_cvt_pk_bf16_f32 v91, v94, v91
	global_store_dwordx4 v[96:97], v[88:91], off
	v_pk_mul_f32 v[86:87], v[156:157], v[86:87] op_sel_hi:[0,1]
	v_max_f32_e32 v81, 0, v81
	v_mul_f32_e32 v88, v80, v80
	v_max_f32_e32 v80, 0, v85
	v_max_f32_e32 v82, 0, v82
	v_max_f32_e32 v84, 0, v84
	v_mul_f32_e32 v80, v80, v80
	v_mul_f32_e32 v85, v81, v81
	v_max_f32_e32 v81, 0, v86
	v_mul_f32_e32 v86, v82, v82
	v_max_f32_e32 v82, 0, v87
	v_max_f32_e32 v83, 0, v83
	v_mul_f32_e32 v84, v84, v84
	v_mul_f32_e32 v81, v81, v81
	v_mul_f32_e32 v82, v82, v82
	v_mul_f32_e32 v83, v83, v83
	v_cvt_pk_bf16_f32 v80, v84, v80
	v_cvt_pk_bf16_f32 v81, v81, v82
	v_cvt_pk_bf16_f32 v82, v88, v85
	v_cvt_pk_bf16_f32 v83, v86, v83
	global_store_dwordx4 v[96:97], v[80:83], off offset:256
	v_mov_b32_e32 v238, v158
	v_pk_mul_f32 v[72:73], v[158:159], v[72:73] op_sel_hi:[0,1]
	v_pk_mul_f32 v[76:77], v[158:159], v[76:77] op_sel_hi:[0,1]
	v_or_b32_e32 v80, 48, v144
	v_ashrrev_i32_e32 v81, 31, v80
	v_pk_mul_f32 v[74:75], v[158:159], v[74:75] op_sel_hi:[0,1]
	v_max_f32_e32 v72, 0, v72
	v_mov_b32_e32 v249, 0x8100
	v_mad_u64_u32 v[250:251], s[96:97], v80, v249, 0
	v_mov_b32_e32 v80, v250
	v_mov_b32_e32 v81, v251
	v_pk_mul_f32 v[78:79], v[158:159], v[78:79] op_sel_hi:[0,1]
	v_mul_f32_e32 v82, v72, v72
	v_max_f32_e32 v72, 0, v77
	v_max_f32_e32 v73, 0, v73
	v_max_f32_e32 v74, 0, v74
	v_lshl_add_u64 v[80:81], s[10:11], 0, v[80:81]
	v_max_f32_e32 v76, 0, v76
	v_mul_f32_e32 v72, v72, v72
	v_mul_f32_e32 v77, v73, v73
	v_max_f32_e32 v73, 0, v78
	v_mul_f32_e32 v78, v74, v74
	v_max_f32_e32 v74, 0, v79
	v_max_f32_e32 v75, 0, v75
	v_pk_mul_f32 v[66:67], v[158:159], v[66:67] op_sel_hi:[0,1]
	v_pk_mul_f32 v[64:65], v[158:159], v[64:65] op_sel_hi:[0,1]
	v_lshl_add_u64 v[80:81], v[80:81], 0, v[164:165]
	v_mul_f32_e32 v76, v76, v76
	v_mul_f32_e32 v73, v73, v73
	v_mul_f32_e32 v74, v74, v74
	v_mul_f32_e32 v75, v75, v75
	v_cvt_pk_bf16_f32 v72, v76, v72
	v_pk_mul_f32 v[70:71], v[158:159], v[70:71] op_sel_hi:[0,1]
	v_pk_mul_f32 v[68:69], v[158:159], v[68:69] op_sel_hi:[0,1]
	v_max_f32_e32 v64, 0, v64
	v_max_f32_e32 v65, 0, v65
	v_max_f32_e32 v66, 0, v66
	v_cvt_f32_i32_e32 v62, v62
	v_cvt_pk_bf16_f32 v73, v73, v74
	v_cvt_pk_bf16_f32 v74, v82, v77
	v_cvt_pk_bf16_f32 v75, v78, v75
	global_store_dwordx4 v[80:81], v[72:75], off
	v_max_f32_e32 v68, 0, v68
	v_max_f32_e32 v67, 0, v67
	v_mul_f32_e32 v72, v64, v64
	v_max_f32_e32 v64, 0, v69
	v_mul_f32_e32 v69, v65, v65
	v_max_f32_e32 v65, 0, v70
	v_mul_f32_e32 v70, v66, v66
	v_max_f32_e32 v66, 0, v71
	v_mul_f32_e32 v64, v64, v64
	v_mul_f32_e32 v65, v65, v65
	v_mul_f32_e32 v66, v66, v66
	v_mov_b32_e32 v240, v154
	v_pk_mul_f32 v[56:57], v[154:155], v[56:57] op_sel_hi:[0,1]
	v_cvt_f32_i32_e32 v49, v49
	v_cvt_f32_i32_e32 v51, v51
	v_cvt_f32_i32_e32 v50, v50
	v_cvt_f32_i32_e32 v48, v48
	v_mul_f32_e32 v68, v68, v68
	v_mul_f32_e32 v67, v67, v67
	v_cvt_pk_bf16_f32 v64, v68, v64
	v_cvt_pk_bf16_f32 v65, v65, v66
	v_cvt_pk_bf16_f32 v66, v72, v69
	v_pk_mul_f32 v[60:61], v[154:155], v[60:61] op_sel_hi:[0,1]
	v_pk_mul_f32 v[58:59], v[154:155], v[58:59] op_sel_hi:[0,1]
	v_max_f32_e32 v56, 0, v56
	v_cvt_f32_i32_e32 v53, v53
	v_cvt_f32_i32_e32 v52, v52
	v_cvt_f32_i32_e32 v55, v55
	v_cvt_f32_i32_e32 v54, v54
	v_cvt_pk_bf16_f32 v67, v70, v67
	global_store_dwordx4 v[80:81], v[64:67], off offset:256
	v_pk_mul_f32 v[62:63], v[154:155], v[62:63] op_sel_hi:[0,1]
	v_max_f32_e32 v60, 0, v60
	v_mul_f32_e32 v66, v56, v56
	v_max_f32_e32 v56, 0, v61
	v_max_f32_e32 v57, 0, v57
	v_max_f32_e32 v58, 0, v58
	v_mul_f32_e32 v60, v60, v60
	v_mul_f32_e32 v56, v56, v56
	v_mul_f32_e32 v61, v57, v57
	v_max_f32_e32 v57, 0, v62
	v_mul_f32_e32 v62, v58, v58
	v_max_f32_e32 v58, 0, v63
	v_cvt_f32_i32_e32 v41, v41
	v_cvt_f32_i32_e32 v40, v40
	v_mul_f32_e32 v57, v57, v57
	v_max_f32_e32 v59, 0, v59
	v_mul_f32_e32 v58, v58, v58
	v_cvt_pk_bf16_f32 v56, v60, v56
	v_add_co_u32_e32 v60, vcc, s56, v148
	v_pk_mul_f32 v[50:51], v[154:155], v[50:51] op_sel_hi:[0,1]
	v_pk_mul_f32 v[48:49], v[154:155], v[48:49] op_sel_hi:[0,1]
	v_cvt_f32_i32_e32 v45, v45
	v_cvt_f32_i32_e32 v44, v44
	v_cvt_f32_i32_e32 v43, v43
	v_cvt_f32_i32_e32 v42, v42
	v_mul_f32_e32 v59, v59, v59
	v_cvt_pk_bf16_f32 v57, v57, v58
	v_cvt_pk_bf16_f32 v58, v66, v61
	v_addc_co_u32_e32 v61, vcc, 0, v149, vcc
	v_pk_mul_f32 v[54:55], v[154:155], v[54:55] op_sel_hi:[0,1]
	v_pk_mul_f32 v[52:53], v[154:155], v[52:53] op_sel_hi:[0,1]
	v_max_f32_e32 v48, 0, v48
	v_max_f32_e32 v49, 0, v49
	v_max_f32_e32 v50, 0, v50
	v_cvt_f32_i32_e32 v47, v47
	v_cvt_f32_i32_e32 v46, v46
	v_cvt_pk_bf16_f32 v59, v62, v59
	global_store_dwordx4 v[60:61], v[56:59], off
	v_max_f32_e32 v52, 0, v52
	v_max_f32_e32 v51, 0, v51
	v_mul_f32_e32 v56, v48, v48
	v_max_f32_e32 v48, 0, v53
	v_mul_f32_e32 v53, v49, v49
	v_max_f32_e32 v49, 0, v54
	v_mul_f32_e32 v54, v50, v50
	v_max_f32_e32 v50, 0, v55
	v_mul_f32_e32 v48, v48, v48
	v_mul_f32_e32 v49, v49, v49
	v_mul_f32_e32 v50, v50, v50
	v_mov_b32_e32 v242, v152
	v_pk_mul_f32 v[40:41], v[152:153], v[40:41] op_sel_hi:[0,1]
	v_cvt_f32_i32_e32 v33, v33
	v_cvt_f32_i32_e32 v35, v35
	v_cvt_f32_i32_e32 v34, v34
	v_cvt_f32_i32_e32 v32, v32
	v_lshl_add_u64 v[64:65], v[148:149], 0, s[20:21]
	v_mul_f32_e32 v52, v52, v52
	v_mul_f32_e32 v51, v51, v51
	v_cvt_pk_bf16_f32 v48, v52, v48
	v_cvt_pk_bf16_f32 v49, v49, v50
	v_cvt_pk_bf16_f32 v50, v56, v53
	v_pk_mul_f32 v[44:45], v[152:153], v[44:45] op_sel_hi:[0,1]
	v_pk_mul_f32 v[42:43], v[152:153], v[42:43] op_sel_hi:[0,1]
	v_max_f32_e32 v40, 0, v40
	v_cvt_f32_i32_e32 v37, v37
	v_cvt_f32_i32_e32 v36, v36
	v_cvt_f32_i32_e32 v39, v39
	v_cvt_f32_i32_e32 v38, v38
	v_cvt_pk_bf16_f32 v51, v54, v51
	global_store_dwordx4 v[64:65], v[48:51], off offset:256
	v_pk_mul_f32 v[46:47], v[152:153], v[46:47] op_sel_hi:[0,1]
	v_max_f32_e32 v44, 0, v44
	v_mul_f32_e32 v50, v40, v40
	v_max_f32_e32 v40, 0, v45
	v_max_f32_e32 v41, 0, v41
	v_max_f32_e32 v42, 0, v42
	v_mul_f32_e32 v44, v44, v44
	v_mul_f32_e32 v40, v40, v40
	v_mul_f32_e32 v45, v41, v41
	v_max_f32_e32 v41, 0, v46
	v_mul_f32_e32 v46, v42, v42
	v_max_f32_e32 v42, 0, v47
	v_cvt_f32_i32_e32 v25, v25
	v_cvt_f32_i32_e32 v24, v24
	v_mul_f32_e32 v41, v41, v41
	v_max_f32_e32 v43, 0, v43
	v_mul_f32_e32 v42, v42, v42
	v_cvt_pk_bf16_f32 v40, v44, v40
	v_add_co_u32_e32 v44, vcc, s57, v148
	v_pk_mul_f32 v[34:35], v[152:153], v[34:35] op_sel_hi:[0,1]
	v_pk_mul_f32 v[32:33], v[152:153], v[32:33] op_sel_hi:[0,1]
	v_cvt_f32_i32_e32 v29, v29
	v_cvt_f32_i32_e32 v28, v28
	v_cvt_f32_i32_e32 v27, v27
	v_cvt_f32_i32_e32 v26, v26
	v_mul_f32_e32 v43, v43, v43
	v_cvt_pk_bf16_f32 v41, v41, v42
	v_cvt_pk_bf16_f32 v42, v50, v45
	v_addc_co_u32_e32 v45, vcc, 0, v149, vcc
	v_pk_mul_f32 v[38:39], v[152:153], v[38:39] op_sel_hi:[0,1]
	v_pk_mul_f32 v[36:37], v[152:153], v[36:37] op_sel_hi:[0,1]
	v_max_f32_e32 v32, 0, v32
	v_max_f32_e32 v33, 0, v33
	v_max_f32_e32 v34, 0, v34
	v_cvt_f32_i32_e32 v31, v31
	v_cvt_f32_i32_e32 v30, v30
	v_cvt_pk_bf16_f32 v43, v46, v43
	global_store_dwordx4 v[44:45], v[40:43], off
	v_max_f32_e32 v36, 0, v36
	v_max_f32_e32 v35, 0, v35
	v_mul_f32_e32 v40, v32, v32
	v_max_f32_e32 v32, 0, v37
	v_mul_f32_e32 v37, v33, v33
	v_max_f32_e32 v33, 0, v38
	v_mul_f32_e32 v38, v34, v34
	v_max_f32_e32 v34, 0, v39
	v_mul_f32_e32 v32, v32, v32
	v_mul_f32_e32 v33, v33, v33
	v_mul_f32_e32 v34, v34, v34
	v_mov_b32_e32 v244, v150
	v_pk_mul_f32 v[24:25], v[150:151], v[24:25] op_sel_hi:[0,1]
	v_cvt_f32_i32_e32 v17, v17
	v_cvt_f32_i32_e32 v19, v19
	v_cvt_f32_i32_e32 v18, v18
	v_cvt_f32_i32_e32 v16, v16
	v_rsq_f32_e32 v147, v147
	v_lshl_add_u64 v[48:49], v[148:149], 0, s[22:23]
	v_mul_f32_e32 v36, v36, v36
	v_mul_f32_e32 v35, v35, v35
	v_cvt_pk_bf16_f32 v32, v36, v32
	v_cvt_pk_bf16_f32 v33, v33, v34
	v_cvt_pk_bf16_f32 v34, v40, v37
	v_pk_mul_f32 v[28:29], v[150:151], v[28:29] op_sel_hi:[0,1]
	v_pk_mul_f32 v[26:27], v[150:151], v[26:27] op_sel_hi:[0,1]
	v_max_f32_e32 v24, 0, v24
	v_cvt_f32_i32_e32 v21, v21
	v_cvt_f32_i32_e32 v20, v20
	v_cvt_f32_i32_e32 v23, v23
	v_cvt_f32_i32_e32 v22, v22
	v_cvt_pk_bf16_f32 v35, v38, v35
	global_store_dwordx4 v[48:49], v[32:35], off offset:256
	v_pk_mul_f32 v[30:31], v[150:151], v[30:31] op_sel_hi:[0,1]
	v_max_f32_e32 v28, 0, v28
	v_mul_f32_e32 v34, v24, v24
	v_max_f32_e32 v24, 0, v29
	v_max_f32_e32 v25, 0, v25
	v_max_f32_e32 v26, 0, v26
	v_mul_f32_e32 v28, v28, v28
	v_mul_f32_e32 v24, v24, v24
	v_mul_f32_e32 v29, v25, v25
	v_max_f32_e32 v25, 0, v30
	v_mul_f32_e32 v30, v26, v26
	v_max_f32_e32 v26, 0, v31
	v_cvt_f32_i32_e32 v9, v9
	v_cvt_f32_i32_e32 v8, v8
	v_mul_f32_e32 v25, v25, v25
	v_max_f32_e32 v27, 0, v27
	v_mul_f32_e32 v26, v26, v26
	v_cvt_pk_bf16_f32 v24, v28, v24
	v_add_co_u32_e32 v28, vcc, s58, v148
	v_pk_mul_f32 v[18:19], v[150:151], v[18:19] op_sel_hi:[0,1]
	v_pk_mul_f32 v[16:17], v[150:151], v[16:17] op_sel_hi:[0,1]
	v_cvt_f32_i32_e32 v13, v13
	v_cvt_f32_i32_e32 v12, v12
	v_cvt_f32_i32_e32 v11, v11
	v_cvt_f32_i32_e32 v10, v10
	v_mul_f32_e32 v147, 0x37a34f4c, v147
	v_mul_f32_e32 v27, v27, v27
	v_cvt_pk_bf16_f32 v25, v25, v26
	v_cvt_pk_bf16_f32 v26, v34, v29
	v_addc_co_u32_e32 v29, vcc, 0, v149, vcc
	v_pk_mul_f32 v[22:23], v[150:151], v[22:23] op_sel_hi:[0,1]
	v_pk_mul_f32 v[20:21], v[150:151], v[20:21] op_sel_hi:[0,1]
	v_max_f32_e32 v16, 0, v16
	v_max_f32_e32 v17, 0, v17
	v_max_f32_e32 v18, 0, v18
	v_cvt_f32_i32_e32 v15, v15
	v_cvt_f32_i32_e32 v14, v14
	v_mul_f32_e32 v146, v147, v146
	v_cvt_pk_bf16_f32 v27, v30, v27
	global_store_dwordx4 v[28:29], v[24:27], off
	v_max_f32_e32 v20, 0, v20
	v_max_f32_e32 v19, 0, v19
	v_mul_f32_e32 v24, v16, v16
	v_max_f32_e32 v16, 0, v21
	v_mul_f32_e32 v21, v17, v17
	v_max_f32_e32 v17, 0, v22
	v_mul_f32_e32 v22, v18, v18
	v_max_f32_e32 v18, 0, v23
	v_mul_f32_e32 v16, v16, v16
	v_mul_f32_e32 v17, v17, v17
	v_mul_f32_e32 v18, v18, v18
	v_mov_b32_e32 v246, v146
	v_pk_mul_f32 v[8:9], v[146:147], v[8:9] op_sel_hi:[0,1]
	v_cvt_f32_i32_e32 v1, v1
	v_cvt_f32_i32_e32 v3, v3
	v_cvt_f32_i32_e32 v2, v2
	v_cvt_f32_i32_e32 v0, v0
	v_lshl_add_u64 v[32:33], v[148:149], 0, s[24:25]
	v_mul_f32_e32 v20, v20, v20
	v_mul_f32_e32 v19, v19, v19
	v_cvt_pk_bf16_f32 v16, v20, v16
	v_cvt_pk_bf16_f32 v17, v17, v18
	v_cvt_pk_bf16_f32 v18, v24, v21
	v_pk_mul_f32 v[12:13], v[146:147], v[12:13] op_sel_hi:[0,1]
	v_pk_mul_f32 v[10:11], v[146:147], v[10:11] op_sel_hi:[0,1]
	v_max_f32_e32 v8, 0, v8
	v_cvt_f32_i32_e32 v5, v5
	v_cvt_f32_i32_e32 v4, v4
	v_cvt_f32_i32_e32 v7, v7
	v_cvt_f32_i32_e32 v6, v6
	v_cvt_pk_bf16_f32 v19, v22, v19
	global_store_dwordx4 v[32:33], v[16:19], off offset:256
	v_pk_mul_f32 v[14:15], v[146:147], v[14:15] op_sel_hi:[0,1]
	v_max_f32_e32 v12, 0, v12
	v_mul_f32_e32 v18, v8, v8
	v_max_f32_e32 v8, 0, v13
	v_max_f32_e32 v9, 0, v9
	v_max_f32_e32 v10, 0, v10
	v_mul_f32_e32 v12, v12, v12
	v_mul_f32_e32 v8, v8, v8
	v_mul_f32_e32 v13, v9, v9
	v_max_f32_e32 v9, 0, v14
	v_mul_f32_e32 v14, v10, v10
	v_max_f32_e32 v10, 0, v15
	v_mul_f32_e32 v9, v9, v9
	v_max_f32_e32 v11, 0, v11
	v_mul_f32_e32 v10, v10, v10
	v_cvt_pk_bf16_f32 v8, v12, v8
	v_add_co_u32_e32 v12, vcc, s59, v148
	v_pk_mul_f32 v[2:3], v[146:147], v[2:3] op_sel_hi:[0,1]
	v_pk_mul_f32 v[0:1], v[146:147], v[0:1] op_sel_hi:[0,1]
	v_mul_f32_e32 v11, v11, v11
	v_cvt_pk_bf16_f32 v9, v9, v10
	v_cvt_pk_bf16_f32 v10, v18, v13
	v_addc_co_u32_e32 v13, vcc, 0, v149, vcc
	v_pk_mul_f32 v[6:7], v[146:147], v[6:7] op_sel_hi:[0,1]
	v_pk_mul_f32 v[4:5], v[146:147], v[4:5] op_sel_hi:[0,1]
	v_max_f32_e32 v0, 0, v0
	v_max_f32_e32 v1, 0, v1
	v_max_f32_e32 v2, 0, v2
	v_cvt_pk_bf16_f32 v11, v14, v11
	global_store_dwordx4 v[12:13], v[8:11], off
	v_max_f32_e32 v3, 0, v3
	v_lshl_add_u64 v[16:17], v[148:149], 0, s[26:27]
	v_mul_f32_e32 v8, v0, v0
	v_max_f32_e32 v0, 0, v5
	v_mul_f32_e32 v5, v1, v1
	v_max_f32_e32 v1, 0, v6
	v_mul_f32_e32 v6, v2, v2
	v_max_f32_e32 v2, 0, v7
	v_max_f32_e32 v4, 0, v4
	v_mul_f32_e32 v0, v0, v0
	v_mul_f32_e32 v1, v1, v1
	v_mul_f32_e32 v2, v2, v2
	v_mul_f32_e32 v3, v3, v3
	s_andn2_b64 vcc, exec, s[2:3]
	s_mov_b64 s[0:1], -1
	v_mul_f32_e32 v4, v4, v4
	v_cvt_pk_bf16_f32 v0, v4, v0
	v_cvt_pk_bf16_f32 v1, v1, v2
	v_cvt_pk_bf16_f32 v2, v8, v5
	v_cvt_pk_bf16_f32 v3, v6, v3
	global_store_dwordx4 v[16:17], v[0:3], off offset:256
	s_cbranch_vccnz .LBB0_542
.Ljoin_p5:
	s_andn2_b64 vcc, exec, s[8:9]
	s_cbranch_vccnz .LBB0_541
	s_barrier
	s_branch .LBB0_541
.Llean_p5:
	v_lshl_add_u32 v144, s0, 8, v155
	v_mov_b32_e32 v145, 0
	v_lshl_or_b32 v148, s60, 8, v159
	v_mov_b32_e32 v149, 0
	v_mov_b32_e32 v146, 0x8100
	v_mad_u64_u32 v[146:147], s[96:97], v144, v146, 0
	v_lshlrev_b64 v[148:149], 1, v[148:149]
	v_lshl_add_u64 v[146:147], s[10:11], 0, v[146:147]
	v_lshl_add_u64 v[150:151], v[146:147], 0, v[148:149]
	v_cvt_f32_i32_e32 v124, v124
	v_cvt_f32_i32_e32 v125, v125
	v_cvt_f32_i32_e32 v126, v126
	v_cvt_f32_i32_e32 v127, v127
	v_cvt_f32_i32_e32 v120, v120
	v_cvt_f32_i32_e32 v121, v121
	v_cvt_f32_i32_e32 v122, v122
	v_cvt_f32_i32_e32 v123, v123
	v_pk_mul_f32 v[124:125], v[232:233], v[124:125] op_sel_hi:[0,1]
	v_pk_mul_f32 v[126:127], v[232:233], v[126:127] op_sel_hi:[0,1]
	v_pk_mul_f32 v[120:121], v[232:233], v[120:121] op_sel_hi:[0,1]
	v_pk_mul_f32 v[122:123], v[232:233], v[122:123] op_sel_hi:[0,1]
	v_max_f32_e32 v124, 0, v124
	v_max_f32_e32 v125, 0, v125
	v_max_f32_e32 v126, 0, v126
	v_max_f32_e32 v127, 0, v127
	v_max_f32_e32 v120, 0, v120
	v_max_f32_e32 v121, 0, v121
	v_max_f32_e32 v122, 0, v122
	v_max_f32_e32 v123, 0, v123
	v_pk_mul_f32 v[124:125], v[124:125], v[124:125]
	v_pk_mul_f32 v[126:127], v[126:127], v[126:127]
	v_pk_mul_f32 v[120:121], v[120:121], v[120:121]
	v_pk_mul_f32 v[122:123], v[122:123], v[122:123]
	v_cvt_pk_bf16_f32 v170, v124, v125
	v_cvt_pk_bf16_f32 v171, v126, v127
	v_cvt_pk_bf16_f32 v172, v120, v121
	v_cvt_pk_bf16_f32 v173, v122, v123
	global_store_dwordx4 v[150:151], v[170:173], off
	v_cvt_f32_i32_e32 v116, v116
	v_cvt_f32_i32_e32 v117, v117
	v_cvt_f32_i32_e32 v118, v118
	v_cvt_f32_i32_e32 v119, v119
	v_cvt_f32_i32_e32 v112, v112
	v_cvt_f32_i32_e32 v113, v113
	v_cvt_f32_i32_e32 v114, v114
	v_cvt_f32_i32_e32 v115, v115
	v_pk_mul_f32 v[116:117], v[232:233], v[116:117] op_sel_hi:[0,1]
	v_pk_mul_f32 v[118:119], v[232:233], v[118:119] op_sel_hi:[0,1]
	v_pk_mul_f32 v[112:113], v[232:233], v[112:113] op_sel_hi:[0,1]
	v_pk_mul_f32 v[114:115], v[232:233], v[114:115] op_sel_hi:[0,1]
	v_max_f32_e32 v116, 0, v116
	v_max_f32_e32 v117, 0, v117
	v_max_f32_e32 v118, 0, v118
	v_max_f32_e32 v119, 0, v119
	v_max_f32_e32 v112, 0, v112
	v_max_f32_e32 v113, 0, v113
	v_max_f32_e32 v114, 0, v114
	v_max_f32_e32 v115, 0, v115
	v_pk_mul_f32 v[116:117], v[116:117], v[116:117]
	v_pk_mul_f32 v[118:119], v[118:119], v[118:119]
	v_pk_mul_f32 v[112:113], v[112:113], v[112:113]
	v_pk_mul_f32 v[114:115], v[114:115], v[114:115]
	v_cvt_pk_bf16_f32 v174, v116, v117
	v_cvt_pk_bf16_f32 v175, v118, v119
	v_cvt_pk_bf16_f32 v176, v112, v113
	v_cvt_pk_bf16_f32 v177, v114, v115
	global_store_dwordx4 v[150:151], v[174:177], off offset:256
	v_add_co_u32_e32 v152, vcc, 0x81000, v150
	s_nop 1
	v_addc_co_u32_e32 v153, vcc, 0, v151, vcc
	v_cvt_f32_i32_e32 v108, v108
	v_cvt_f32_i32_e32 v109, v109
	v_cvt_f32_i32_e32 v110, v110
	v_cvt_f32_i32_e32 v111, v111
	v_cvt_f32_i32_e32 v104, v104
	v_cvt_f32_i32_e32 v105, v105
	v_cvt_f32_i32_e32 v106, v106
	v_cvt_f32_i32_e32 v107, v107
	v_pk_mul_f32 v[108:109], v[234:235], v[108:109] op_sel_hi:[0,1]
	v_pk_mul_f32 v[110:111], v[234:235], v[110:111] op_sel_hi:[0,1]
	v_pk_mul_f32 v[104:105], v[234:235], v[104:105] op_sel_hi:[0,1]
	v_pk_mul_f32 v[106:107], v[234:235], v[106:107] op_sel_hi:[0,1]
	v_max_f32_e32 v108, 0, v108
	v_max_f32_e32 v109, 0, v109
	v_max_f32_e32 v110, 0, v110
	v_max_f32_e32 v111, 0, v111
	v_max_f32_e32 v104, 0, v104
	v_max_f32_e32 v105, 0, v105
	v_max_f32_e32 v106, 0, v106
	v_max_f32_e32 v107, 0, v107
	v_pk_mul_f32 v[108:109], v[108:109], v[108:109]
	v_pk_mul_f32 v[110:111], v[110:111], v[110:111]
	v_pk_mul_f32 v[104:105], v[104:105], v[104:105]
	v_pk_mul_f32 v[106:107], v[106:107], v[106:107]
	v_cvt_pk_bf16_f32 v178, v108, v109
	v_cvt_pk_bf16_f32 v179, v110, v111
	v_cvt_pk_bf16_f32 v180, v104, v105
	v_cvt_pk_bf16_f32 v181, v106, v107
	global_store_dwordx4 v[152:153], v[178:181], off
	v_cvt_f32_i32_e32 v100, v100
	v_cvt_f32_i32_e32 v101, v101
	v_cvt_f32_i32_e32 v102, v102
	v_cvt_f32_i32_e32 v103, v103
	v_cvt_f32_i32_e32 v96, v96
	v_cvt_f32_i32_e32 v97, v97
	v_cvt_f32_i32_e32 v98, v98
	v_cvt_f32_i32_e32 v99, v99
	v_pk_mul_f32 v[100:101], v[234:235], v[100:101] op_sel_hi:[0,1]
	v_pk_mul_f32 v[102:103], v[234:235], v[102:103] op_sel_hi:[0,1]
	v_pk_mul_f32 v[96:97], v[234:235], v[96:97] op_sel_hi:[0,1]
	v_pk_mul_f32 v[98:99], v[234:235], v[98:99] op_sel_hi:[0,1]
	v_max_f32_e32 v100, 0, v100
	v_max_f32_e32 v101, 0, v101
	v_max_f32_e32 v102, 0, v102
	v_max_f32_e32 v103, 0, v103
	v_max_f32_e32 v96, 0, v96
	v_max_f32_e32 v97, 0, v97
	v_max_f32_e32 v98, 0, v98
	v_max_f32_e32 v99, 0, v99
	v_pk_mul_f32 v[100:101], v[100:101], v[100:101]
	v_pk_mul_f32 v[102:103], v[102:103], v[102:103]
	v_pk_mul_f32 v[96:97], v[96:97], v[96:97]
	v_pk_mul_f32 v[98:99], v[98:99], v[98:99]
	v_cvt_pk_bf16_f32 v182, v100, v101
	v_cvt_pk_bf16_f32 v183, v102, v103
	v_cvt_pk_bf16_f32 v184, v96, v97
	v_cvt_pk_bf16_f32 v185, v98, v99
	global_store_dwordx4 v[152:153], v[182:185], off offset:256
	v_add_co_u32_e32 v152, vcc, 0x102000, v150
	s_nop 1
	v_addc_co_u32_e32 v153, vcc, 0, v151, vcc
	v_cvt_f32_i32_e32 v92, v92
	v_cvt_f32_i32_e32 v93, v93
	v_cvt_f32_i32_e32 v94, v94
	v_cvt_f32_i32_e32 v95, v95
	v_cvt_f32_i32_e32 v88, v88
	v_cvt_f32_i32_e32 v89, v89
	v_cvt_f32_i32_e32 v90, v90
	v_cvt_f32_i32_e32 v91, v91
	v_pk_mul_f32 v[92:93], v[236:237], v[92:93] op_sel_hi:[0,1]
	v_pk_mul_f32 v[94:95], v[236:237], v[94:95] op_sel_hi:[0,1]
	v_pk_mul_f32 v[88:89], v[236:237], v[88:89] op_sel_hi:[0,1]
	v_pk_mul_f32 v[90:91], v[236:237], v[90:91] op_sel_hi:[0,1]
	v_max_f32_e32 v92, 0, v92
	v_max_f32_e32 v93, 0, v93
	v_max_f32_e32 v94, 0, v94
	v_max_f32_e32 v95, 0, v95
	v_max_f32_e32 v88, 0, v88
	v_max_f32_e32 v89, 0, v89
	v_max_f32_e32 v90, 0, v90
	v_max_f32_e32 v91, 0, v91
	v_pk_mul_f32 v[92:93], v[92:93], v[92:93]
	v_pk_mul_f32 v[94:95], v[94:95], v[94:95]
	v_pk_mul_f32 v[88:89], v[88:89], v[88:89]
	v_pk_mul_f32 v[90:91], v[90:91], v[90:91]
	v_cvt_pk_bf16_f32 v186, v92, v93
	v_cvt_pk_bf16_f32 v187, v94, v95
	v_cvt_pk_bf16_f32 v188, v88, v89
	v_cvt_pk_bf16_f32 v189, v90, v91
	global_store_dwordx4 v[152:153], v[186:189], off
	v_cvt_f32_i32_e32 v84, v84
	v_cvt_f32_i32_e32 v85, v85
	v_cvt_f32_i32_e32 v86, v86
	v_cvt_f32_i32_e32 v87, v87
	v_cvt_f32_i32_e32 v80, v80
	v_cvt_f32_i32_e32 v81, v81
	v_cvt_f32_i32_e32 v82, v82
	v_cvt_f32_i32_e32 v83, v83
	v_pk_mul_f32 v[84:85], v[236:237], v[84:85] op_sel_hi:[0,1]
	v_pk_mul_f32 v[86:87], v[236:237], v[86:87] op_sel_hi:[0,1]
	v_pk_mul_f32 v[80:81], v[236:237], v[80:81] op_sel_hi:[0,1]
	v_pk_mul_f32 v[82:83], v[236:237], v[82:83] op_sel_hi:[0,1]
	v_max_f32_e32 v84, 0, v84
	v_max_f32_e32 v85, 0, v85
	v_max_f32_e32 v86, 0, v86
	v_max_f32_e32 v87, 0, v87
	v_max_f32_e32 v80, 0, v80
	v_max_f32_e32 v81, 0, v81
	v_max_f32_e32 v82, 0, v82
	v_max_f32_e32 v83, 0, v83
	v_pk_mul_f32 v[84:85], v[84:85], v[84:85]
	v_pk_mul_f32 v[86:87], v[86:87], v[86:87]
	v_pk_mul_f32 v[80:81], v[80:81], v[80:81]
	v_pk_mul_f32 v[82:83], v[82:83], v[82:83]
	v_cvt_pk_bf16_f32 v190, v84, v85
	v_cvt_pk_bf16_f32 v191, v86, v87
	v_cvt_pk_bf16_f32 v192, v80, v81
	v_cvt_pk_bf16_f32 v193, v82, v83
	global_store_dwordx4 v[152:153], v[190:193], off offset:256
	v_add_co_u32_e32 v152, vcc, 0x183000, v150
	s_nop 1
	v_addc_co_u32_e32 v153, vcc, 0, v151, vcc
	v_cvt_f32_i32_e32 v76, v76
	v_cvt_f32_i32_e32 v77, v77
	v_cvt_f32_i32_e32 v78, v78
	v_cvt_f32_i32_e32 v79, v79
	v_cvt_f32_i32_e32 v72, v72
	v_cvt_f32_i32_e32 v73, v73
	v_cvt_f32_i32_e32 v74, v74
	v_cvt_f32_i32_e32 v75, v75
	v_pk_mul_f32 v[76:77], v[238:239], v[76:77] op_sel_hi:[0,1]
	v_pk_mul_f32 v[78:79], v[238:239], v[78:79] op_sel_hi:[0,1]
	v_pk_mul_f32 v[72:73], v[238:239], v[72:73] op_sel_hi:[0,1]
	v_pk_mul_f32 v[74:75], v[238:239], v[74:75] op_sel_hi:[0,1]
	v_max_f32_e32 v76, 0, v76
	v_max_f32_e32 v77, 0, v77
	v_max_f32_e32 v78, 0, v78
	v_max_f32_e32 v79, 0, v79
	v_max_f32_e32 v72, 0, v72
	v_max_f32_e32 v73, 0, v73
	v_max_f32_e32 v74, 0, v74
	v_max_f32_e32 v75, 0, v75
	v_pk_mul_f32 v[76:77], v[76:77], v[76:77]
	v_pk_mul_f32 v[78:79], v[78:79], v[78:79]
	v_pk_mul_f32 v[72:73], v[72:73], v[72:73]
	v_pk_mul_f32 v[74:75], v[74:75], v[74:75]
	v_cvt_pk_bf16_f32 v194, v76, v77
	v_cvt_pk_bf16_f32 v195, v78, v79
	v_cvt_pk_bf16_f32 v196, v72, v73
	v_cvt_pk_bf16_f32 v197, v74, v75
	global_store_dwordx4 v[152:153], v[194:197], off
	v_cvt_f32_i32_e32 v68, v68
	v_cvt_f32_i32_e32 v69, v69
	v_cvt_f32_i32_e32 v70, v70
	v_cvt_f32_i32_e32 v71, v71
	v_cvt_f32_i32_e32 v64, v64
	v_cvt_f32_i32_e32 v65, v65
	v_cvt_f32_i32_e32 v66, v66
	v_cvt_f32_i32_e32 v67, v67
	v_pk_mul_f32 v[68:69], v[238:239], v[68:69] op_sel_hi:[0,1]
	v_pk_mul_f32 v[70:71], v[238:239], v[70:71] op_sel_hi:[0,1]
	v_pk_mul_f32 v[64:65], v[238:239], v[64:65] op_sel_hi:[0,1]
	v_pk_mul_f32 v[66:67], v[238:239], v[66:67] op_sel_hi:[0,1]
	v_max_f32_e32 v68, 0, v68
	v_max_f32_e32 v69, 0, v69
	v_max_f32_e32 v70, 0, v70
	v_max_f32_e32 v71, 0, v71
	v_max_f32_e32 v64, 0, v64
	v_max_f32_e32 v65, 0, v65
	v_max_f32_e32 v66, 0, v66
	v_max_f32_e32 v67, 0, v67
	v_pk_mul_f32 v[68:69], v[68:69], v[68:69]
	v_pk_mul_f32 v[70:71], v[70:71], v[70:71]
	v_pk_mul_f32 v[64:65], v[64:65], v[64:65]
	v_pk_mul_f32 v[66:67], v[66:67], v[66:67]
	v_cvt_pk_bf16_f32 v198, v68, v69
	v_cvt_pk_bf16_f32 v199, v70, v71
	v_cvt_pk_bf16_f32 v200, v64, v65
	v_cvt_pk_bf16_f32 v201, v66, v67
	global_store_dwordx4 v[152:153], v[198:201], off offset:256
	v_add_co_u32_e32 v152, vcc, 0x408000, v150
	s_nop 1
	v_addc_co_u32_e32 v153, vcc, 0, v151, vcc
	v_cvt_f32_i32_e32 v60, v60
	v_cvt_f32_i32_e32 v61, v61
	v_cvt_f32_i32_e32 v62, v62
	v_cvt_f32_i32_e32 v63, v63
	v_cvt_f32_i32_e32 v56, v56
	v_cvt_f32_i32_e32 v57, v57
	v_cvt_f32_i32_e32 v58, v58
	v_cvt_f32_i32_e32 v59, v59
	v_pk_mul_f32 v[60:61], v[240:241], v[60:61] op_sel_hi:[0,1]
	v_pk_mul_f32 v[62:63], v[240:241], v[62:63] op_sel_hi:[0,1]
	v_pk_mul_f32 v[56:57], v[240:241], v[56:57] op_sel_hi:[0,1]
	v_pk_mul_f32 v[58:59], v[240:241], v[58:59] op_sel_hi:[0,1]
	v_max_f32_e32 v60, 0, v60
	v_max_f32_e32 v61, 0, v61
	v_max_f32_e32 v62, 0, v62
	v_max_f32_e32 v63, 0, v63
	v_max_f32_e32 v56, 0, v56
	v_max_f32_e32 v57, 0, v57
	v_max_f32_e32 v58, 0, v58
	v_max_f32_e32 v59, 0, v59
	v_pk_mul_f32 v[60:61], v[60:61], v[60:61]
	v_pk_mul_f32 v[62:63], v[62:63], v[62:63]
	v_pk_mul_f32 v[56:57], v[56:57], v[56:57]
	v_pk_mul_f32 v[58:59], v[58:59], v[58:59]
	v_cvt_pk_bf16_f32 v170, v60, v61
	v_cvt_pk_bf16_f32 v171, v62, v63
	v_cvt_pk_bf16_f32 v172, v56, v57
	v_cvt_pk_bf16_f32 v173, v58, v59
	global_store_dwordx4 v[152:153], v[170:173], off
	v_cvt_f32_i32_e32 v52, v52
	v_cvt_f32_i32_e32 v53, v53
	v_cvt_f32_i32_e32 v54, v54
	v_cvt_f32_i32_e32 v55, v55
	v_cvt_f32_i32_e32 v48, v48
	v_cvt_f32_i32_e32 v49, v49
	v_cvt_f32_i32_e32 v50, v50
	v_cvt_f32_i32_e32 v51, v51
	v_pk_mul_f32 v[52:53], v[240:241], v[52:53] op_sel_hi:[0,1]
	v_pk_mul_f32 v[54:55], v[240:241], v[54:55] op_sel_hi:[0,1]
	v_pk_mul_f32 v[48:49], v[240:241], v[48:49] op_sel_hi:[0,1]
	v_pk_mul_f32 v[50:51], v[240:241], v[50:51] op_sel_hi:[0,1]
	v_max_f32_e32 v52, 0, v52
	v_max_f32_e32 v53, 0, v53
	v_max_f32_e32 v54, 0, v54
	v_max_f32_e32 v55, 0, v55
	v_max_f32_e32 v48, 0, v48
	v_max_f32_e32 v49, 0, v49
	v_max_f32_e32 v50, 0, v50
	v_max_f32_e32 v51, 0, v51
	v_pk_mul_f32 v[52:53], v[52:53], v[52:53]
	v_pk_mul_f32 v[54:55], v[54:55], v[54:55]
	v_pk_mul_f32 v[48:49], v[48:49], v[48:49]
	v_pk_mul_f32 v[50:51], v[50:51], v[50:51]
	v_cvt_pk_bf16_f32 v174, v52, v53
	v_cvt_pk_bf16_f32 v175, v54, v55
	v_cvt_pk_bf16_f32 v176, v48, v49
	v_cvt_pk_bf16_f32 v177, v50, v51
	global_store_dwordx4 v[152:153], v[174:177], off offset:256
	v_add_co_u32_e32 v152, vcc, 0x489000, v150
	s_nop 1
	v_addc_co_u32_e32 v153, vcc, 0, v151, vcc
	v_cvt_f32_i32_e32 v44, v44
	v_cvt_f32_i32_e32 v45, v45
	v_cvt_f32_i32_e32 v46, v46
	v_cvt_f32_i32_e32 v47, v47
	v_cvt_f32_i32_e32 v40, v40
	v_cvt_f32_i32_e32 v41, v41
	v_cvt_f32_i32_e32 v42, v42
	v_cvt_f32_i32_e32 v43, v43
	v_pk_mul_f32 v[44:45], v[242:243], v[44:45] op_sel_hi:[0,1]
	v_pk_mul_f32 v[46:47], v[242:243], v[46:47] op_sel_hi:[0,1]
	v_pk_mul_f32 v[40:41], v[242:243], v[40:41] op_sel_hi:[0,1]
	v_pk_mul_f32 v[42:43], v[242:243], v[42:43] op_sel_hi:[0,1]
	v_max_f32_e32 v44, 0, v44
	v_max_f32_e32 v45, 0, v45
	v_max_f32_e32 v46, 0, v46
	v_max_f32_e32 v47, 0, v47
	v_max_f32_e32 v40, 0, v40
	v_max_f32_e32 v41, 0, v41
	v_max_f32_e32 v42, 0, v42
	v_max_f32_e32 v43, 0, v43
	v_pk_mul_f32 v[44:45], v[44:45], v[44:45]
	v_pk_mul_f32 v[46:47], v[46:47], v[46:47]
	v_pk_mul_f32 v[40:41], v[40:41], v[40:41]
	v_pk_mul_f32 v[42:43], v[42:43], v[42:43]
	v_cvt_pk_bf16_f32 v178, v44, v45
	v_cvt_pk_bf16_f32 v179, v46, v47
	v_cvt_pk_bf16_f32 v180, v40, v41
	v_cvt_pk_bf16_f32 v181, v42, v43
	global_store_dwordx4 v[152:153], v[178:181], off
	v_cvt_f32_i32_e32 v36, v36
	v_cvt_f32_i32_e32 v37, v37
	v_cvt_f32_i32_e32 v38, v38
	v_cvt_f32_i32_e32 v39, v39
	v_cvt_f32_i32_e32 v32, v32
	v_cvt_f32_i32_e32 v33, v33
	v_cvt_f32_i32_e32 v34, v34
	v_cvt_f32_i32_e32 v35, v35
	v_pk_mul_f32 v[36:37], v[242:243], v[36:37] op_sel_hi:[0,1]
	v_pk_mul_f32 v[38:39], v[242:243], v[38:39] op_sel_hi:[0,1]
	v_pk_mul_f32 v[32:33], v[242:243], v[32:33] op_sel_hi:[0,1]
	v_pk_mul_f32 v[34:35], v[242:243], v[34:35] op_sel_hi:[0,1]
	v_max_f32_e32 v36, 0, v36
	v_max_f32_e32 v37, 0, v37
	v_max_f32_e32 v38, 0, v38
	v_max_f32_e32 v39, 0, v39
	v_max_f32_e32 v32, 0, v32
	v_max_f32_e32 v33, 0, v33
	v_max_f32_e32 v34, 0, v34
	v_max_f32_e32 v35, 0, v35
	v_pk_mul_f32 v[36:37], v[36:37], v[36:37]
	v_pk_mul_f32 v[38:39], v[38:39], v[38:39]
	v_pk_mul_f32 v[32:33], v[32:33], v[32:33]
	v_pk_mul_f32 v[34:35], v[34:35], v[34:35]
	v_cvt_pk_bf16_f32 v182, v36, v37
	v_cvt_pk_bf16_f32 v183, v38, v39
	v_cvt_pk_bf16_f32 v184, v32, v33
	v_cvt_pk_bf16_f32 v185, v34, v35
	global_store_dwordx4 v[152:153], v[182:185], off offset:256
	v_add_co_u32_e32 v152, vcc, 0x50a000, v150
	s_nop 1
	v_addc_co_u32_e32 v153, vcc, 0, v151, vcc
	v_cvt_f32_i32_e32 v28, v28
	v_cvt_f32_i32_e32 v29, v29
	v_cvt_f32_i32_e32 v30, v30
	v_cvt_f32_i32_e32 v31, v31
	v_cvt_f32_i32_e32 v24, v24
	v_cvt_f32_i32_e32 v25, v25
	v_cvt_f32_i32_e32 v26, v26
	v_cvt_f32_i32_e32 v27, v27
	v_pk_mul_f32 v[28:29], v[244:245], v[28:29] op_sel_hi:[0,1]
	v_pk_mul_f32 v[30:31], v[244:245], v[30:31] op_sel_hi:[0,1]
	v_pk_mul_f32 v[24:25], v[244:245], v[24:25] op_sel_hi:[0,1]
	v_pk_mul_f32 v[26:27], v[244:245], v[26:27] op_sel_hi:[0,1]
	v_max_f32_e32 v28, 0, v28
	v_max_f32_e32 v29, 0, v29
	v_max_f32_e32 v30, 0, v30
	v_max_f32_e32 v31, 0, v31
	v_max_f32_e32 v24, 0, v24
	v_max_f32_e32 v25, 0, v25
	v_max_f32_e32 v26, 0, v26
	v_max_f32_e32 v27, 0, v27
	v_pk_mul_f32 v[28:29], v[28:29], v[28:29]
	v_pk_mul_f32 v[30:31], v[30:31], v[30:31]
	v_pk_mul_f32 v[24:25], v[24:25], v[24:25]
	v_pk_mul_f32 v[26:27], v[26:27], v[26:27]
	v_cvt_pk_bf16_f32 v186, v28, v29
	v_cvt_pk_bf16_f32 v187, v30, v31
	v_cvt_pk_bf16_f32 v188, v24, v25
	v_cvt_pk_bf16_f32 v189, v26, v27
	global_store_dwordx4 v[152:153], v[186:189], off
	v_cvt_f32_i32_e32 v20, v20
	v_cvt_f32_i32_e32 v21, v21
	v_cvt_f32_i32_e32 v22, v22
	v_cvt_f32_i32_e32 v23, v23
	v_cvt_f32_i32_e32 v16, v16
	v_cvt_f32_i32_e32 v17, v17
	v_cvt_f32_i32_e32 v18, v18
	v_cvt_f32_i32_e32 v19, v19
	v_pk_mul_f32 v[20:21], v[244:245], v[20:21] op_sel_hi:[0,1]
	v_pk_mul_f32 v[22:23], v[244:245], v[22:23] op_sel_hi:[0,1]
	v_pk_mul_f32 v[16:17], v[244:245], v[16:17] op_sel_hi:[0,1]
	v_pk_mul_f32 v[18:19], v[244:245], v[18:19] op_sel_hi:[0,1]
	v_max_f32_e32 v20, 0, v20
	v_max_f32_e32 v21, 0, v21
	v_max_f32_e32 v22, 0, v22
	v_max_f32_e32 v23, 0, v23
	v_max_f32_e32 v16, 0, v16
	v_max_f32_e32 v17, 0, v17
	v_max_f32_e32 v18, 0, v18
	v_max_f32_e32 v19, 0, v19
	v_pk_mul_f32 v[20:21], v[20:21], v[20:21]
	v_pk_mul_f32 v[22:23], v[22:23], v[22:23]
	v_pk_mul_f32 v[16:17], v[16:17], v[16:17]
	v_pk_mul_f32 v[18:19], v[18:19], v[18:19]
	v_cvt_pk_bf16_f32 v190, v20, v21
	v_cvt_pk_bf16_f32 v191, v22, v23
	v_cvt_pk_bf16_f32 v192, v16, v17
	v_cvt_pk_bf16_f32 v193, v18, v19
	global_store_dwordx4 v[152:153], v[190:193], off offset:256
	v_add_co_u32_e32 v152, vcc, 0x58b000, v150
	s_nop 1
	v_addc_co_u32_e32 v153, vcc, 0, v151, vcc
	v_cvt_f32_i32_e32 v12, v12
	v_cvt_f32_i32_e32 v13, v13
	v_cvt_f32_i32_e32 v14, v14
	v_cvt_f32_i32_e32 v15, v15
	v_cvt_f32_i32_e32 v8, v8
	v_cvt_f32_i32_e32 v9, v9
	v_cvt_f32_i32_e32 v10, v10
	v_cvt_f32_i32_e32 v11, v11
	v_pk_mul_f32 v[12:13], v[246:247], v[12:13] op_sel_hi:[0,1]
	v_pk_mul_f32 v[14:15], v[246:247], v[14:15] op_sel_hi:[0,1]
	v_pk_mul_f32 v[8:9], v[246:247], v[8:9] op_sel_hi:[0,1]
	v_pk_mul_f32 v[10:11], v[246:247], v[10:11] op_sel_hi:[0,1]
	v_max_f32_e32 v12, 0, v12
	v_max_f32_e32 v13, 0, v13
	v_max_f32_e32 v14, 0, v14
	v_max_f32_e32 v15, 0, v15
	v_max_f32_e32 v8, 0, v8
	v_max_f32_e32 v9, 0, v9
	v_max_f32_e32 v10, 0, v10
	v_max_f32_e32 v11, 0, v11
	v_pk_mul_f32 v[12:13], v[12:13], v[12:13]
	v_pk_mul_f32 v[14:15], v[14:15], v[14:15]
	v_pk_mul_f32 v[8:9], v[8:9], v[8:9]
	v_pk_mul_f32 v[10:11], v[10:11], v[10:11]
	v_cvt_pk_bf16_f32 v194, v12, v13
	v_cvt_pk_bf16_f32 v195, v14, v15
	v_cvt_pk_bf16_f32 v196, v8, v9
	v_cvt_pk_bf16_f32 v197, v10, v11
	global_store_dwordx4 v[152:153], v[194:197], off
	v_cvt_f32_i32_e32 v4, v4
	v_cvt_f32_i32_e32 v5, v5
	v_cvt_f32_i32_e32 v6, v6
	v_cvt_f32_i32_e32 v7, v7
	v_cvt_f32_i32_e32 v0, v0
	v_cvt_f32_i32_e32 v1, v1
	v_cvt_f32_i32_e32 v2, v2
	v_cvt_f32_i32_e32 v3, v3
	v_pk_mul_f32 v[4:5], v[246:247], v[4:5] op_sel_hi:[0,1]
	v_pk_mul_f32 v[6:7], v[246:247], v[6:7] op_sel_hi:[0,1]
	v_pk_mul_f32 v[0:1], v[246:247], v[0:1] op_sel_hi:[0,1]
	v_pk_mul_f32 v[2:3], v[246:247], v[2:3] op_sel_hi:[0,1]
	v_max_f32_e32 v4, 0, v4
	v_max_f32_e32 v5, 0, v5
	v_max_f32_e32 v6, 0, v6
	v_max_f32_e32 v7, 0, v7
	v_max_f32_e32 v0, 0, v0
	v_max_f32_e32 v1, 0, v1
	v_max_f32_e32 v2, 0, v2
	v_max_f32_e32 v3, 0, v3
	v_pk_mul_f32 v[4:5], v[4:5], v[4:5]
	v_pk_mul_f32 v[6:7], v[6:7], v[6:7]
	v_pk_mul_f32 v[0:1], v[0:1], v[0:1]
	v_pk_mul_f32 v[2:3], v[2:3], v[2:3]
	v_cvt_pk_bf16_f32 v198, v4, v5
	v_cvt_pk_bf16_f32 v199, v6, v7
	v_cvt_pk_bf16_f32 v200, v0, v1
	v_cvt_pk_bf16_f32 v201, v2, v3
	global_store_dwordx4 v[152:153], v[198:201], off offset:256
	s_andn2_b64 vcc, exec, s[2:3]
	s_mov_b64 s[0:1], -1
	s_cbranch_vccnz .LBB0_542
	s_branch .Ljoin_p5

.LBB0_622:
	s_andn2_b64 vcc, exec, s[0:1]
	s_cbranch_vccnz .LBB0_658
	s_waitcnt lgkmcnt(0)
	s_add_u32 s33, s2, 0x46200000
	s_addc_u32 s38, s3, 0
	s_add_u32 s39, s2, 0x1ea00000
	v_mbcnt_lo_u32_b32 v0, s6, 0
	s_addc_u32 s40, s3, 0
	v_mbcnt_hi_u32_b32 v10, s6, v0
	s_lshl_b32 s41, s81, 10
	v_lshl_add_u32 v0, v10, 4, s41
	v_ashrrev_i32_e32 v1, 31, v0
	v_lshrrev_b32_e32 v1, 22, v1
	v_add_u32_e32 v1, v0, v1
	v_ashrrev_i32_e32 v8, 10, v1
	v_mul_i32_i24_e32 v1, 0x400, v8
	v_sub_u32_e32 v1, v0, v1
	v_lshrrev_b32_e32 v2, 4, v1
	v_bitop3_b32 v1, v2, v1, 32 bitop3:0x6c
	v_ashrrev_i32_e32 v3, 31, v1
	v_lshrrev_b32_e32 v3, 26, v3
	v_add_u32_e32 v3, v1, v3
	v_lshlrev_b32_e32 v2, 3, v8
	v_ashrrev_i32_e32 v9, 6, v3
	v_and_b32_e32 v3, 0xc0, v3
	v_and_b32_e32 v2, -16, v2
	v_sub_u32_e32 v1, v1, v3
	v_mov_b32_e32 v3, 1
	v_add_u32_e32 v2, v9, v2
	v_ashrrev_i16_sdwa v1, v3, sext(v1) dst_sel:DWORD dst_unused:UNUSED_PAD src0_sel:DWORD src1_sel:BYTE_0
	v_lshlrev_b32_e32 v4, 5, v8
	v_bfe_i32 v11, v1, 0, 16
	v_lshlrev_b32_e32 v1, 1, v2
	v_lshrrev_b32_e32 v5, 2, v2
	v_and_b32_e32 v6, 3, v9
	s_mov_b32 s0, 0x1ffe0
	v_and_b32_e32 v4, 32, v4
	v_and_b32_e32 v1, 24, v1
	v_and_b32_e32 v5, 4, v5
	v_and_or_b32 v6, v2, s0, v6
	v_or3_b32 v1, v6, v5, v1
	v_add_lshl_u32 v4, v4, v11, 1
	v_add_u32_e32 v0, 0x2000, v0
	v_lshl_add_u32 v154, v1, 15, v4
	v_ashrrev_i32_e32 v1, 31, v0
	v_lshrrev_b32_e32 v1, 22, v1
	v_add_u32_e32 v1, v0, v1
	v_ashrrev_i32_e32 v12, 10, v1
	v_mul_i32_i24_e32 v1, 0x400, v12
	v_sub_u32_e32 v0, v0, v1
	v_lshrrev_b32_e32 v1, 4, v0
	v_bitop3_b32 v0, v1, v0, 32 bitop3:0x6c
	s_mov_b32 s96, 0x8100
	v_mad_u32_u24 v152, v2, s96, v4
	v_ashrrev_i32_e32 v2, 31, v0
	v_lshrrev_b32_e32 v2, 26, v2
	v_add_u32_e32 v2, v0, v2
	v_ashrrev_i32_e32 v13, 6, v2
	v_and_b32_e32 v2, 0xffc0, v2
	v_sub_u32_e32 v0, v0, v2
	v_lshrrev_b16_e32 v2, 7, v0
	v_lshlrev_b32_e32 v1, 3, v12
	v_and_b32_e32 v2, 1, v2
	v_and_b32_e32 v1, -16, v1
	v_add_u16_e32 v0, v0, v2
	v_add_u32_e32 v1, v13, v1
	v_ashrrev_i16_sdwa v0, v3, sext(v0) dst_sel:DWORD dst_unused:UNUSED_PAD src0_sel:DWORD src1_sel:BYTE_0
	v_and_b32_e32 v3, 3, v13
	s_ashr_i32 s27, s26, 31
	s_ashr_i32 s29, s28, 31
	v_and_or_b32 v3, v1, s0, v3
	s_lshr_b32 s4, s92, 8
	s_mul_i32 s0, s26, 0x810000
	s_mov_b32 s1, 0
	s_lshl_b64 s[6:7], s[28:29], 23
	s_add_u32 s30, s39, s6
	v_lshlrev_b32_e32 v4, 5, v12
	v_bfe_i32 v14, v0, 0, 16
	v_lshlrev_b32_e32 v0, 1, v1
	v_lshrrev_b32_e32 v2, 2, v1
	s_addc_u32 s31, s40, s7
	s_add_i32 s29, s41, 0
	v_and_b32_e32 v4, 32, v4
	v_and_b32_e32 v0, 24, v0
	v_and_b32_e32 v2, 4, v2
	s_add_i32 m0, s29, 0x10000
	v_or3_b32 v0, v3, v2, v0
	v_add_lshl_u32 v2, v4, v14, 1
	global_load_lds_dwordx4 v154, s[30:31]
	s_add_i32 m0, s29, 0x12000
	v_lshl_add_u32 v158, v0, 15, v2
	s_add_u32 s6, s30, 0x400000
	global_load_lds_dwordx4 v158, s[30:31]
	s_addc_u32 s7, s31, 0
	s_add_i32 m0, s29, 0x14000
	s_mov_b32 s96, 0x8100
	v_mad_u32_u24 v156, v1, s96, v2
	global_load_lds_dwordx4 v154, s[6:7]
	s_add_i32 m0, s29, 0x16000
	s_add_u32 s34, s33, s0
	s_addc_u32 s35, s38, s1
	s_add_i32 s42, s29, 0x2000
	global_load_lds_dwordx4 v158, s[6:7]
	s_mov_b32 m0, s29
	s_add_u32 s0, s34, 0x408000
	global_load_lds_dwordx4 v152, s[34:35]
	s_mov_b32 m0, s42
	s_addc_u32 s1, s35, 0
	s_add_i32 s43, s29, 0x4000
	global_load_lds_dwordx4 v156, s[34:35]
	s_mov_b32 m0, s43
	s_add_i32 s44, s29, 0x6000
	global_load_lds_dwordx4 v152, s[0:1]
	s_mov_b32 m0, s44
	v_mov_b32_e32 v155, 0
	global_load_lds_dwordx4 v156, s[0:1]
	v_mov_b32_e32 v159, v155
	v_mov_b32_e32 v153, v155
	v_mov_b32_e32 v157, v155
	s_cmp_eq_u32 s4, 1
	s_mov_b32 s45, 0
	v_lshl_add_u64 v[6:7], s[30:31], 0, v[154:155]
	v_lshl_add_u64 v[4:5], s[30:31], 0, v[158:159]
	v_lshl_add_u64 v[0:1], s[34:35], 0, v[152:153]
	s_cselect_b64 s[0:1], -1, 0
	s_cmp_lg_u32 s4, 1
	v_lshl_add_u64 v[2:3], s[34:35], 0, v[156:157]
	s_cbranch_scc1 .LBB0_625
	s_barrier
.LBB0_625:
	s_add_u32 s6, s2, 0x2ea00000
	s_addc_u32 s7, s3, 0
	s_add_u32 s8, s2, 0x40000
	s_addc_u32 s9, s3, 0
	s_add_u32 s10, s2, 0x60000
	s_addc_u32 s11, s3, 0
	s_add_u32 s12, s2, 0x38400000
	s_addc_u32 s13, s3, 0
	s_lshl_b32 s2, s81, 5
	s_mov_b64 s[14:15], 0x80
	s_and_b32 s18, s2, 0x60
	s_add_i32 m0, s29, 0x18000
	v_lshl_add_u64 v[6:7], v[6:7], 0, s[14:15]
	s_lshl_b32 s5, s4, 13
	s_lshr_b32 s16, s18, 3
	s_waitcnt vmcnt(2)
	s_barrier
	global_load_lds_dwordx4 v[6:7], off
	v_lshl_add_u64 v[4:5], v[4:5], 0, s[14:15]
	s_add_i32 m0, s29, 0x1a000
	s_add_i32 s46, s29, 0x8000
	s_add_i32 s47, s29, 0xa000
	global_load_lds_dwordx4 v[4:5], off
	v_lshl_add_u64 v[0:1], v[0:1], 0, s[14:15]
	s_mov_b32 m0, s46
	s_add_u32 s2, s30, 0x400080
	global_load_lds_dwordx4 v[0:1], off
	v_lshl_add_u64 v[0:1], v[2:3], 0, s[14:15]
	s_mov_b32 m0, s47
	s_addc_u32 s3, s31, 0
	global_load_lds_dwordx4 v[0:1], off
	s_add_i32 m0, s29, 0x1c000
	v_lshl_add_u64 v[0:1], s[2:3], 0, v[154:155]
	global_load_lds_dwordx4 v[0:1], off
	v_lshl_add_u64 v[0:1], s[2:3], 0, v[158:159]
	s_add_i32 m0, s29, 0x1e000
	v_lshrrev_b32_e32 v2, 6, v10
	global_load_lds_dwordx4 v[0:1], off
	v_and_b32_e32 v0, 15, v10
	v_lshlrev_b32_e32 v5, 2, v10
	v_lshl_or_b32 v190, s4, 6, v0
	v_and_b32_e32 v3, 48, v10
	v_lshlrev_b32_e32 v4, 10, v2
	v_lshlrev_b32_e32 v0, 6, v0
	v_and_b32_e32 v5, 32, v5
	v_or_b32_e32 v2, s16, v2
	v_bitop3_b32 v6, v0, v5, v3 bitop3:0x36
	v_or_b32_e32 v0, v0, v3
	v_lshlrev_b32_e32 v2, 10, v2
	v_lshrrev_b32_e32 v1, 1, v10
	v_bitop3_b32 v191, v0, v2, v5 bitop3:0xde
	v_lshlrev_b32_e32 v0, 18, v12
	v_and_b32_e32 v1, 56, v1
	v_and_b32_e32 v0, 0xfff80000, v0
	v_add_u32_e32 v192, s18, v1
	v_lshl_add_u32 v0, v13, 15, v0
	v_and_b32_e32 v1, 1, v12
	v_lshl_or_b32 v0, v1, 6, v0
	v_mov_b32_e32 v160, v156
	v_lshlrev_b32_e32 v0, 18, v8
	v_and_b32_e32 v0, 0xfff80000, v0
	v_lshl_add_u32 v0, v9, 15, v0
	v_and_b32_e32 v1, 1, v8
	s_waitcnt vmcnt(6)
	s_cmpk_lt_u32 s92, 0x100
	v_lshl_or_b32 v0, v1, 6, v0
	v_or3_b32 v4, v4, s5, v6
	s_cselect_b64 s[16:17], -1, 0
	v_mov_b32_e32 v162, v152
	s_add_i32 s50, 0, 0x10000
	s_add_i32 s51, 0, 0x14000
	v_mbcnt_lo_u32_b32 v0, -1, 0
	v_cmp_gt_u32_e64 s[2:3], 16, v10
	s_ashr_i32 s48, s77, 31
	s_ashr_i32 s49, s87, 31
	v_mov_b32_e32 v161, v155
	v_mov_b32_e32 v163, v155
	v_mov_b64_e32 v[164:165], 0x400
	v_mov_b64_e32 v[166:167], 0x3ff
	v_add_u32_e32 v193, s50, v191
	v_add_u32_e32 v194, s51, v191
	v_add_u32_e32 v195, 0, v4
	v_mov_b32_e32 v196, 0x358637bd
	s_mov_b32 s52, 0xc2fe0000
	s_mov_b32 s53, 0x40c0c00
	v_mbcnt_hi_u32_b32 v197, -1, v0
	s_mov_b32 s54, 0x49800000
	v_mov_b32_e32 v198, 0x42fe0000
	s_barrier
	s_branch .LBB0_628

.LBB0_634:
	s_ashr_i32 s21, s20, 31
	s_mul_i32 s22, s20, 0x810000
	s_mov_b32 s23, 0
	s_add_u32 s22, s33, s22
	s_addc_u32 s23, s38, s23
	s_and_b64 s[24:25], s[4:5], exec
	s_cselect_b32 s21, s23, s35
	s_cselect_b32 s27, s22, s34
	s_ashr_i32 s19, s18, 31
	s_lshl_b64 s[24:25], s[18:19], 23
	s_add_u32 s24, s39, s24
	s_addc_u32 s25, s40, s25
	s_and_b64 s[36:37], s[4:5], exec
	s_cselect_b32 s19, s25, s31
	s_cselect_b32 s55, s24, s30
	s_add_u32 s56, s30, 0x100
	s_addc_u32 s57, s31, 0
	s_add_u32 s30, s34, 0x408080
	v_mov_b32_e32 v0, 0
	s_addc_u32 s31, s35, 0
	s_mov_b32 s58, -2
	s_waitcnt lgkmcnt(0)
	v_mov_b32_e32 v1, v0
	v_mov_b32_e32 v2, v0
	v_mov_b32_e32 v3, v0
	v_mov_b32_e32 v4, v0
	v_mov_b32_e32 v5, v0
	v_mov_b32_e32 v6, v0
	v_mov_b32_e32 v7, v0
	v_mov_b32_e32 v16, v0
	v_mov_b32_e32 v17, v0
	v_mov_b32_e32 v18, v0
	v_mov_b32_e32 v19, v0
	v_mov_b32_e32 v20, v0
	v_mov_b32_e32 v21, v0
	v_mov_b32_e32 v22, v0
	v_mov_b32_e32 v23, v0
	v_mov_b32_e32 v32, v0
	v_mov_b32_e32 v33, v0
	v_mov_b32_e32 v34, v0
	v_mov_b32_e32 v35, v0
	v_mov_b32_e32 v36, v0
	v_mov_b32_e32 v37, v0
	v_mov_b32_e32 v38, v0
	v_mov_b32_e32 v39, v0
	v_mov_b32_e32 v48, v0
	v_mov_b32_e32 v49, v0
	v_mov_b32_e32 v50, v0
	v_mov_b32_e32 v51, v0
	v_mov_b32_e32 v52, v0
	v_mov_b32_e32 v53, v0
	v_mov_b32_e32 v54, v0
	v_mov_b32_e32 v55, v0
	v_mov_b32_e32 v8, v0
	v_mov_b32_e32 v9, v0
	v_mov_b32_e32 v10, v0
	v_mov_b32_e32 v11, v0
	v_mov_b32_e32 v12, v0
	v_mov_b32_e32 v13, v0
	v_mov_b32_e32 v14, v0
	v_mov_b32_e32 v15, v0
	v_mov_b32_e32 v24, v0
	v_mov_b32_e32 v25, v0
	v_mov_b32_e32 v26, v0
	v_mov_b32_e32 v27, v0
	v_mov_b32_e32 v28, v0
	v_mov_b32_e32 v29, v0
	v_mov_b32_e32 v30, v0
	v_mov_b32_e32 v31, v0
	v_mov_b32_e32 v40, v0
	v_mov_b32_e32 v41, v0
	v_mov_b32_e32 v42, v0
	v_mov_b32_e32 v43, v0
	v_mov_b32_e32 v44, v0
	v_mov_b32_e32 v45, v0
	v_mov_b32_e32 v46, v0
	v_mov_b32_e32 v47, v0
	v_mov_b32_e32 v56, v0
	v_mov_b32_e32 v57, v0
	v_mov_b32_e32 v58, v0
	v_mov_b32_e32 v59, v0
	v_mov_b32_e32 v60, v0
	v_mov_b32_e32 v61, v0
	v_mov_b32_e32 v62, v0
	v_mov_b32_e32 v63, v0
	v_mov_b32_e32 v64, v0
	v_mov_b32_e32 v65, v0
	v_mov_b32_e32 v66, v0
	v_mov_b32_e32 v67, v0
	v_mov_b32_e32 v68, v0
	v_mov_b32_e32 v69, v0
	v_mov_b32_e32 v70, v0
	v_mov_b32_e32 v71, v0
	v_mov_b32_e32 v80, v0
	v_mov_b32_e32 v81, v0
	v_mov_b32_e32 v82, v0
	v_mov_b32_e32 v83, v0
	v_mov_b32_e32 v84, v0
	v_mov_b32_e32 v85, v0
	v_mov_b32_e32 v86, v0
	v_mov_b32_e32 v87, v0
	v_mov_b32_e32 v96, v0
	v_mov_b32_e32 v97, v0
	v_mov_b32_e32 v98, v0
	v_mov_b32_e32 v99, v0
	v_mov_b32_e32 v100, v0
	v_mov_b32_e32 v101, v0
	v_mov_b32_e32 v102, v0
	v_mov_b32_e32 v103, v0
	v_mov_b32_e32 v116, v0
	v_mov_b32_e32 v117, v0
	v_mov_b32_e32 v118, v0
	v_mov_b32_e32 v119, v0
	v_mov_b32_e32 v120, v0
	v_mov_b32_e32 v121, v0
	v_mov_b32_e32 v122, v0
	v_mov_b32_e32 v123, v0
	v_mov_b32_e32 v72, v0
	v_mov_b32_e32 v73, v0
	v_mov_b32_e32 v74, v0
	v_mov_b32_e32 v75, v0
	v_mov_b32_e32 v76, v0
	v_mov_b32_e32 v77, v0
	v_mov_b32_e32 v78, v0
	v_mov_b32_e32 v79, v0
	v_mov_b32_e32 v88, v0
	v_mov_b32_e32 v89, v0
	v_mov_b32_e32 v90, v0
	v_mov_b32_e32 v91, v0
	v_mov_b32_e32 v92, v0
	v_mov_b32_e32 v93, v0
	v_mov_b32_e32 v94, v0
	v_mov_b32_e32 v95, v0
	v_mov_b32_e32 v104, v0
	v_mov_b32_e32 v105, v0
	v_mov_b32_e32 v106, v0
	v_mov_b32_e32 v107, v0
	v_mov_b32_e32 v108, v0
	v_mov_b32_e32 v109, v0
	v_mov_b32_e32 v110, v0
	v_mov_b32_e32 v111, v0
	v_mov_b32_e32 v128, v0
	v_mov_b32_e32 v129, v0
	v_mov_b32_e32 v130, v0
	v_mov_b32_e32 v131, v0
	v_mov_b32_e32 v132, v0
	v_mov_b32_e32 v133, v0
	v_mov_b32_e32 v134, v0
	v_mov_b32_e32 v135, v0
.LBB0_635:
	ds_read_b128 v[112:115], v193
	ds_read_b128 v[124:127], v193 offset:1024
	ds_read_b128 v[136:139], v193 offset:2048
	ds_read_b128 v[140:143], v193 offset:3072
	ds_read_b128 v[144:147], v194
	ds_read_b128 v[148:151], v194 offset:1024
	ds_read_b128 v[168:171], v194 offset:2048
	ds_read_b128 v[172:175], v194 offset:3072
	s_add_u32 s34, s30, 0xffbf8080
	s_addc_u32 s35, s31, -1
	s_cmpk_eq_i32 s58, 0xfc
	s_cselect_b32 s37, s21, s35
	s_cselect_b32 s36, s27, s34
	s_cselect_b32 s35, s19, s57
	s_cselect_b32 s34, s55, s56
	v_lshl_add_u64 v[188:189], s[30:31], 0, v[162:163]
	s_add_i32 m0, s29, 0xc000
	ds_read_b128 v[176:179], v195
	ds_read_b128 v[180:183], v195 offset:1024
	ds_read_b128 v[184:187], v195 offset:2048
	ds_read_b128 v[200:203], v195 offset:3072
	ds_read_b128 v[204:207], v195 offset:4096
	ds_read_b128 v[208:211], v195 offset:5120
	ds_read_b128 v[212:215], v195 offset:6144
	ds_read_b128 v[216:219], v195 offset:7168
	global_load_lds_dwordx4 v[188:189], off
	v_lshl_add_u64 v[188:189], s[30:31], 0, v[160:161]
	s_add_i32 m0, s29, 0xe000
	s_nop 0
	global_load_lds_dwordx4 v[188:189], off
	s_waitcnt vmcnt(8)
	s_waitcnt lgkmcnt(0)
	s_barrier
	s_setprio 1
	s_waitcnt lgkmcnt(0)
	v_mfma_f32_16x16x32_bf16 v[132:135], v[112:115], v[176:179], v[132:135]
	v_mfma_f32_16x16x32_bf16 v[128:131], v[136:139], v[176:179], v[128:131]
	v_mfma_f32_16x16x32_bf16 v[108:111], v[112:115], v[184:187], v[108:111]
	v_mfma_f32_16x16x32_bf16 v[104:107], v[136:139], v[184:187], v[104:107]
	v_mfma_f32_16x16x32_bf16 v[92:95], v[112:115], v[204:207], v[92:95]
	v_mfma_f32_16x16x32_bf16 v[88:91], v[136:139], v[204:207], v[88:91]
	v_mfma_f32_16x16x32_bf16 v[76:79], v[112:115], v[212:215], v[76:79]
	v_mfma_f32_16x16x32_bf16 v[72:75], v[136:139], v[212:215], v[72:75]
	v_mfma_f32_16x16x32_bf16 v[132:135], v[124:127], v[180:183], v[132:135]
	v_mfma_f32_16x16x32_bf16 v[128:131], v[140:143], v[180:183], v[128:131]
	v_mfma_f32_16x16x32_bf16 v[108:111], v[124:127], v[200:203], v[108:111]
	v_mfma_f32_16x16x32_bf16 v[104:107], v[140:143], v[200:203], v[104:107]
	v_mfma_f32_16x16x32_bf16 v[92:95], v[124:127], v[208:211], v[92:95]
	v_mfma_f32_16x16x32_bf16 v[88:91], v[140:143], v[208:211], v[88:91]
	v_mfma_f32_16x16x32_bf16 v[76:79], v[124:127], v[216:219], v[76:79]
	v_mfma_f32_16x16x32_bf16 v[72:75], v[140:143], v[216:219], v[72:75]
	s_setprio 0
	s_setprio 1
	v_mfma_f32_16x16x32_bf16 v[120:123], v[144:147], v[176:179], v[120:123]
	v_mfma_f32_16x16x32_bf16 v[116:119], v[168:171], v[176:179], v[116:119]
	v_mfma_f32_16x16x32_bf16 v[100:103], v[144:147], v[184:187], v[100:103]
	v_mfma_f32_16x16x32_bf16 v[96:99], v[168:171], v[184:187], v[96:99]
	v_mfma_f32_16x16x32_bf16 v[84:87], v[144:147], v[204:207], v[84:87]
	v_mfma_f32_16x16x32_bf16 v[80:83], v[168:171], v[204:207], v[80:83]
	v_mfma_f32_16x16x32_bf16 v[68:71], v[144:147], v[212:215], v[68:71]
	v_mfma_f32_16x16x32_bf16 v[64:67], v[168:171], v[212:215], v[64:67]
	v_mfma_f32_16x16x32_bf16 v[120:123], v[148:151], v[180:183], v[120:123]
	v_mfma_f32_16x16x32_bf16 v[116:119], v[172:175], v[180:183], v[116:119]
	v_mfma_f32_16x16x32_bf16 v[100:103], v[148:151], v[200:203], v[100:103]
	v_mfma_f32_16x16x32_bf16 v[96:99], v[172:175], v[200:203], v[96:99]
	v_mfma_f32_16x16x32_bf16 v[84:87], v[148:151], v[208:211], v[84:87]
	v_mfma_f32_16x16x32_bf16 v[80:83], v[172:175], v[208:211], v[80:83]
	v_mfma_f32_16x16x32_bf16 v[68:71], v[148:151], v[216:219], v[68:71]
	v_mfma_f32_16x16x32_bf16 v[64:67], v[172:175], v[216:219], v[64:67]
	s_setprio 0
	s_barrier
	s_add_i32 s59, s50, s41
	v_lshl_add_u64 v[188:189], s[34:35], 0, v[154:155]
	s_mov_b32 m0, s59
	ds_read_b128 v[176:179], v195 offset:16384
	ds_read_b128 v[180:183], v195 offset:17408
	ds_read_b128 v[184:187], v195 offset:18432
	ds_read_b128 v[200:203], v195 offset:19456
	ds_read_b128 v[204:207], v195 offset:20480
	ds_read_b128 v[208:211], v195 offset:21504
	ds_read_b128 v[212:215], v195 offset:22528
	ds_read_b128 v[216:219], v195 offset:23552
	global_load_lds_dwordx4 v[188:189], off
	s_add_i32 m0, s59, 0x2000
	s_add_u32 s60, s34, 0x400000
	v_lshl_add_u64 v[220:221], s[34:35], 0, v[158:159]
	s_addc_u32 s61, s35, 0
	s_add_i32 s59, s51, s41
	global_load_lds_dwordx4 v[220:221], off
	v_lshl_add_u64 v[222:223], s[60:61], 0, v[154:155]
	s_mov_b32 m0, s59
	v_lshl_add_u64 v[224:225], s[36:37], 0, v[156:157]
	global_load_lds_dwordx4 v[222:223], off
	v_lshl_add_u64 v[222:223], s[60:61], 0, v[158:159]
	s_add_i32 m0, s59, 0x2000
	s_nop 0
	global_load_lds_dwordx4 v[222:223], off
	v_lshl_add_u64 v[222:223], s[36:37], 0, v[152:153]
	s_mov_b32 m0, s29
	s_nop 0
	global_load_lds_dwordx4 v[222:223], off
	s_mov_b32 m0, s42
	s_nop 0
	global_load_lds_dwordx4 v[224:225], off
	s_waitcnt vmcnt(8)
	s_waitcnt lgkmcnt(0)
	s_barrier
	s_setprio 1
	s_waitcnt lgkmcnt(0)
	v_mfma_f32_16x16x32_bf16 v[60:63], v[112:115], v[176:179], v[60:63]
	v_mfma_f32_16x16x32_bf16 v[56:59], v[136:139], v[176:179], v[56:59]
	v_mfma_f32_16x16x32_bf16 v[44:47], v[112:115], v[184:187], v[44:47]
	v_mfma_f32_16x16x32_bf16 v[40:43], v[136:139], v[184:187], v[40:43]
	v_mfma_f32_16x16x32_bf16 v[28:31], v[112:115], v[204:207], v[28:31]
	v_mfma_f32_16x16x32_bf16 v[24:27], v[136:139], v[204:207], v[24:27]
	v_mfma_f32_16x16x32_bf16 v[12:15], v[112:115], v[212:215], v[12:15]
	v_mfma_f32_16x16x32_bf16 v[8:11], v[136:139], v[212:215], v[8:11]
	v_mfma_f32_16x16x32_bf16 v[60:63], v[124:127], v[180:183], v[60:63]
	v_mfma_f32_16x16x32_bf16 v[56:59], v[140:143], v[180:183], v[56:59]
	v_mfma_f32_16x16x32_bf16 v[44:47], v[124:127], v[200:203], v[44:47]
	v_mfma_f32_16x16x32_bf16 v[40:43], v[140:143], v[200:203], v[40:43]
	v_mfma_f32_16x16x32_bf16 v[28:31], v[124:127], v[208:211], v[28:31]
	v_mfma_f32_16x16x32_bf16 v[24:27], v[140:143], v[208:211], v[24:27]
	v_mfma_f32_16x16x32_bf16 v[12:15], v[124:127], v[216:219], v[12:15]
	v_mfma_f32_16x16x32_bf16 v[8:11], v[140:143], v[216:219], v[8:11]
	s_setprio 0
	s_setprio 1
	v_mfma_f32_16x16x32_bf16 v[52:55], v[144:147], v[176:179], v[52:55]
	v_mfma_f32_16x16x32_bf16 v[48:51], v[168:171], v[176:179], v[48:51]
	v_mfma_f32_16x16x32_bf16 v[36:39], v[144:147], v[184:187], v[36:39]
	v_mfma_f32_16x16x32_bf16 v[32:35], v[168:171], v[184:187], v[32:35]
	v_mfma_f32_16x16x32_bf16 v[20:23], v[144:147], v[204:207], v[20:23]
	v_mfma_f32_16x16x32_bf16 v[16:19], v[168:171], v[204:207], v[16:19]
	v_mfma_f32_16x16x32_bf16 v[4:7], v[144:147], v[212:215], v[4:7]
	v_mfma_f32_16x16x32_bf16 v[0:3], v[168:171], v[212:215], v[0:3]
	v_mfma_f32_16x16x32_bf16 v[52:55], v[148:151], v[180:183], v[52:55]
	v_mfma_f32_16x16x32_bf16 v[48:51], v[172:175], v[180:183], v[48:51]
	v_mfma_f32_16x16x32_bf16 v[36:39], v[148:151], v[200:203], v[36:39]
	v_mfma_f32_16x16x32_bf16 v[32:35], v[172:175], v[200:203], v[32:35]
	v_mfma_f32_16x16x32_bf16 v[20:23], v[148:151], v[208:211], v[20:23]
	v_mfma_f32_16x16x32_bf16 v[16:19], v[172:175], v[208:211], v[16:19]
	v_mfma_f32_16x16x32_bf16 v[4:7], v[148:151], v[216:219], v[4:7]
	v_mfma_f32_16x16x32_bf16 v[0:3], v[172:175], v[216:219], v[0:3]
	s_setprio 0
	s_barrier
	s_add_i32 s59, 0, 0x18000
	s_add_i32 s60, 0, 0x1c000
	v_add_u32_e32 v140, s59, v191
	v_add_u32_e32 v172, s60, v191
	ds_read_b128 v[112:115], v140
	ds_read_b128 v[124:127], v140 offset:1024
	ds_read_b128 v[136:139], v140 offset:2048
	ds_read_b128 v[140:143], v140 offset:3072
	ds_read_b128 v[144:147], v172
	ds_read_b128 v[148:151], v172 offset:1024
	ds_read_b128 v[168:171], v172 offset:2048
	ds_read_b128 v[172:175], v172 offset:3072
	s_add_u32 s36, s36, 0x408000
	s_addc_u32 s37, s37, 0
	s_mov_b32 m0, s43
	v_lshl_add_u64 v[226:227], s[36:37], 0, v[152:153]
	ds_read_b128 v[176:179], v195 offset:32768
	ds_read_b128 v[180:183], v195 offset:33792
	ds_read_b128 v[184:187], v195 offset:34816
	ds_read_b128 v[200:203], v195 offset:35840
	ds_read_b128 v[204:207], v195 offset:36864
	ds_read_b128 v[208:211], v195 offset:37888
	ds_read_b128 v[212:215], v195 offset:38912
	ds_read_b128 v[216:219], v195 offset:39936
	global_load_lds_dwordx4 v[226:227], off
	v_lshl_add_u64 v[226:227], s[36:37], 0, v[156:157]
	s_mov_b32 m0, s44
	s_nop 0
	global_load_lds_dwordx4 v[226:227], off
	s_waitcnt vmcnt(8)
	s_waitcnt lgkmcnt(0)
	s_barrier
	s_setprio 1
	s_waitcnt lgkmcnt(0)
	v_mfma_f32_16x16x32_bf16 v[132:135], v[112:115], v[176:179], v[132:135]
	v_mfma_f32_16x16x32_bf16 v[128:131], v[136:139], v[176:179], v[128:131]
	v_mfma_f32_16x16x32_bf16 v[108:111], v[112:115], v[184:187], v[108:111]
	v_mfma_f32_16x16x32_bf16 v[104:107], v[136:139], v[184:187], v[104:107]
	v_mfma_f32_16x16x32_bf16 v[92:95], v[112:115], v[204:207], v[92:95]
	v_mfma_f32_16x16x32_bf16 v[88:91], v[136:139], v[204:207], v[88:91]
	v_mfma_f32_16x16x32_bf16 v[76:79], v[112:115], v[212:215], v[76:79]
	v_mfma_f32_16x16x32_bf16 v[72:75], v[136:139], v[212:215], v[72:75]
	v_mfma_f32_16x16x32_bf16 v[132:135], v[124:127], v[180:183], v[132:135]
	v_mfma_f32_16x16x32_bf16 v[128:131], v[140:143], v[180:183], v[128:131]
	v_mfma_f32_16x16x32_bf16 v[108:111], v[124:127], v[200:203], v[108:111]
	v_mfma_f32_16x16x32_bf16 v[104:107], v[140:143], v[200:203], v[104:107]
	v_mfma_f32_16x16x32_bf16 v[92:95], v[124:127], v[208:211], v[92:95]
	v_mfma_f32_16x16x32_bf16 v[88:91], v[140:143], v[208:211], v[88:91]
	v_mfma_f32_16x16x32_bf16 v[76:79], v[124:127], v[216:219], v[76:79]
	v_mfma_f32_16x16x32_bf16 v[72:75], v[140:143], v[216:219], v[72:75]
	s_setprio 0
	s_setprio 1
	v_mfma_f32_16x16x32_bf16 v[120:123], v[144:147], v[176:179], v[120:123]
	v_mfma_f32_16x16x32_bf16 v[116:119], v[168:171], v[176:179], v[116:119]
	v_mfma_f32_16x16x32_bf16 v[100:103], v[144:147], v[184:187], v[100:103]
	v_mfma_f32_16x16x32_bf16 v[96:99], v[168:171], v[184:187], v[96:99]
	v_mfma_f32_16x16x32_bf16 v[84:87], v[144:147], v[204:207], v[84:87]
	v_mfma_f32_16x16x32_bf16 v[80:83], v[168:171], v[204:207], v[80:83]
	v_mfma_f32_16x16x32_bf16 v[68:71], v[144:147], v[212:215], v[68:71]
	v_mfma_f32_16x16x32_bf16 v[64:67], v[168:171], v[212:215], v[64:67]
	v_mfma_f32_16x16x32_bf16 v[120:123], v[148:151], v[180:183], v[120:123]
	v_mfma_f32_16x16x32_bf16 v[116:119], v[172:175], v[180:183], v[116:119]
	v_mfma_f32_16x16x32_bf16 v[100:103], v[148:151], v[200:203], v[100:103]
	v_mfma_f32_16x16x32_bf16 v[96:99], v[172:175], v[200:203], v[96:99]
	v_mfma_f32_16x16x32_bf16 v[84:87], v[148:151], v[208:211], v[84:87]
	v_mfma_f32_16x16x32_bf16 v[80:83], v[172:175], v[208:211], v[80:83]
	v_mfma_f32_16x16x32_bf16 v[68:71], v[148:151], v[216:219], v[68:71]
	v_mfma_f32_16x16x32_bf16 v[64:67], v[172:175], v[216:219], v[64:67]
	s_setprio 0
	s_barrier
	s_add_i32 s36, s59, s41
	v_lshl_add_u64 v[188:189], v[188:189], 0, s[14:15]
	s_mov_b32 m0, s36
	ds_read_b128 v[176:179], v195 offset:49152
	ds_read_b128 v[180:183], v195 offset:50176
	ds_read_b128 v[184:187], v195 offset:51200
	ds_read_b128 v[200:203], v195 offset:52224
	ds_read_b128 v[204:207], v195 offset:53248
	ds_read_b128 v[208:211], v195 offset:54272
	ds_read_b128 v[212:215], v195 offset:55296
	ds_read_b128 v[216:219], v195 offset:56320
	global_load_lds_dwordx4 v[188:189], off
	s_add_i32 m0, s36, 0x2000
	s_add_u32 s34, s34, 0x400080
	v_lshl_add_u64 v[188:189], v[220:221], 0, s[14:15]
	s_addc_u32 s35, s35, 0
	s_add_i32 s36, s60, s41
	global_load_lds_dwordx4 v[188:189], off
	v_lshl_add_u64 v[188:189], s[34:35], 0, v[154:155]
	s_mov_b32 m0, s36
	s_nop 0
	global_load_lds_dwordx4 v[188:189], off
	v_lshl_add_u64 v[188:189], s[34:35], 0, v[158:159]
	s_add_i32 m0, s36, 0x2000
	s_nop 0
	global_load_lds_dwordx4 v[188:189], off
	v_lshl_add_u64 v[188:189], v[222:223], 0, s[14:15]
	s_mov_b32 m0, s46
	s_nop 0
	global_load_lds_dwordx4 v[188:189], off
	v_lshl_add_u64 v[188:189], v[224:225], 0, s[14:15]
	s_mov_b32 m0, s47
	s_nop 0
	global_load_lds_dwordx4 v[188:189], off
	s_waitcnt vmcnt(8)
	s_waitcnt lgkmcnt(0)
	s_barrier
	s_setprio 1
	s_waitcnt lgkmcnt(0)
	v_mfma_f32_16x16x32_bf16 v[60:63], v[112:115], v[176:179], v[60:63]
	v_mfma_f32_16x16x32_bf16 v[56:59], v[136:139], v[176:179], v[56:59]
	v_mfma_f32_16x16x32_bf16 v[44:47], v[112:115], v[184:187], v[44:47]
	v_mfma_f32_16x16x32_bf16 v[40:43], v[136:139], v[184:187], v[40:43]
	v_mfma_f32_16x16x32_bf16 v[28:31], v[112:115], v[204:207], v[28:31]
	v_mfma_f32_16x16x32_bf16 v[24:27], v[136:139], v[204:207], v[24:27]
	v_mfma_f32_16x16x32_bf16 v[12:15], v[112:115], v[212:215], v[12:15]
	v_mfma_f32_16x16x32_bf16 v[8:11], v[136:139], v[212:215], v[8:11]
	v_mfma_f32_16x16x32_bf16 v[60:63], v[124:127], v[180:183], v[60:63]
	v_mfma_f32_16x16x32_bf16 v[56:59], v[140:143], v[180:183], v[56:59]
	v_mfma_f32_16x16x32_bf16 v[44:47], v[124:127], v[200:203], v[44:47]
	v_mfma_f32_16x16x32_bf16 v[40:43], v[140:143], v[200:203], v[40:43]
	v_mfma_f32_16x16x32_bf16 v[28:31], v[124:127], v[208:211], v[28:31]
	v_mfma_f32_16x16x32_bf16 v[24:27], v[140:143], v[208:211], v[24:27]
	v_mfma_f32_16x16x32_bf16 v[12:15], v[124:127], v[216:219], v[12:15]
	v_mfma_f32_16x16x32_bf16 v[8:11], v[140:143], v[216:219], v[8:11]
	s_setprio 0
	s_setprio 1
	v_mfma_f32_16x16x32_bf16 v[52:55], v[144:147], v[176:179], v[52:55]
	v_mfma_f32_16x16x32_bf16 v[48:51], v[168:171], v[176:179], v[48:51]
	v_mfma_f32_16x16x32_bf16 v[36:39], v[144:147], v[184:187], v[36:39]
	v_mfma_f32_16x16x32_bf16 v[32:35], v[168:171], v[184:187], v[32:35]
	v_mfma_f32_16x16x32_bf16 v[20:23], v[144:147], v[204:207], v[20:23]
	v_mfma_f32_16x16x32_bf16 v[16:19], v[168:171], v[204:207], v[16:19]
	v_mfma_f32_16x16x32_bf16 v[4:7], v[144:147], v[212:215], v[4:7]
	v_mfma_f32_16x16x32_bf16 v[0:3], v[168:171], v[212:215], v[0:3]
	v_mfma_f32_16x16x32_bf16 v[52:55], v[148:151], v[180:183], v[52:55]
	v_mfma_f32_16x16x32_bf16 v[48:51], v[172:175], v[180:183], v[48:51]
	v_mfma_f32_16x16x32_bf16 v[36:39], v[148:151], v[200:203], v[36:39]
	v_mfma_f32_16x16x32_bf16 v[32:35], v[172:175], v[200:203], v[32:35]
	v_mfma_f32_16x16x32_bf16 v[20:23], v[148:151], v[208:211], v[20:23]
	v_mfma_f32_16x16x32_bf16 v[16:19], v[172:175], v[208:211], v[16:19]
	v_mfma_f32_16x16x32_bf16 v[4:7], v[148:151], v[216:219], v[4:7]
	v_mfma_f32_16x16x32_bf16 v[0:3], v[172:175], v[216:219], v[0:3]
	s_setprio 0
	s_barrier
	s_add_i32 s58, s58, 2
	s_add_u32 s56, s56, 0x100
	s_addc_u32 s57, s57, 0
	s_add_u32 s30, s30, 0x100
	s_addc_u32 s31, s31, 0
	s_cmpk_gt_u32 s58, 0xfd
	s_cbranch_scc0 .LBB0_635
	s_and_b64 vcc, exec, s[16:17]
	s_cbranch_vccz .LBB0_638
	s_barrier
.LBB0_638:
	v_lshl_add_u32 v174, s26, 8, v190
	v_lshl_or_b32 v168, s28, 8, v192
	v_ashrrev_i32_e32 v169, 31, v168
	v_ashrrev_i32_e32 v175, 31, v174
	v_lshl_add_u64 v[172:173], v[168:169], 1, s[6:7]
	v_lshlrev_b64 v[112:113], 13, v[174:175]
	v_lshl_add_u64 v[170:171], v[174:175], 3, s[8:9]
	v_lshl_add_u64 v[188:189], v[172:173], 0, v[112:113]
	global_load_dwordx2 v[208:209], v[170:171], off
	global_load_dwordx2 v[232:233], v[170:171], off offset:128
	global_load_dwordx2 v[234:235], v[170:171], off offset:256
	global_load_dwordx2 v[236:237], v[170:171], off offset:384
	global_load_dwordx2 v[238:239], v[170:171], off offset:1024
	global_load_dwordx2 v[240:241], v[170:171], off offset:1152
	global_load_dwordx2 v[242:243], v[170:171], off offset:1280
	global_load_dwordx2 v[244:245], v[170:171], off offset:1408
	global_load_dwordx4 v[200:203], v[188:189], off
	v_or_b32_e32 v184, 16, v174
	v_or_b32_e32 v180, 32, v174
	v_or_b32_e32 v176, 48, v174
	v_ashrrev_i32_e32 v185, 31, v184
	v_ashrrev_i32_e32 v181, 31, v180
	v_ashrrev_i32_e32 v177, 31, v176
	v_lshlrev_b64 v[112:113], 12, v[174:175]
	v_lshlrev_b64 v[114:115], 13, v[184:185]
	v_lshlrev_b64 v[124:125], 13, v[180:181]
	v_lshlrev_b64 v[126:127], 13, v[176:177]
	v_lshl_add_u64 v[112:113], v[112:113], 0, v[168:169]
	v_lshl_add_u64 v[186:187], v[172:173], 0, v[114:115]
	v_lshl_add_u64 v[182:183], v[172:173], 0, v[124:125]
	v_lshl_add_u64 v[178:179], v[172:173], 0, v[126:127]
	v_lshl_add_u64 v[210:211], s[12:13], 0, v[112:113]
	global_load_dwordx4 v[204:207], v[188:189], off offset:256
	global_load_dwordx4 v[148:151], v[186:187], off
	global_load_dwordx4 v[144:147], v[186:187], off offset:256
	global_load_dwordx4 v[140:143], v[182:183], off
	global_load_dwordx4 v[136:139], v[182:183], off offset:256
	global_load_dwordx4 v[124:127], v[178:179], off
	global_load_dwordx4 v[112:115], v[178:179], off offset:256
	s_waitcnt vmcnt(0)
	v_ffbh_u32_e32 v199, v209
	v_min_u32_e32 v199, 32, v199
	v_lshlrev_b64 v[208:209], v199, v[208:209]
	v_min_u32_e32 v208, 1, v208
	v_or_b32_e32 v208, v209, v208
	v_cvt_f32_u32_e32 v208, v208
	v_lshlrev_b32_e32 v212, 16, v200
	v_and_b32_e32 v213, 0xffff0000, v200
	v_lshlrev_b32_e32 v200, 16, v201
	v_and_b32_e32 v201, 0xffff0000, v201
	v_lshlrev_b32_e32 v214, 16, v202
	v_and_b32_e32 v215, 0xffff0000, v202
	v_lshlrev_b32_e32 v202, 16, v203
	v_and_b32_e32 v203, 0xffff0000, v203
	v_pk_add_f32 v[134:135], v[134:135], v[200:201]
	v_pk_add_f32 v[132:133], v[132:133], v[212:213]
	v_pk_add_f32 v[200:201], v[130:131], v[202:203]
	v_pk_add_f32 v[202:203], v[128:129], v[214:215]
	v_sub_u32_e32 v199, 32, v199
	v_cvt_pk_bf16_f32 v128, v132, v133
	v_cvt_pk_bf16_f32 v129, v134, v135
	v_cvt_pk_bf16_f32 v130, v202, v203
	v_cvt_pk_bf16_f32 v131, v200, v201
	global_store_dwordx4 v[188:189], v[128:131], off
	v_mul_f32_e32 v212, v133, v133
	v_mul_f32_e32 v213, v135, v135
	v_ldexp_f32 v128, v208, v199
	v_fmamk_f32 v128, v128, 0x2f800000, v196
	v_rsq_f32_e32 v128, v128
	v_mul_f32_e32 v214, v203, v203
	v_fmac_f32_e32 v212, v132, v132
	v_fmac_f32_e32 v213, v134, v134
	v_fmac_f32_e32 v214, v202, v202
	v_add_f32_e32 v129, v212, v213
	v_mul_f32_e32 v199, 0x41b56db7, v128
	v_add_f32_e32 v130, v214, v129
	v_mul_f32_e32 v128, v199, v132
	v_mul_f32_e32 v129, v199, v133
	v_mul_f32_e32 v131, v199, v134
	v_mul_f32_e32 v132, v199, v135
	v_mul_f32_e32 v134, v199, v203
	v_mul_f32_e32 v133, v199, v202
	v_mul_f32_e32 v135, v199, v200
	v_mul_f32_e32 v202, v199, v201
	v_med3_f32 v128, v128, s52, v198
	v_med3_f32 v129, v129, s52, v198
	v_med3_f32 v132, v132, s52, v198
	v_med3_f32 v134, v134, s52, v198
	v_med3_f32 v131, v131, s52, v198
	v_med3_f32 v133, v133, s52, v198
	v_med3_f32 v135, v135, s52, v198
	v_med3_f32 v202, v202, s52, v198
	v_rndne_f32_e32 v128, v128
	v_rndne_f32_e32 v129, v129
	v_rndne_f32_e32 v132, v132
	v_rndne_f32_e32 v134, v134
	v_rndne_f32_e32 v131, v131
	v_rndne_f32_e32 v133, v133
	v_rndne_f32_e32 v135, v135
	v_rndne_f32_e32 v202, v202
	v_cvt_i32_f32_e32 v128, v128
	v_cvt_i32_f32_e32 v129, v129
	v_cvt_i32_f32_e32 v132, v132
	v_cvt_i32_f32_e32 v134, v134
	v_cvt_i32_f32_sdwa v131, v131 dst_sel:WORD_1 dst_unused:UNUSED_PAD src0_sel:DWORD
	v_cvt_i32_f32_e32 v133, v133
	v_cvt_i32_f32_sdwa v135, v135 dst_sel:WORD_1 dst_unused:UNUSED_PAD src0_sel:DWORD
	v_cvt_i32_f32_e32 v202, v202
	v_lshlrev_b32_e32 v129, 8, v129
	v_perm_b32 v128, v132, v128, s53
	v_lshlrev_b32_e32 v132, 8, v134
	v_and_b32_e32 v131, 0xff0000, v131
	v_and_b32_e32 v134, 0xff0000, v135
	v_perm_b32 v133, v202, v133, s53
	v_and_b32_e32 v129, 0xff00, v129
	v_and_b32_e32 v132, 0xff00, v132
	v_or3_b32 v128, v128, v129, v131
	v_or3_b32 v129, v133, v132, v134
	global_store_dwordx2 v[210:211], v[128:129], off
	v_mul_f32_e32 v128, v201, v201
	v_fmac_f32_e32 v128, v200, v200
	v_add_f32_e32 v200, v128, v130
	v_lshlrev_b32_e32 v128, 16, v204
	v_and_b32_e32 v129, 0xffff0000, v204
	v_lshlrev_b32_e32 v130, 16, v205
	v_and_b32_e32 v131, 0xffff0000, v205
	v_lshlrev_b32_e32 v132, 16, v206
	v_and_b32_e32 v133, 0xffff0000, v206
	v_lshlrev_b32_e32 v134, 16, v207
	v_and_b32_e32 v135, 0xffff0000, v207
	v_pk_add_f32 v[122:123], v[122:123], v[130:131]
	v_pk_add_f32 v[120:121], v[120:121], v[128:129]
	v_pk_add_f32 v[130:131], v[116:117], v[132:133]
	v_cvt_pk_bf16_f32 v116, v120, v121
	v_cvt_pk_bf16_f32 v117, v122, v123
	v_pk_add_f32 v[128:129], v[118:119], v[134:135]
	v_cvt_pk_bf16_f32 v118, v130, v131
	s_nop 0
	v_cvt_pk_bf16_f32 v119, v128, v129
	global_store_dwordx4 v[188:189], v[116:119], off offset:256
	s_nop 1
	v_mul_f32_e32 v117, v199, v121
	v_mul_f32_e32 v116, v199, v120
	v_mul_f32_e32 v118, v199, v122
	v_mul_f32_e32 v119, v199, v123
	v_med3_f32 v117, v117, s52, v198
	v_med3_f32 v116, v116, s52, v198
	v_rndne_f32_e32 v117, v117
	v_med3_f32 v118, v118, s52, v198
	v_med3_f32 v119, v119, s52, v198
	v_rndne_f32_e32 v116, v116
	v_cvt_i32_f32_e32 v117, v117
	v_rndne_f32_e32 v118, v118
	v_rndne_f32_e32 v119, v119
	v_cvt_i32_f32_e32 v116, v116
	v_cvt_i32_f32_sdwa v118, v118 dst_sel:WORD_1 dst_unused:UNUSED_PAD src0_sel:DWORD
	v_cvt_i32_f32_e32 v119, v119
	v_lshlrev_b32_e32 v117, 8, v117
	v_and_b32_e32 v117, 0xff00, v117
	v_and_b32_e32 v118, 0xff0000, v118
	v_perm_b32 v116, v119, v116, s53
	v_or3_b32 v132, v116, v117, v118
	v_mul_f32_e32 v117, v199, v131
	v_med3_f32 v117, v117, s52, v198
	v_rndne_f32_e32 v117, v117
	v_cvt_i32_f32_e32 v117, v117
	v_mul_f32_e32 v116, v199, v130
	v_med3_f32 v116, v116, s52, v198
	v_rndne_f32_e32 v116, v116
	v_mul_f32_e32 v118, v199, v128
	v_cvt_i32_f32_e32 v133, v116
	v_lshlrev_b32_e32 v116, 8, v117
	v_and_b32_e32 v134, 0xff00, v116
	v_med3_f32 v116, v118, s52, v198
	v_rndne_f32_e32 v117, v116
	v_mul_f32_e32 v116, v121, v121
	v_mul_f32_e32 v118, v123, v123
	v_fmac_f32_e32 v116, v120, v120
	v_fmac_f32_e32 v118, v122, v122
	v_add_f32_e32 v116, v116, v118
	v_mul_f32_e32 v118, v131, v131
	v_fmac_f32_e32 v118, v130, v130
	v_add_f32_e32 v116, v118, v116
	v_mul_f32_e32 v118, v129, v129
	v_fmac_f32_e32 v118, v128, v128
	v_add_f32_e32 v116, v118, v116
	v_and_b32_e32 v120, 64, v197
	v_add_f32_e32 v118, v200, v116
	v_xor_b32_e32 v116, 16, v197
	v_add_u32_e32 v120, 64, v120
	v_cmp_lt_i32_e32 vcc, v116, v120
	v_mul_f32_e32 v119, v199, v129
	v_cvt_i32_f32_sdwa v122, v117 dst_sel:WORD_1 dst_unused:UNUSED_PAD src0_sel:DWORD
	v_cndmask_b32_e32 v116, v197, v116, vcc
	v_lshlrev_b32_e32 v116, 2, v116
	ds_bpermute_b32 v121, v116, v118
	v_med3_f32 v117, v119, s52, v198
	v_rndne_f32_e32 v117, v117
	v_cvt_i32_f32_e32 v123, v117
	v_xor_b32_e32 v117, 32, v197
	v_cmp_lt_i32_e32 vcc, v117, v120
	s_waitcnt lgkmcnt(0)
	v_add_f32_e32 v118, v118, v121
	v_and_b32_e32 v120, 0xff0000, v122
	v_cndmask_b32_e32 v117, v197, v117, vcc
	v_lshlrev_b32_e32 v117, 2, v117
	ds_bpermute_b32 v119, v117, v118
	v_perm_b32 v121, v123, v133, s53
	v_or3_b32 v133, v121, v134, v120
	global_store_dwordx2 v[210:211], v[132:133], off offset:128
	s_and_saveexec_b64 s[26:27], s[2:3]
	s_cbranch_execz .LBB0_640
	s_waitcnt lgkmcnt(0)
	v_add_f32_e32 v118, v118, v119
	v_fma_f32 v118, v118, s54, 0.5
	v_trunc_f32_e32 v118, v118
	v_mul_f32_e32 v119, 0x2f800000, v118
	v_floor_f32_e32 v119, v119
	v_fmac_f32_e32 v118, 0xcf800000, v119
	v_cvt_u32_f32_e32 v118, v118
	v_cvt_u32_f32_e32 v119, v119
	v_lshl_add_u64 v[120:121], v[174:175], 3, s[10:11]
	v_mov_b32_e32 v228, v120
	v_mov_b32_e32 v229, v121
	v_mov_b32_e32 v246, v118
	v_mov_b32_e32 v247, v119
.LBB0_640:
	s_or_b64 exec, exec, s[26:27]
	s_waitcnt lgkmcnt(0)
	v_lshl_add_u64 v[118:119], v[184:185], 3, s[8:9]
	v_mov_b32_e32 v118, v232
	v_mov_b32_e32 v119, v233
	v_lshlrev_b32_e32 v122, 16, v148
	v_and_b32_e32 v123, 0xffff0000, v148
	v_lshlrev_b32_e32 v128, 16, v149
	v_and_b32_e32 v129, 0xffff0000, v149
	v_lshlrev_b32_e32 v148, 16, v146
	v_and_b32_e32 v149, 0xffff0000, v146
	v_lshlrev_b32_e32 v130, 16, v150
	v_and_b32_e32 v131, 0xffff0000, v150
	v_lshlrev_b32_e32 v132, 16, v151
	v_and_b32_e32 v133, 0xffff0000, v151
	v_lshlrev_b32_e32 v146, 16, v147
	v_and_b32_e32 v147, 0xffff0000, v147
	v_pk_add_f32 v[110:111], v[110:111], v[128:129]
	v_pk_add_f32 v[108:109], v[108:109], v[122:123]
	v_pk_add_f32 v[128:129], v[96:97], v[148:149]
	v_cvt_pk_bf16_f32 v96, v108, v109
	v_pk_add_f32 v[106:107], v[106:107], v[132:133]
	v_pk_add_f32 v[104:105], v[104:105], v[130:131]
	v_pk_add_f32 v[122:123], v[98:99], v[146:147]
	v_cvt_pk_bf16_f32 v97, v110, v111
	v_cvt_pk_bf16_f32 v98, v104, v105
	v_cvt_pk_bf16_f32 v99, v106, v107
	global_store_dwordx4 v[186:187], v[96:99], off
	v_mul_f32_e32 v130, v109, v109
	v_mul_f32_e32 v131, v111, v111
	v_mul_f32_e32 v132, v105, v105
	v_fmac_f32_e32 v130, v108, v108
	v_fmac_f32_e32 v131, v110, v110
	v_mul_f32_e32 v133, v107, v107
	v_fmac_f32_e32 v132, v104, v104
	v_fmac_f32_e32 v133, v106, v106
	v_lshlrev_b64 v[120:121], 12, v[184:185]
	v_lshlrev_b32_e32 v134, 16, v144
	v_and_b32_e32 v135, 0xffff0000, v144
	v_lshl_add_u64 v[120:121], v[120:121], 0, v[168:169]
	v_lshlrev_b32_e32 v144, 16, v145
	v_and_b32_e32 v145, 0xffff0000, v145
	v_pk_add_f32 v[100:101], v[100:101], v[134:135]
	v_lshl_add_u64 v[120:121], s[12:13], 0, v[120:121]
	v_pk_add_f32 v[102:103], v[102:103], v[144:145]
	v_ffbh_u32_e32 v96, v119
	v_min_u32_e32 v98, 32, v96
	v_lshlrev_b64 v[96:97], v98, v[118:119]
	v_min_u32_e32 v96, 1, v96
	v_or_b32_e32 v96, v97, v96
	v_cvt_f32_u32_e32 v96, v96
	v_sub_u32_e32 v97, 32, v98
	v_ldexp_f32 v96, v96, v97
	v_fmamk_f32 v96, v96, 0x2f800000, v196
	v_rsq_f32_e32 v96, v96
	v_add_f32_e32 v97, v130, v131
	v_add_f32_e32 v97, v132, v97
	v_add_f32_e32 v118, v133, v97
	v_mul_f32_e32 v119, 0x41b56db7, v96
	v_mul_f32_e32 v96, v108, v119
	v_mul_f32_e32 v97, v109, v119
	v_mul_f32_e32 v99, v111, v119
	v_mul_f32_e32 v105, v105, v119
	v_mul_f32_e32 v98, v110, v119
	v_mul_f32_e32 v104, v104, v119
	v_mul_f32_e32 v106, v106, v119
	v_mul_f32_e32 v107, v107, v119
	v_med3_f32 v96, v96, s52, v198
	v_med3_f32 v97, v97, s52, v198
	v_med3_f32 v99, v99, s52, v198
	v_med3_f32 v105, v105, s52, v198
	v_med3_f32 v98, v98, s52, v198
	v_med3_f32 v104, v104, s52, v198
	v_med3_f32 v106, v106, s52, v198
	v_med3_f32 v107, v107, s52, v198
	v_rndne_f32_e32 v96, v96
	v_rndne_f32_e32 v97, v97
	v_rndne_f32_e32 v99, v99
	v_rndne_f32_e32 v105, v105
	v_rndne_f32_e32 v98, v98
	v_rndne_f32_e32 v104, v104
	v_rndne_f32_e32 v106, v106
	v_rndne_f32_e32 v107, v107
	v_cvt_i32_f32_e32 v96, v96
	v_cvt_i32_f32_e32 v97, v97
	v_cvt_i32_f32_e32 v99, v99
	v_cvt_i32_f32_e32 v105, v105
	v_cvt_i32_f32_sdwa v98, v98 dst_sel:WORD_1 dst_unused:UNUSED_PAD src0_sel:DWORD
	v_cvt_i32_f32_e32 v104, v104
	v_cvt_i32_f32_sdwa v106, v106 dst_sel:WORD_1 dst_unused:UNUSED_PAD src0_sel:DWORD
	v_cvt_i32_f32_e32 v107, v107
	v_lshlrev_b32_e32 v97, 8, v97
	v_perm_b32 v96, v99, v96, s53
	v_lshlrev_b32_e32 v99, 8, v105
	v_and_b32_e32 v98, 0xff0000, v98
	v_and_b32_e32 v105, 0xff0000, v106
	v_perm_b32 v104, v107, v104, s53
	v_and_b32_e32 v97, 0xff00, v97
	v_and_b32_e32 v99, 0xff00, v99
	v_or3_b32 v96, v96, v97, v98
	v_or3_b32 v97, v104, v99, v105
	v_mul_f32_e32 v109, v101, v119
	global_store_dwordx2 v[120:121], v[96:97], off
	v_cvt_pk_bf16_f32 v96, v100, v101
	v_cvt_pk_bf16_f32 v97, v102, v103
	v_mul_f32_e32 v108, v100, v119
	v_mul_f32_e32 v110, v102, v119
	v_mul_f32_e32 v111, v103, v119
	v_cvt_pk_bf16_f32 v98, v128, v129
	v_cvt_pk_bf16_f32 v99, v122, v123
	global_store_dwordx4 v[186:187], v[96:99], off offset:256
	v_med3_f32 v108, v108, s52, v198
	v_mul_f32_e32 v104, v123, v119
	v_med3_f32 v97, v109, s52, v198
	v_rndne_f32_e32 v97, v97
	v_med3_f32 v98, v110, s52, v198
	v_med3_f32 v99, v111, s52, v198
	v_rndne_f32_e32 v96, v108
	v_cvt_i32_f32_e32 v97, v97
	v_rndne_f32_e32 v98, v98
	v_rndne_f32_e32 v99, v99
	v_cvt_i32_f32_e32 v96, v96
	v_cvt_i32_f32_sdwa v98, v98 dst_sel:WORD_1 dst_unused:UNUSED_PAD src0_sel:DWORD
	v_cvt_i32_f32_e32 v99, v99
	v_lshlrev_b32_e32 v97, 8, v97
	v_and_b32_e32 v97, 0xff00, v97
	v_and_b32_e32 v98, 0xff0000, v98
	v_perm_b32 v96, v99, v96, s53
	v_or3_b32 v98, v96, v97, v98
	v_mul_f32_e32 v97, v129, v119
	v_med3_f32 v97, v97, s52, v198
	v_rndne_f32_e32 v97, v97
	v_cvt_i32_f32_e32 v97, v97
	v_mul_f32_e32 v96, v128, v119
	v_med3_f32 v96, v96, s52, v198
	v_rndne_f32_e32 v96, v96
	v_mul_f32_e32 v99, v122, v119
	v_cvt_i32_f32_e32 v105, v96
	v_lshlrev_b32_e32 v96, 8, v97
	v_and_b32_e32 v106, 0xff00, v96
	v_med3_f32 v96, v99, s52, v198
	v_mul_f32_e32 v97, v101, v101
	v_mul_f32_e32 v99, v103, v103
	v_fmac_f32_e32 v97, v100, v100
	v_fmac_f32_e32 v99, v102, v102
	v_add_f32_e32 v97, v97, v99
	v_mul_f32_e32 v99, v129, v129
	v_fmac_f32_e32 v99, v128, v128
	v_add_f32_e32 v97, v99, v97
	v_mul_f32_e32 v99, v123, v123
	v_fmac_f32_e32 v99, v122, v122
	v_add_f32_e32 v97, v99, v97
	v_add_f32_e32 v97, v118, v97
	ds_bpermute_b32 v99, v116, v97
	v_rndne_f32_e32 v96, v96
	v_cvt_i32_f32_sdwa v100, v96 dst_sel:WORD_1 dst_unused:UNUSED_PAD src0_sel:DWORD
	v_med3_f32 v96, v104, s52, v198
	v_rndne_f32_e32 v96, v96
	v_cvt_i32_f32_e32 v101, v96
	s_waitcnt lgkmcnt(0)
	v_add_f32_e32 v96, v97, v99
	ds_bpermute_b32 v97, v117, v96
	v_and_b32_e32 v99, 0xff0000, v100
	v_perm_b32 v100, v101, v105, s53
	v_or3_b32 v99, v100, v106, v99
	global_store_dwordx2 v[120:121], v[98:99], off offset:128
	s_and_saveexec_b64 s[26:27], s[2:3]
	s_cbranch_execz .LBB0_642
	s_waitcnt lgkmcnt(0)
	v_add_f32_e32 v96, v96, v97
	v_fma_f32 v96, v96, s54, 0.5
	v_trunc_f32_e32 v96, v96
	v_mul_f32_e32 v97, 0x2f800000, v96
	v_floor_f32_e32 v97, v97
	v_fmac_f32_e32 v96, 0xcf800000, v97
	v_cvt_u32_f32_e32 v96, v96
	v_cvt_u32_f32_e32 v97, v97
	v_lshl_add_u64 v[98:99], v[184:185], 3, s[10:11]
	v_mov_b32_e32 v248, v96
	v_mov_b32_e32 v249, v97
.LBB0_642:
	s_or_b64 exec, exec, s[26:27]
	s_waitcnt lgkmcnt(0)
	v_lshl_add_u64 v[96:97], v[180:181], 3, s[8:9]
	v_mov_b32_e32 v96, v234
	v_mov_b32_e32 v97, v235
	v_lshlrev_b32_e32 v100, 16, v140
	v_and_b32_e32 v101, 0xffff0000, v140
	v_lshlrev_b32_e32 v102, 16, v141
	v_and_b32_e32 v103, 0xffff0000, v141
	v_lshlrev_b32_e32 v118, 16, v138
	v_and_b32_e32 v119, 0xffff0000, v138
	v_lshlrev_b32_e32 v104, 16, v142
	v_and_b32_e32 v105, 0xffff0000, v142
	v_lshlrev_b32_e32 v106, 16, v143
	v_and_b32_e32 v107, 0xffff0000, v143
	v_lshlrev_b32_e32 v120, 16, v139
	v_and_b32_e32 v121, 0xffff0000, v139
	v_pk_add_f32 v[94:95], v[94:95], v[102:103]
	v_pk_add_f32 v[92:93], v[92:93], v[100:101]
	v_pk_add_f32 v[102:103], v[80:81], v[118:119]
	v_cvt_pk_bf16_f32 v80, v92, v93
	v_pk_add_f32 v[90:91], v[90:91], v[106:107]
	v_pk_add_f32 v[88:89], v[88:89], v[104:105]
	v_pk_add_f32 v[100:101], v[82:83], v[120:121]
	v_cvt_pk_bf16_f32 v81, v94, v95
	v_cvt_pk_bf16_f32 v82, v88, v89
	v_cvt_pk_bf16_f32 v83, v90, v91
	global_store_dwordx4 v[182:183], v[80:83], off
	v_mul_f32_e32 v104, v93, v93
	v_mul_f32_e32 v105, v95, v95
	v_mul_f32_e32 v106, v89, v89
	v_fmac_f32_e32 v104, v92, v92
	v_fmac_f32_e32 v105, v94, v94
	v_mul_f32_e32 v107, v91, v91
	v_fmac_f32_e32 v106, v88, v88
	v_fmac_f32_e32 v107, v90, v90
	v_lshlrev_b64 v[98:99], 12, v[180:181]
	v_lshlrev_b32_e32 v108, 16, v136
	v_and_b32_e32 v109, 0xffff0000, v136
	v_lshl_add_u64 v[98:99], v[98:99], 0, v[168:169]
	v_lshlrev_b32_e32 v110, 16, v137
	v_and_b32_e32 v111, 0xffff0000, v137
	v_pk_add_f32 v[84:85], v[84:85], v[108:109]
	v_lshl_add_u64 v[98:99], s[12:13], 0, v[98:99]
	v_pk_add_f32 v[86:87], v[86:87], v[110:111]
	v_ffbh_u32_e32 v80, v97
	v_min_u32_e32 v82, 32, v80
	v_lshlrev_b64 v[80:81], v82, v[96:97]
	v_min_u32_e32 v80, 1, v80
	v_or_b32_e32 v80, v81, v80
	v_cvt_f32_u32_e32 v80, v80
	v_sub_u32_e32 v81, 32, v82
	v_ldexp_f32 v80, v80, v81
	v_fmamk_f32 v80, v80, 0x2f800000, v196
	v_rsq_f32_e32 v80, v80
	v_add_f32_e32 v81, v104, v105
	v_add_f32_e32 v81, v106, v81
	v_add_f32_e32 v96, v107, v81
	v_mul_f32_e32 v97, 0x41b56db7, v80
	v_mul_f32_e32 v80, v92, v97
	v_mul_f32_e32 v81, v93, v97
	v_mul_f32_e32 v83, v95, v97
	v_mul_f32_e32 v89, v89, v97
	v_mul_f32_e32 v82, v94, v97
	v_mul_f32_e32 v88, v88, v97
	v_mul_f32_e32 v90, v90, v97
	v_mul_f32_e32 v91, v91, v97
	v_med3_f32 v80, v80, s52, v198
	v_med3_f32 v81, v81, s52, v198
	v_med3_f32 v83, v83, s52, v198
	v_med3_f32 v89, v89, s52, v198
	v_med3_f32 v82, v82, s52, v198
	v_med3_f32 v88, v88, s52, v198
	v_med3_f32 v90, v90, s52, v198
	v_med3_f32 v91, v91, s52, v198
	v_rndne_f32_e32 v80, v80
	v_rndne_f32_e32 v81, v81
	v_rndne_f32_e32 v83, v83
	v_rndne_f32_e32 v89, v89
	v_rndne_f32_e32 v82, v82
	v_rndne_f32_e32 v88, v88
	v_rndne_f32_e32 v90, v90
	v_rndne_f32_e32 v91, v91
	v_cvt_i32_f32_e32 v80, v80
	v_cvt_i32_f32_e32 v81, v81
	v_cvt_i32_f32_e32 v83, v83
	v_cvt_i32_f32_e32 v89, v89
	v_cvt_i32_f32_sdwa v82, v82 dst_sel:WORD_1 dst_unused:UNUSED_PAD src0_sel:DWORD
	v_cvt_i32_f32_e32 v88, v88
	v_cvt_i32_f32_sdwa v90, v90 dst_sel:WORD_1 dst_unused:UNUSED_PAD src0_sel:DWORD
	v_cvt_i32_f32_e32 v91, v91
	v_lshlrev_b32_e32 v81, 8, v81
	v_perm_b32 v80, v83, v80, s53
	v_lshlrev_b32_e32 v83, 8, v89
	v_and_b32_e32 v82, 0xff0000, v82
	v_and_b32_e32 v89, 0xff0000, v90
	v_perm_b32 v88, v91, v88, s53
	v_and_b32_e32 v81, 0xff00, v81
	v_and_b32_e32 v83, 0xff00, v83
	v_or3_b32 v80, v80, v81, v82
	v_or3_b32 v81, v88, v83, v89
	v_mul_f32_e32 v93, v85, v97
	global_store_dwordx2 v[98:99], v[80:81], off
	v_cvt_pk_bf16_f32 v80, v84, v85
	v_cvt_pk_bf16_f32 v81, v86, v87
	v_mul_f32_e32 v92, v84, v97
	v_mul_f32_e32 v94, v86, v97
	v_mul_f32_e32 v95, v87, v97
	v_cvt_pk_bf16_f32 v82, v102, v103
	v_cvt_pk_bf16_f32 v83, v100, v101
	global_store_dwordx4 v[182:183], v[80:83], off offset:256
	v_med3_f32 v92, v92, s52, v198
	v_mul_f32_e32 v88, v101, v97
	v_med3_f32 v81, v93, s52, v198
	v_rndne_f32_e32 v81, v81
	v_med3_f32 v82, v94, s52, v198
	v_med3_f32 v83, v95, s52, v198
	v_rndne_f32_e32 v80, v92
	v_cvt_i32_f32_e32 v81, v81
	v_rndne_f32_e32 v82, v82
	v_rndne_f32_e32 v83, v83
	v_cvt_i32_f32_e32 v80, v80
	v_cvt_i32_f32_sdwa v82, v82 dst_sel:WORD_1 dst_unused:UNUSED_PAD src0_sel:DWORD
	v_cvt_i32_f32_e32 v83, v83
	v_lshlrev_b32_e32 v81, 8, v81
	v_and_b32_e32 v81, 0xff00, v81
	v_and_b32_e32 v82, 0xff0000, v82
	v_perm_b32 v80, v83, v80, s53
	v_or3_b32 v82, v80, v81, v82
	v_mul_f32_e32 v81, v103, v97
	v_med3_f32 v81, v81, s52, v198
	v_rndne_f32_e32 v81, v81
	v_cvt_i32_f32_e32 v81, v81
	v_mul_f32_e32 v80, v102, v97
	v_med3_f32 v80, v80, s52, v198
	v_rndne_f32_e32 v80, v80
	v_mul_f32_e32 v83, v100, v97
	v_cvt_i32_f32_e32 v89, v80
	v_lshlrev_b32_e32 v80, 8, v81
	v_and_b32_e32 v90, 0xff00, v80
	v_med3_f32 v80, v83, s52, v198
	v_mul_f32_e32 v81, v85, v85
	v_mul_f32_e32 v83, v87, v87
	v_fmac_f32_e32 v81, v84, v84
	v_fmac_f32_e32 v83, v86, v86
	v_add_f32_e32 v81, v81, v83
	v_mul_f32_e32 v83, v103, v103
	v_fmac_f32_e32 v83, v102, v102
	v_add_f32_e32 v81, v83, v81
	v_mul_f32_e32 v83, v101, v101
	v_fmac_f32_e32 v83, v100, v100
	v_add_f32_e32 v81, v83, v81
	v_add_f32_e32 v81, v96, v81
	ds_bpermute_b32 v83, v116, v81
	v_rndne_f32_e32 v80, v80
	v_cvt_i32_f32_sdwa v84, v80 dst_sel:WORD_1 dst_unused:UNUSED_PAD src0_sel:DWORD
	v_med3_f32 v80, v88, s52, v198
	v_rndne_f32_e32 v80, v80
	v_cvt_i32_f32_e32 v85, v80
	s_waitcnt lgkmcnt(0)
	v_add_f32_e32 v80, v81, v83
	ds_bpermute_b32 v81, v117, v80
	v_and_b32_e32 v83, 0xff0000, v84
	v_perm_b32 v84, v85, v89, s53
	v_or3_b32 v83, v84, v90, v83
	global_store_dwordx2 v[98:99], v[82:83], off offset:128
	s_and_saveexec_b64 s[26:27], s[2:3]
	s_cbranch_execz .LBB0_644
	s_waitcnt lgkmcnt(0)
	v_add_f32_e32 v80, v80, v81
	v_fma_f32 v80, v80, s54, 0.5
	v_trunc_f32_e32 v80, v80
	v_mul_f32_e32 v81, 0x2f800000, v80
	v_floor_f32_e32 v81, v81
	v_fmac_f32_e32 v80, 0xcf800000, v81
	v_cvt_u32_f32_e32 v80, v80
	v_cvt_u32_f32_e32 v81, v81
	v_lshl_add_u64 v[82:83], v[180:181], 3, s[10:11]
	v_mov_b32_e32 v250, v80
	v_mov_b32_e32 v251, v81
.LBB0_644:
	s_or_b64 exec, exec, s[26:27]
	s_waitcnt lgkmcnt(0)
	v_lshl_add_u64 v[80:81], v[176:177], 3, s[8:9]
	v_mov_b32_e32 v80, v236
	v_mov_b32_e32 v81, v237
	v_lshlrev_b32_e32 v84, 16, v124
	v_and_b32_e32 v85, 0xffff0000, v124
	v_lshlrev_b32_e32 v86, 16, v125
	v_and_b32_e32 v87, 0xffff0000, v125
	v_lshlrev_b32_e32 v96, 16, v114
	v_and_b32_e32 v97, 0xffff0000, v114
	v_lshlrev_b32_e32 v88, 16, v126
	v_and_b32_e32 v89, 0xffff0000, v126
	v_lshlrev_b32_e32 v90, 16, v127
	v_and_b32_e32 v91, 0xffff0000, v127
	v_lshlrev_b32_e32 v98, 16, v115
	v_and_b32_e32 v99, 0xffff0000, v115
	v_pk_add_f32 v[78:79], v[78:79], v[86:87]
	v_pk_add_f32 v[76:77], v[76:77], v[84:85]
	v_pk_add_f32 v[86:87], v[64:65], v[96:97]
	v_cvt_pk_bf16_f32 v64, v76, v77
	v_pk_add_f32 v[74:75], v[74:75], v[90:91]
	v_pk_add_f32 v[72:73], v[72:73], v[88:89]
	v_pk_add_f32 v[84:85], v[66:67], v[98:99]
	v_cvt_pk_bf16_f32 v65, v78, v79
	v_cvt_pk_bf16_f32 v66, v72, v73
	v_cvt_pk_bf16_f32 v67, v74, v75
	global_store_dwordx4 v[178:179], v[64:67], off
	v_mul_f32_e32 v88, v77, v77
	v_mul_f32_e32 v89, v79, v79
	v_mul_f32_e32 v90, v73, v73
	v_fmac_f32_e32 v88, v76, v76
	v_fmac_f32_e32 v89, v78, v78
	v_mul_f32_e32 v91, v75, v75
	v_fmac_f32_e32 v90, v72, v72
	v_fmac_f32_e32 v91, v74, v74
	v_lshlrev_b64 v[82:83], 12, v[176:177]
	v_lshlrev_b32_e32 v92, 16, v112
	v_and_b32_e32 v93, 0xffff0000, v112
	v_lshl_add_u64 v[82:83], v[82:83], 0, v[168:169]
	v_lshlrev_b32_e32 v94, 16, v113
	v_and_b32_e32 v95, 0xffff0000, v113
	v_pk_add_f32 v[68:69], v[68:69], v[92:93]
	v_lshl_add_u64 v[82:83], s[12:13], 0, v[82:83]
	v_pk_add_f32 v[70:71], v[70:71], v[94:95]
	v_ffbh_u32_e32 v64, v81
	v_min_u32_e32 v66, 32, v64
	v_lshlrev_b64 v[64:65], v66, v[80:81]
	v_min_u32_e32 v64, 1, v64
	v_or_b32_e32 v64, v65, v64
	v_cvt_f32_u32_e32 v64, v64
	v_sub_u32_e32 v65, 32, v66
	v_ldexp_f32 v64, v64, v65
	v_fmamk_f32 v64, v64, 0x2f800000, v196
	v_rsq_f32_e32 v64, v64
	v_add_f32_e32 v65, v88, v89
	v_add_f32_e32 v65, v90, v65
	v_add_f32_e32 v80, v91, v65
	v_mul_f32_e32 v81, 0x41b56db7, v64
	v_mul_f32_e32 v64, v76, v81
	v_mul_f32_e32 v65, v77, v81
	v_mul_f32_e32 v67, v79, v81
	v_mul_f32_e32 v73, v73, v81
	v_mul_f32_e32 v66, v78, v81
	v_mul_f32_e32 v72, v72, v81
	v_mul_f32_e32 v74, v74, v81
	v_mul_f32_e32 v75, v75, v81
	v_med3_f32 v64, v64, s52, v198
	v_med3_f32 v65, v65, s52, v198
	v_med3_f32 v67, v67, s52, v198
	v_med3_f32 v73, v73, s52, v198
	v_med3_f32 v66, v66, s52, v198
	v_med3_f32 v72, v72, s52, v198
	v_med3_f32 v74, v74, s52, v198
	v_med3_f32 v75, v75, s52, v198
	v_rndne_f32_e32 v64, v64
	v_rndne_f32_e32 v65, v65
	v_rndne_f32_e32 v67, v67
	v_rndne_f32_e32 v73, v73
	v_rndne_f32_e32 v66, v66
	v_rndne_f32_e32 v72, v72
	v_rndne_f32_e32 v74, v74
	v_rndne_f32_e32 v75, v75
	v_cvt_i32_f32_e32 v64, v64
	v_cvt_i32_f32_e32 v65, v65
	v_cvt_i32_f32_e32 v67, v67
	v_cvt_i32_f32_e32 v73, v73
	v_cvt_i32_f32_sdwa v66, v66 dst_sel:WORD_1 dst_unused:UNUSED_PAD src0_sel:DWORD
	v_cvt_i32_f32_e32 v72, v72
	v_cvt_i32_f32_sdwa v74, v74 dst_sel:WORD_1 dst_unused:UNUSED_PAD src0_sel:DWORD
	v_cvt_i32_f32_e32 v75, v75
	v_lshlrev_b32_e32 v65, 8, v65
	v_perm_b32 v64, v67, v64, s53
	v_lshlrev_b32_e32 v67, 8, v73
	v_and_b32_e32 v66, 0xff0000, v66
	v_and_b32_e32 v73, 0xff0000, v74
	v_perm_b32 v72, v75, v72, s53
	v_and_b32_e32 v65, 0xff00, v65
	v_and_b32_e32 v67, 0xff00, v67
	v_or3_b32 v64, v64, v65, v66
	v_or3_b32 v65, v72, v67, v73
	v_mul_f32_e32 v77, v69, v81
	global_store_dwordx2 v[82:83], v[64:65], off
	v_cvt_pk_bf16_f32 v64, v68, v69
	v_cvt_pk_bf16_f32 v65, v70, v71
	v_mul_f32_e32 v76, v68, v81
	v_mul_f32_e32 v78, v70, v81
	v_mul_f32_e32 v79, v71, v81
	v_cvt_pk_bf16_f32 v66, v86, v87
	v_cvt_pk_bf16_f32 v67, v84, v85
	global_store_dwordx4 v[178:179], v[64:67], off offset:256
	v_med3_f32 v76, v76, s52, v198
	v_mul_f32_e32 v72, v85, v81
	v_med3_f32 v65, v77, s52, v198
	v_rndne_f32_e32 v65, v65
	v_med3_f32 v66, v78, s52, v198
	v_med3_f32 v67, v79, s52, v198
	v_rndne_f32_e32 v64, v76
	v_cvt_i32_f32_e32 v65, v65
	v_rndne_f32_e32 v66, v66
	v_rndne_f32_e32 v67, v67
	v_cvt_i32_f32_e32 v64, v64
	v_cvt_i32_f32_sdwa v66, v66 dst_sel:WORD_1 dst_unused:UNUSED_PAD src0_sel:DWORD
	v_cvt_i32_f32_e32 v67, v67
	v_lshlrev_b32_e32 v65, 8, v65
	v_and_b32_e32 v65, 0xff00, v65
	v_and_b32_e32 v66, 0xff0000, v66
	v_perm_b32 v64, v67, v64, s53
	v_or3_b32 v66, v64, v65, v66
	v_mul_f32_e32 v65, v87, v81
	v_med3_f32 v65, v65, s52, v198
	v_rndne_f32_e32 v65, v65
	v_cvt_i32_f32_e32 v65, v65
	v_mul_f32_e32 v64, v86, v81
	v_med3_f32 v64, v64, s52, v198
	v_rndne_f32_e32 v64, v64
	v_mul_f32_e32 v67, v84, v81
	v_cvt_i32_f32_e32 v73, v64
	v_lshlrev_b32_e32 v64, 8, v65
	v_and_b32_e32 v74, 0xff00, v64
	v_med3_f32 v64, v67, s52, v198
	v_mul_f32_e32 v65, v69, v69
	v_mul_f32_e32 v67, v71, v71
	v_fmac_f32_e32 v65, v68, v68
	v_fmac_f32_e32 v67, v70, v70
	v_add_f32_e32 v65, v65, v67
	v_mul_f32_e32 v67, v87, v87
	v_fmac_f32_e32 v67, v86, v86
	v_add_f32_e32 v65, v67, v65
	v_mul_f32_e32 v67, v85, v85
	v_fmac_f32_e32 v67, v84, v84
	v_add_f32_e32 v65, v67, v65
	v_add_f32_e32 v65, v80, v65
	ds_bpermute_b32 v67, v116, v65
	v_rndne_f32_e32 v64, v64
	v_cvt_i32_f32_sdwa v68, v64 dst_sel:WORD_1 dst_unused:UNUSED_PAD src0_sel:DWORD
	v_med3_f32 v64, v72, s52, v198
	v_rndne_f32_e32 v64, v64
	v_cvt_i32_f32_e32 v69, v64
	s_waitcnt lgkmcnt(0)
	v_add_f32_e32 v64, v65, v67
	ds_bpermute_b32 v65, v117, v64
	v_and_b32_e32 v67, 0xff0000, v68
	v_perm_b32 v68, v69, v73, s53
	v_or3_b32 v67, v68, v74, v67
	global_store_dwordx2 v[82:83], v[66:67], off offset:128
	s_and_saveexec_b64 s[26:27], s[2:3]
	s_cbranch_execz .LBB0_646
	s_waitcnt lgkmcnt(0)
	v_add_f32_e32 v64, v64, v65
	v_fma_f32 v64, v64, s54, 0.5
	v_trunc_f32_e32 v64, v64
	v_mul_f32_e32 v65, 0x2f800000, v64
	v_floor_f32_e32 v65, v65
	v_fmac_f32_e32 v64, 0xcf800000, v65
	v_cvt_u32_f32_e32 v64, v64
	v_cvt_u32_f32_e32 v65, v65
	v_lshl_add_u64 v[66:67], v[176:177], 3, s[10:11]
	v_mov_b32_e32 v252, v64
	v_mov_b32_e32 v253, v65
.LBB0_646:
	s_or_b64 exec, exec, s[26:27]
	v_add_u32_e32 v100, 0x80, v174
	v_ashrrev_i32_e32 v101, 31, v100
	s_waitcnt lgkmcnt(0)
	v_lshlrev_b64 v[64:65], 13, v[100:101]
	v_lshl_add_u64 v[102:103], v[172:173], 0, v[64:65]
	v_mov_b32_e32 v112, v238
	v_mov_b32_e32 v113, v239
	global_load_dwordx4 v[104:107], v[102:103], off
	v_add_u32_e32 v96, 0x90, v174
	v_add_u32_e32 v92, 0xa0, v174
	v_add_u32_e32 v88, 0xb0, v174
	v_ashrrev_i32_e32 v97, 31, v96
	v_ashrrev_i32_e32 v93, 31, v92
	v_ashrrev_i32_e32 v89, 31, v88
	v_lshlrev_b64 v[64:65], 13, v[96:97]
	v_lshlrev_b64 v[66:67], 13, v[92:93]
	v_lshlrev_b64 v[68:69], 13, v[88:89]
	v_lshlrev_b64 v[70:71], 12, v[100:101]
	v_lshl_add_u64 v[98:99], v[172:173], 0, v[64:65]
	v_lshl_add_u64 v[94:95], v[172:173], 0, v[66:67]
	v_lshl_add_u64 v[90:91], v[172:173], 0, v[68:69]
	v_lshl_add_u64 v[114:115], v[70:71], 0, v[168:169]
	global_load_dwordx4 v[108:111], v[102:103], off offset:256
	global_load_dwordx4 v[84:87], v[98:99], off
	global_load_dwordx4 v[80:83], v[98:99], off offset:256
	global_load_dwordx4 v[76:79], v[94:95], off
	global_load_dwordx4 v[72:75], v[94:95], off offset:256
	global_load_dwordx4 v[68:71], v[90:91], off
	global_load_dwordx4 v[64:67], v[90:91], off offset:256
	s_and_saveexec_b64 s[96:97], s[2:3]
	global_atomic_add_x2 v[228:229], v[246:247], off
	global_atomic_add_x2 v[228:229], v[248:249], off offset:128
	global_atomic_add_x2 v[228:229], v[250:251], off offset:256
	global_atomic_add_x2 v[228:229], v[252:253], off offset:384
	s_mov_b64 exec, s[96:97]
	v_lshl_add_u64 v[114:115], s[12:13], 0, v[114:115]
	v_ffbh_u32_e32 v122, v113
	v_min_u32_e32 v122, 32, v122
	s_waitcnt vmcnt(11)
	v_lshlrev_b32_e32 v118, 16, v104
	v_and_b32_e32 v119, 0xffff0000, v104
	v_lshlrev_b32_e32 v104, 16, v105
	v_and_b32_e32 v105, 0xffff0000, v105
	v_lshlrev_b32_e32 v120, 16, v106
	v_and_b32_e32 v121, 0xffff0000, v106
	v_lshlrev_b32_e32 v106, 16, v107
	v_and_b32_e32 v107, 0xffff0000, v107
	v_lshlrev_b64 v[112:113], v122, v[112:113]
	v_pk_add_f32 v[62:63], v[62:63], v[104:105]
	v_pk_add_f32 v[60:61], v[60:61], v[118:119]
	v_pk_add_f32 v[104:105], v[58:59], v[106:107]
	v_pk_add_f32 v[106:107], v[56:57], v[120:121]
	v_cvt_pk_bf16_f32 v56, v60, v61
	v_min_u32_e32 v112, 1, v112
	v_cvt_pk_bf16_f32 v57, v62, v63
	v_cvt_pk_bf16_f32 v58, v106, v107
	v_cvt_pk_bf16_f32 v59, v104, v105
	global_store_dwordx4 v[102:103], v[56:59], off
	v_sub_u32_e32 v118, 32, v122
	v_mul_f32_e32 v119, v61, v61
	v_or_b32_e32 v56, v113, v112
	v_cvt_f32_u32_e32 v56, v56
	v_mul_f32_e32 v120, v63, v63
	v_mul_f32_e32 v121, v107, v107
	v_fmac_f32_e32 v119, v60, v60
	v_ldexp_f32 v56, v56, v118
	v_fmamk_f32 v56, v56, 0x2f800000, v196
	v_rsq_f32_e32 v56, v56
	v_fmac_f32_e32 v120, v62, v62
	v_mul_f32_e32 v122, v105, v105
	v_fmac_f32_e32 v121, v106, v106
	v_add_f32_e32 v57, v119, v120
	v_fmac_f32_e32 v122, v104, v104
	v_add_f32_e32 v57, v121, v57
	v_mul_f32_e32 v113, 0x41b56db7, v56
	v_add_f32_e32 v112, v122, v57
	v_mul_f32_e32 v56, v113, v60
	v_mul_f32_e32 v57, v113, v61
	v_mul_f32_e32 v59, v113, v63
	v_mul_f32_e32 v61, v113, v107
	v_mul_f32_e32 v58, v113, v62
	v_mul_f32_e32 v60, v113, v106
	v_mul_f32_e32 v62, v113, v104
	v_mul_f32_e32 v63, v113, v105
	v_med3_f32 v56, v56, s52, v198
	v_med3_f32 v57, v57, s52, v198
	v_med3_f32 v59, v59, s52, v198
	v_med3_f32 v61, v61, s52, v198
	v_med3_f32 v58, v58, s52, v198
	v_med3_f32 v60, v60, s52, v198
	v_med3_f32 v62, v62, s52, v198
	v_med3_f32 v63, v63, s52, v198
	v_rndne_f32_e32 v56, v56
	v_rndne_f32_e32 v57, v57
	v_rndne_f32_e32 v59, v59
	v_rndne_f32_e32 v61, v61
	v_rndne_f32_e32 v58, v58
	v_rndne_f32_e32 v60, v60
	v_rndne_f32_e32 v62, v62
	v_rndne_f32_e32 v63, v63
	v_cvt_i32_f32_e32 v56, v56
	v_cvt_i32_f32_e32 v57, v57
	v_cvt_i32_f32_e32 v59, v59
	v_cvt_i32_f32_e32 v61, v61
	v_cvt_i32_f32_sdwa v58, v58 dst_sel:WORD_1 dst_unused:UNUSED_PAD src0_sel:DWORD
	v_cvt_i32_f32_e32 v60, v60
	v_cvt_i32_f32_sdwa v62, v62 dst_sel:WORD_1 dst_unused:UNUSED_PAD src0_sel:DWORD
	v_cvt_i32_f32_e32 v63, v63
	v_lshlrev_b32_e32 v57, 8, v57
	v_perm_b32 v56, v59, v56, s53
	v_lshlrev_b32_e32 v59, 8, v61
	v_and_b32_e32 v58, 0xff0000, v58
	v_and_b32_e32 v61, 0xff0000, v62
	v_perm_b32 v60, v63, v60, s53
	v_and_b32_e32 v57, 0xff00, v57
	v_and_b32_e32 v59, 0xff00, v59
	v_or3_b32 v56, v56, v57, v58
	v_or3_b32 v57, v60, v59, v61
	global_store_dwordx2 v[114:115], v[56:57], off
	s_waitcnt vmcnt(12)
	v_lshlrev_b32_e32 v56, 16, v108
	v_and_b32_e32 v57, 0xffff0000, v108
	v_lshlrev_b32_e32 v58, 16, v109
	v_and_b32_e32 v59, 0xffff0000, v109
	v_lshlrev_b32_e32 v60, 16, v110
	v_and_b32_e32 v61, 0xffff0000, v110
	v_lshlrev_b32_e32 v62, 16, v111
	v_and_b32_e32 v63, 0xffff0000, v111
	v_pk_add_f32 v[54:55], v[54:55], v[58:59]
	v_pk_add_f32 v[52:53], v[52:53], v[56:57]
	v_pk_add_f32 v[58:59], v[48:49], v[60:61]
	v_cvt_pk_bf16_f32 v48, v52, v53
	v_cvt_pk_bf16_f32 v49, v54, v55
	v_pk_add_f32 v[56:57], v[50:51], v[62:63]
	v_cvt_pk_bf16_f32 v50, v58, v59
	s_nop 0
	v_cvt_pk_bf16_f32 v51, v56, v57
	global_store_dwordx4 v[102:103], v[48:51], off offset:256
	v_mul_f32_e32 v60, v113, v57
	s_nop 0
	v_mul_f32_e32 v49, v113, v53
	v_mul_f32_e32 v48, v113, v52
	v_mul_f32_e32 v50, v113, v54
	v_mul_f32_e32 v51, v113, v55
	v_med3_f32 v49, v49, s52, v198
	v_med3_f32 v48, v48, s52, v198
	v_rndne_f32_e32 v49, v49
	v_med3_f32 v50, v50, s52, v198
	v_med3_f32 v51, v51, s52, v198
	v_rndne_f32_e32 v48, v48
	v_cvt_i32_f32_e32 v49, v49
	v_rndne_f32_e32 v50, v50
	v_rndne_f32_e32 v51, v51
	v_cvt_i32_f32_e32 v48, v48
	v_cvt_i32_f32_sdwa v50, v50 dst_sel:WORD_1 dst_unused:UNUSED_PAD src0_sel:DWORD
	v_cvt_i32_f32_e32 v51, v51
	v_lshlrev_b32_e32 v49, 8, v49
	v_and_b32_e32 v49, 0xff00, v49
	v_and_b32_e32 v50, 0xff0000, v50
	v_perm_b32 v48, v51, v48, s53
	v_or3_b32 v50, v48, v49, v50
	v_mul_f32_e32 v49, v113, v59
	v_med3_f32 v49, v49, s52, v198
	v_rndne_f32_e32 v49, v49
	v_cvt_i32_f32_e32 v49, v49
	v_mul_f32_e32 v48, v113, v58
	v_med3_f32 v48, v48, s52, v198
	v_rndne_f32_e32 v48, v48
	v_mul_f32_e32 v51, v113, v56
	v_cvt_i32_f32_e32 v61, v48
	v_lshlrev_b32_e32 v48, 8, v49
	v_and_b32_e32 v62, 0xff00, v48
	v_med3_f32 v48, v51, s52, v198
	v_mul_f32_e32 v49, v53, v53
	v_mul_f32_e32 v51, v55, v55
	v_fmac_f32_e32 v49, v52, v52
	v_fmac_f32_e32 v51, v54, v54
	v_add_f32_e32 v49, v49, v51
	v_mul_f32_e32 v51, v59, v59
	v_fmac_f32_e32 v51, v58, v58
	v_add_f32_e32 v49, v51, v49
	v_mul_f32_e32 v51, v57, v57
	v_fmac_f32_e32 v51, v56, v56
	v_add_f32_e32 v49, v51, v49
	v_add_f32_e32 v49, v112, v49
	ds_bpermute_b32 v51, v116, v49
	v_rndne_f32_e32 v48, v48
	v_cvt_i32_f32_sdwa v52, v48 dst_sel:WORD_1 dst_unused:UNUSED_PAD src0_sel:DWORD
	v_med3_f32 v48, v60, s52, v198
	v_rndne_f32_e32 v48, v48
	v_cvt_i32_f32_e32 v53, v48
	s_waitcnt lgkmcnt(0)
	v_add_f32_e32 v48, v49, v51
	ds_bpermute_b32 v49, v117, v48
	v_and_b32_e32 v51, 0xff0000, v52
	v_perm_b32 v52, v53, v61, s53
	v_or3_b32 v51, v52, v62, v51
	global_store_dwordx2 v[114:115], v[50:51], off offset:128
	s_and_saveexec_b64 s[26:27], s[2:3]
	s_cbranch_execz .LBB0_648
	s_waitcnt lgkmcnt(0)
	v_add_f32_e32 v48, v48, v49
	v_fma_f32 v48, v48, s54, 0.5
	v_trunc_f32_e32 v48, v48
	v_mul_f32_e32 v49, 0x2f800000, v48
	v_floor_f32_e32 v49, v49
	v_fmac_f32_e32 v48, 0xcf800000, v49
	v_cvt_u32_f32_e32 v48, v48
	v_cvt_u32_f32_e32 v49, v49
	v_lshl_add_u64 v[50:51], v[100:101], 3, s[10:11]
	v_mov_b32_e32 v228, v50
	v_mov_b32_e32 v229, v51
	v_mov_b32_e32 v246, v48
	v_mov_b32_e32 v247, v49
.LBB0_648:
	s_or_b64 exec, exec, s[26:27]
	s_waitcnt lgkmcnt(0)
	v_mov_b32_e32 v48, v240
	v_mov_b32_e32 v49, v241
	s_waitcnt vmcnt(12)
	v_lshlrev_b32_e32 v52, 16, v84
	v_and_b32_e32 v53, 0xffff0000, v84
	v_lshlrev_b32_e32 v54, 16, v85
	v_and_b32_e32 v55, 0xffff0000, v85
	s_waitcnt vmcnt(11)
	v_lshlrev_b32_e32 v60, 16, v80
	v_and_b32_e32 v61, 0xffff0000, v80
	v_lshlrev_b32_e32 v62, 16, v81
	v_and_b32_e32 v63, 0xffff0000, v81
	v_lshlrev_b32_e32 v80, 16, v82
	v_and_b32_e32 v81, 0xffff0000, v82
	v_lshlrev_b32_e32 v56, 16, v86
	v_and_b32_e32 v57, 0xffff0000, v86
	v_lshlrev_b32_e32 v58, 16, v87
	v_and_b32_e32 v59, 0xffff0000, v87
	v_lshlrev_b32_e32 v82, 16, v83
	v_and_b32_e32 v83, 0xffff0000, v83
	v_pk_add_f32 v[46:47], v[46:47], v[54:55]
	v_pk_add_f32 v[44:45], v[44:45], v[52:53]
	v_pk_add_f32 v[54:55], v[32:33], v[80:81]
	v_cvt_pk_bf16_f32 v32, v44, v45
	v_pk_add_f32 v[42:43], v[42:43], v[58:59]
	v_pk_add_f32 v[40:41], v[40:41], v[56:57]
	v_pk_add_f32 v[52:53], v[34:35], v[82:83]
	v_cvt_pk_bf16_f32 v33, v46, v47
	v_cvt_pk_bf16_f32 v34, v40, v41
	v_cvt_pk_bf16_f32 v35, v42, v43
	global_store_dwordx4 v[98:99], v[32:35], off
	v_mul_f32_e32 v56, v45, v45
	v_mul_f32_e32 v57, v47, v47
	v_mul_f32_e32 v58, v41, v41
	v_fmac_f32_e32 v56, v44, v44
	v_fmac_f32_e32 v57, v46, v46
	v_mul_f32_e32 v59, v43, v43
	v_fmac_f32_e32 v58, v40, v40
	v_fmac_f32_e32 v59, v42, v42
	v_lshlrev_b64 v[50:51], 12, v[96:97]
	v_lshl_add_u64 v[50:51], v[50:51], 0, v[168:169]
	v_pk_add_f32 v[36:37], v[36:37], v[60:61]
	v_lshl_add_u64 v[50:51], s[12:13], 0, v[50:51]
	v_pk_add_f32 v[38:39], v[38:39], v[62:63]
	s_waitcnt vmcnt(9)
	v_ffbh_u32_e32 v32, v49
	v_min_u32_e32 v34, 32, v32
	v_lshlrev_b64 v[32:33], v34, v[48:49]
	v_min_u32_e32 v32, 1, v32
	v_or_b32_e32 v32, v33, v32
	v_cvt_f32_u32_e32 v32, v32
	v_sub_u32_e32 v33, 32, v34
	v_ldexp_f32 v32, v32, v33
	v_fmamk_f32 v32, v32, 0x2f800000, v196
	v_rsq_f32_e32 v32, v32
	v_add_f32_e32 v33, v56, v57
	v_add_f32_e32 v33, v58, v33
	v_add_f32_e32 v48, v59, v33
	v_mul_f32_e32 v49, 0x41b56db7, v32
	v_mul_f32_e32 v32, v44, v49
	v_mul_f32_e32 v33, v45, v49
	v_mul_f32_e32 v35, v47, v49
	v_mul_f32_e32 v41, v41, v49
	v_mul_f32_e32 v34, v46, v49
	v_mul_f32_e32 v40, v40, v49
	v_mul_f32_e32 v42, v42, v49
	v_mul_f32_e32 v43, v43, v49
	v_med3_f32 v32, v32, s52, v198
	v_med3_f32 v33, v33, s52, v198
	v_med3_f32 v35, v35, s52, v198
	v_med3_f32 v41, v41, s52, v198
	v_med3_f32 v34, v34, s52, v198
	v_med3_f32 v40, v40, s52, v198
	v_med3_f32 v42, v42, s52, v198
	v_med3_f32 v43, v43, s52, v198
	v_rndne_f32_e32 v32, v32
	v_rndne_f32_e32 v33, v33
	v_rndne_f32_e32 v35, v35
	v_rndne_f32_e32 v41, v41
	v_rndne_f32_e32 v34, v34
	v_rndne_f32_e32 v40, v40
	v_rndne_f32_e32 v42, v42
	v_rndne_f32_e32 v43, v43
	v_cvt_i32_f32_e32 v32, v32
	v_cvt_i32_f32_e32 v33, v33
	v_cvt_i32_f32_e32 v35, v35
	v_cvt_i32_f32_e32 v41, v41
	v_cvt_i32_f32_sdwa v34, v34 dst_sel:WORD_1 dst_unused:UNUSED_PAD src0_sel:DWORD
	v_cvt_i32_f32_e32 v40, v40
	v_cvt_i32_f32_sdwa v42, v42 dst_sel:WORD_1 dst_unused:UNUSED_PAD src0_sel:DWORD
	v_cvt_i32_f32_e32 v43, v43
	v_lshlrev_b32_e32 v33, 8, v33
	v_perm_b32 v32, v35, v32, s53
	v_lshlrev_b32_e32 v35, 8, v41
	v_and_b32_e32 v34, 0xff0000, v34
	v_and_b32_e32 v41, 0xff0000, v42
	v_perm_b32 v40, v43, v40, s53
	v_and_b32_e32 v33, 0xff00, v33
	v_and_b32_e32 v35, 0xff00, v35
	v_or3_b32 v32, v32, v33, v34
	v_or3_b32 v33, v40, v35, v41
	v_mul_f32_e32 v45, v37, v49
	global_store_dwordx2 v[50:51], v[32:33], off
	v_cvt_pk_bf16_f32 v32, v36, v37
	v_cvt_pk_bf16_f32 v33, v38, v39
	v_mul_f32_e32 v44, v36, v49
	v_mul_f32_e32 v46, v38, v49
	v_mul_f32_e32 v47, v39, v49
	v_cvt_pk_bf16_f32 v34, v54, v55
	v_cvt_pk_bf16_f32 v35, v52, v53
	global_store_dwordx4 v[98:99], v[32:35], off offset:256
	v_med3_f32 v44, v44, s52, v198
	v_mul_f32_e32 v40, v53, v49
	v_med3_f32 v33, v45, s52, v198
	v_rndne_f32_e32 v33, v33
	v_med3_f32 v34, v46, s52, v198
	v_med3_f32 v35, v47, s52, v198
	v_rndne_f32_e32 v32, v44
	v_cvt_i32_f32_e32 v33, v33
	v_rndne_f32_e32 v34, v34
	v_rndne_f32_e32 v35, v35
	v_cvt_i32_f32_e32 v32, v32
	v_cvt_i32_f32_sdwa v34, v34 dst_sel:WORD_1 dst_unused:UNUSED_PAD src0_sel:DWORD
	v_cvt_i32_f32_e32 v35, v35
	v_lshlrev_b32_e32 v33, 8, v33
	v_and_b32_e32 v33, 0xff00, v33
	v_and_b32_e32 v34, 0xff0000, v34
	v_perm_b32 v32, v35, v32, s53
	v_or3_b32 v34, v32, v33, v34
	v_mul_f32_e32 v33, v55, v49
	v_med3_f32 v33, v33, s52, v198
	v_rndne_f32_e32 v33, v33
	v_cvt_i32_f32_e32 v33, v33
	v_mul_f32_e32 v32, v54, v49
	v_med3_f32 v32, v32, s52, v198
	v_rndne_f32_e32 v32, v32
	v_mul_f32_e32 v35, v52, v49
	v_cvt_i32_f32_e32 v41, v32
	v_lshlrev_b32_e32 v32, 8, v33
	v_and_b32_e32 v42, 0xff00, v32
	v_med3_f32 v32, v35, s52, v198
	v_mul_f32_e32 v33, v37, v37
	v_mul_f32_e32 v35, v39, v39
	v_fmac_f32_e32 v33, v36, v36
	v_fmac_f32_e32 v35, v38, v38
	v_add_f32_e32 v33, v33, v35
	v_mul_f32_e32 v35, v55, v55
	v_fmac_f32_e32 v35, v54, v54
	v_add_f32_e32 v33, v35, v33
	v_mul_f32_e32 v35, v53, v53
	v_fmac_f32_e32 v35, v52, v52
	v_add_f32_e32 v33, v35, v33
	v_add_f32_e32 v33, v48, v33
	ds_bpermute_b32 v35, v116, v33
	v_rndne_f32_e32 v32, v32
	v_cvt_i32_f32_sdwa v36, v32 dst_sel:WORD_1 dst_unused:UNUSED_PAD src0_sel:DWORD
	v_med3_f32 v32, v40, s52, v198
	v_rndne_f32_e32 v32, v32
	v_cvt_i32_f32_e32 v37, v32
	s_waitcnt lgkmcnt(0)
	v_add_f32_e32 v32, v33, v35
	ds_bpermute_b32 v33, v117, v32
	v_and_b32_e32 v35, 0xff0000, v36
	v_perm_b32 v36, v37, v41, s53
	v_or3_b32 v35, v36, v42, v35
	global_store_dwordx2 v[50:51], v[34:35], off offset:128
	s_and_saveexec_b64 s[26:27], s[2:3]
	s_cbranch_execz .LBB0_650
	s_waitcnt lgkmcnt(0)
	v_add_f32_e32 v32, v32, v33
	v_fma_f32 v32, v32, s54, 0.5
	v_trunc_f32_e32 v32, v32
	v_mul_f32_e32 v33, 0x2f800000, v32
	v_floor_f32_e32 v33, v33
	v_fmac_f32_e32 v32, 0xcf800000, v33
	v_cvt_u32_f32_e32 v32, v32
	v_cvt_u32_f32_e32 v33, v33
	v_lshl_add_u64 v[34:35], v[96:97], 3, s[10:11]
	v_mov_b32_e32 v248, v32
	v_mov_b32_e32 v249, v33
.LBB0_650:
	s_or_b64 exec, exec, s[26:27]
	s_waitcnt lgkmcnt(0)
	v_mov_b32_e32 v32, v242
	v_mov_b32_e32 v33, v243
	v_lshlrev_b32_e32 v36, 16, v76
	v_and_b32_e32 v37, 0xffff0000, v76
	v_lshlrev_b32_e32 v38, 16, v77
	v_and_b32_e32 v39, 0xffff0000, v77
	v_lshlrev_b32_e32 v48, 16, v74
	v_and_b32_e32 v49, 0xffff0000, v74
	v_lshlrev_b32_e32 v40, 16, v78
	v_and_b32_e32 v41, 0xffff0000, v78
	v_lshlrev_b32_e32 v42, 16, v79
	v_and_b32_e32 v43, 0xffff0000, v79
	v_lshlrev_b32_e32 v50, 16, v75
	v_and_b32_e32 v51, 0xffff0000, v75
	v_pk_add_f32 v[30:31], v[30:31], v[38:39]
	v_pk_add_f32 v[28:29], v[28:29], v[36:37]
	v_pk_add_f32 v[38:39], v[16:17], v[48:49]
	v_cvt_pk_bf16_f32 v16, v28, v29
	v_pk_add_f32 v[26:27], v[26:27], v[42:43]
	v_pk_add_f32 v[24:25], v[24:25], v[40:41]
	v_pk_add_f32 v[36:37], v[18:19], v[50:51]
	v_cvt_pk_bf16_f32 v17, v30, v31
	v_cvt_pk_bf16_f32 v18, v24, v25
	v_cvt_pk_bf16_f32 v19, v26, v27
	global_store_dwordx4 v[94:95], v[16:19], off
	v_mul_f32_e32 v40, v29, v29
	v_mul_f32_e32 v41, v31, v31
	v_mul_f32_e32 v42, v25, v25
	v_fmac_f32_e32 v40, v28, v28
	v_fmac_f32_e32 v41, v30, v30
	v_mul_f32_e32 v43, v27, v27
	v_fmac_f32_e32 v42, v24, v24
	v_fmac_f32_e32 v43, v26, v26
	v_lshlrev_b64 v[34:35], 12, v[92:93]
	v_lshlrev_b32_e32 v44, 16, v72
	v_and_b32_e32 v45, 0xffff0000, v72
	v_lshl_add_u64 v[34:35], v[34:35], 0, v[168:169]
	v_lshlrev_b32_e32 v46, 16, v73
	v_and_b32_e32 v47, 0xffff0000, v73
	v_pk_add_f32 v[20:21], v[20:21], v[44:45]
	v_lshl_add_u64 v[34:35], s[12:13], 0, v[34:35]
	v_pk_add_f32 v[22:23], v[22:23], v[46:47]
	s_waitcnt vmcnt(13)
	v_ffbh_u32_e32 v16, v33
	v_min_u32_e32 v18, 32, v16
	v_lshlrev_b64 v[16:17], v18, v[32:33]
	v_min_u32_e32 v16, 1, v16
	v_or_b32_e32 v16, v17, v16
	v_cvt_f32_u32_e32 v16, v16
	v_sub_u32_e32 v17, 32, v18
	v_ldexp_f32 v16, v16, v17
	v_fmamk_f32 v16, v16, 0x2f800000, v196
	v_rsq_f32_e32 v16, v16
	v_add_f32_e32 v17, v40, v41
	v_add_f32_e32 v17, v42, v17
	v_add_f32_e32 v32, v43, v17
	v_mul_f32_e32 v33, 0x41b56db7, v16
	v_mul_f32_e32 v16, v28, v33
	v_mul_f32_e32 v17, v29, v33
	v_mul_f32_e32 v19, v31, v33
	v_mul_f32_e32 v25, v25, v33
	v_mul_f32_e32 v18, v30, v33
	v_mul_f32_e32 v24, v24, v33
	v_mul_f32_e32 v26, v26, v33
	v_mul_f32_e32 v27, v27, v33
	v_med3_f32 v16, v16, s52, v198
	v_med3_f32 v17, v17, s52, v198
	v_med3_f32 v19, v19, s52, v198
	v_med3_f32 v25, v25, s52, v198
	v_med3_f32 v18, v18, s52, v198
	v_med3_f32 v24, v24, s52, v198
	v_med3_f32 v26, v26, s52, v198
	v_med3_f32 v27, v27, s52, v198
	v_rndne_f32_e32 v16, v16
	v_rndne_f32_e32 v17, v17
	v_rndne_f32_e32 v19, v19
	v_rndne_f32_e32 v25, v25
	v_rndne_f32_e32 v18, v18
	v_rndne_f32_e32 v24, v24
	v_rndne_f32_e32 v26, v26
	v_rndne_f32_e32 v27, v27
	v_cvt_i32_f32_e32 v16, v16
	v_cvt_i32_f32_e32 v17, v17
	v_cvt_i32_f32_e32 v19, v19
	v_cvt_i32_f32_e32 v25, v25
	v_cvt_i32_f32_sdwa v18, v18 dst_sel:WORD_1 dst_unused:UNUSED_PAD src0_sel:DWORD
	v_cvt_i32_f32_e32 v24, v24
	v_cvt_i32_f32_sdwa v26, v26 dst_sel:WORD_1 dst_unused:UNUSED_PAD src0_sel:DWORD
	v_cvt_i32_f32_e32 v27, v27
	v_lshlrev_b32_e32 v17, 8, v17
	v_perm_b32 v16, v19, v16, s53
	v_lshlrev_b32_e32 v19, 8, v25
	v_and_b32_e32 v18, 0xff0000, v18
	v_and_b32_e32 v25, 0xff0000, v26
	v_perm_b32 v24, v27, v24, s53
	v_and_b32_e32 v17, 0xff00, v17
	v_and_b32_e32 v19, 0xff00, v19
	v_or3_b32 v16, v16, v17, v18
	v_or3_b32 v17, v24, v19, v25
	v_mul_f32_e32 v29, v21, v33
	global_store_dwordx2 v[34:35], v[16:17], off
	v_cvt_pk_bf16_f32 v16, v20, v21
	v_cvt_pk_bf16_f32 v17, v22, v23
	v_mul_f32_e32 v28, v20, v33
	v_mul_f32_e32 v30, v22, v33
	v_mul_f32_e32 v31, v23, v33
	v_cvt_pk_bf16_f32 v18, v38, v39
	v_cvt_pk_bf16_f32 v19, v36, v37
	global_store_dwordx4 v[94:95], v[16:19], off offset:256
	v_med3_f32 v28, v28, s52, v198
	v_mul_f32_e32 v24, v37, v33
	v_med3_f32 v17, v29, s52, v198
	v_rndne_f32_e32 v17, v17
	v_med3_f32 v18, v30, s52, v198
	v_med3_f32 v19, v31, s52, v198
	v_rndne_f32_e32 v16, v28
	v_cvt_i32_f32_e32 v17, v17
	v_rndne_f32_e32 v18, v18
	v_rndne_f32_e32 v19, v19
	v_cvt_i32_f32_e32 v16, v16
	v_cvt_i32_f32_sdwa v18, v18 dst_sel:WORD_1 dst_unused:UNUSED_PAD src0_sel:DWORD
	v_cvt_i32_f32_e32 v19, v19
	v_lshlrev_b32_e32 v17, 8, v17
	v_and_b32_e32 v17, 0xff00, v17
	v_and_b32_e32 v18, 0xff0000, v18
	v_perm_b32 v16, v19, v16, s53
	v_or3_b32 v18, v16, v17, v18
	v_mul_f32_e32 v17, v39, v33
	v_med3_f32 v17, v17, s52, v198
	v_rndne_f32_e32 v17, v17
	v_cvt_i32_f32_e32 v17, v17
	v_mul_f32_e32 v16, v38, v33
	v_med3_f32 v16, v16, s52, v198
	v_rndne_f32_e32 v16, v16
	v_mul_f32_e32 v19, v36, v33
	v_cvt_i32_f32_e32 v25, v16
	v_lshlrev_b32_e32 v16, 8, v17
	v_and_b32_e32 v26, 0xff00, v16
	v_med3_f32 v16, v19, s52, v198
	v_mul_f32_e32 v17, v21, v21
	v_mul_f32_e32 v19, v23, v23
	v_fmac_f32_e32 v17, v20, v20
	v_fmac_f32_e32 v19, v22, v22
	v_add_f32_e32 v17, v17, v19
	v_mul_f32_e32 v19, v39, v39
	v_fmac_f32_e32 v19, v38, v38
	v_add_f32_e32 v17, v19, v17
	v_mul_f32_e32 v19, v37, v37
	v_fmac_f32_e32 v19, v36, v36
	v_add_f32_e32 v17, v19, v17
	v_add_f32_e32 v17, v32, v17
	ds_bpermute_b32 v19, v116, v17
	v_rndne_f32_e32 v16, v16
	v_cvt_i32_f32_sdwa v20, v16 dst_sel:WORD_1 dst_unused:UNUSED_PAD src0_sel:DWORD
	v_med3_f32 v16, v24, s52, v198
	v_rndne_f32_e32 v16, v16
	v_cvt_i32_f32_e32 v21, v16
	s_waitcnt lgkmcnt(0)
	v_add_f32_e32 v16, v17, v19
	ds_bpermute_b32 v17, v117, v16
	v_and_b32_e32 v19, 0xff0000, v20
	v_perm_b32 v20, v21, v25, s53
	v_or3_b32 v19, v20, v26, v19
	global_store_dwordx2 v[34:35], v[18:19], off offset:128
	s_and_saveexec_b64 s[26:27], s[2:3]
	s_cbranch_execz .LBB0_652
	s_waitcnt lgkmcnt(0)
	v_add_f32_e32 v16, v16, v17
	v_fma_f32 v16, v16, s54, 0.5
	v_trunc_f32_e32 v16, v16
	v_mul_f32_e32 v17, 0x2f800000, v16
	v_floor_f32_e32 v17, v17
	v_fmac_f32_e32 v16, 0xcf800000, v17
	v_cvt_u32_f32_e32 v16, v16
	v_cvt_u32_f32_e32 v17, v17
	v_lshl_add_u64 v[18:19], v[92:93], 3, s[10:11]
	v_mov_b32_e32 v250, v16
	v_mov_b32_e32 v251, v17
.LBB0_652:
	s_or_b64 exec, exec, s[26:27]
	s_waitcnt lgkmcnt(0)
	v_mov_b32_e32 v16, v244
	v_mov_b32_e32 v17, v245
	v_lshlrev_b32_e32 v20, 16, v68
	v_and_b32_e32 v21, 0xffff0000, v68
	v_lshlrev_b32_e32 v22, 16, v69
	v_and_b32_e32 v23, 0xffff0000, v69
	v_lshlrev_b32_e32 v32, 16, v66
	v_and_b32_e32 v33, 0xffff0000, v66
	v_lshlrev_b32_e32 v24, 16, v70
	v_and_b32_e32 v25, 0xffff0000, v70
	v_lshlrev_b32_e32 v26, 16, v71
	v_and_b32_e32 v27, 0xffff0000, v71
	v_lshlrev_b32_e32 v34, 16, v67
	v_and_b32_e32 v35, 0xffff0000, v67
	v_pk_add_f32 v[14:15], v[14:15], v[22:23]
	v_pk_add_f32 v[12:13], v[12:13], v[20:21]
	v_pk_add_f32 v[22:23], v[0:1], v[32:33]
	v_cvt_pk_bf16_f32 v0, v12, v13
	v_pk_add_f32 v[10:11], v[10:11], v[26:27]
	v_pk_add_f32 v[8:9], v[8:9], v[24:25]
	v_pk_add_f32 v[20:21], v[2:3], v[34:35]
	v_cvt_pk_bf16_f32 v1, v14, v15
	v_cvt_pk_bf16_f32 v2, v8, v9
	v_cvt_pk_bf16_f32 v3, v10, v11
	global_store_dwordx4 v[90:91], v[0:3], off
	v_mul_f32_e32 v24, v13, v13
	v_mul_f32_e32 v25, v15, v15
	v_mul_f32_e32 v26, v9, v9
	v_fmac_f32_e32 v24, v12, v12
	v_fmac_f32_e32 v25, v14, v14
	v_mul_f32_e32 v27, v11, v11
	v_fmac_f32_e32 v26, v8, v8
	v_fmac_f32_e32 v27, v10, v10
	v_lshlrev_b64 v[18:19], 12, v[88:89]
	v_lshlrev_b32_e32 v28, 16, v64
	v_and_b32_e32 v29, 0xffff0000, v64
	v_lshl_add_u64 v[18:19], v[18:19], 0, v[168:169]
	v_lshlrev_b32_e32 v30, 16, v65
	v_and_b32_e32 v31, 0xffff0000, v65
	v_pk_add_f32 v[4:5], v[4:5], v[28:29]
	v_lshl_add_u64 v[18:19], s[12:13], 0, v[18:19]
	v_pk_add_f32 v[6:7], v[6:7], v[30:31]
	s_waitcnt vmcnt(17)
	v_ffbh_u32_e32 v0, v17
	v_min_u32_e32 v2, 32, v0
	v_lshlrev_b64 v[0:1], v2, v[16:17]
	v_min_u32_e32 v0, 1, v0
	v_or_b32_e32 v0, v1, v0
	v_cvt_f32_u32_e32 v0, v0
	v_sub_u32_e32 v1, 32, v2
	v_ldexp_f32 v0, v0, v1
	v_fmamk_f32 v0, v0, 0x2f800000, v196
	v_rsq_f32_e32 v0, v0
	v_add_f32_e32 v1, v24, v25
	v_add_f32_e32 v1, v26, v1
	v_add_f32_e32 v16, v27, v1
	v_mul_f32_e32 v17, 0x41b56db7, v0
	v_mul_f32_e32 v0, v12, v17
	v_mul_f32_e32 v1, v13, v17
	v_mul_f32_e32 v3, v15, v17
	v_mul_f32_e32 v9, v9, v17
	v_mul_f32_e32 v2, v14, v17
	v_mul_f32_e32 v8, v8, v17
	v_mul_f32_e32 v10, v10, v17
	v_mul_f32_e32 v11, v11, v17
	v_med3_f32 v0, v0, s52, v198
	v_med3_f32 v1, v1, s52, v198
	v_med3_f32 v3, v3, s52, v198
	v_med3_f32 v9, v9, s52, v198
	v_med3_f32 v2, v2, s52, v198
	v_med3_f32 v8, v8, s52, v198
	v_med3_f32 v10, v10, s52, v198
	v_med3_f32 v11, v11, s52, v198
	v_rndne_f32_e32 v0, v0
	v_rndne_f32_e32 v1, v1
	v_rndne_f32_e32 v3, v3
	v_rndne_f32_e32 v9, v9
	v_rndne_f32_e32 v2, v2
	v_rndne_f32_e32 v8, v8
	v_rndne_f32_e32 v10, v10
	v_rndne_f32_e32 v11, v11
	v_cvt_i32_f32_e32 v0, v0
	v_cvt_i32_f32_e32 v1, v1
	v_cvt_i32_f32_e32 v3, v3
	v_cvt_i32_f32_e32 v9, v9
	v_cvt_i32_f32_sdwa v2, v2 dst_sel:WORD_1 dst_unused:UNUSED_PAD src0_sel:DWORD
	v_cvt_i32_f32_e32 v8, v8
	v_cvt_i32_f32_sdwa v10, v10 dst_sel:WORD_1 dst_unused:UNUSED_PAD src0_sel:DWORD
	v_cvt_i32_f32_e32 v11, v11
	v_lshlrev_b32_e32 v1, 8, v1
	v_perm_b32 v0, v3, v0, s53
	v_lshlrev_b32_e32 v3, 8, v9
	v_and_b32_e32 v2, 0xff0000, v2
	v_and_b32_e32 v9, 0xff0000, v10
	v_perm_b32 v8, v11, v8, s53
	v_and_b32_e32 v1, 0xff00, v1
	v_and_b32_e32 v3, 0xff00, v3
	v_or3_b32 v0, v0, v1, v2
	v_or3_b32 v1, v8, v3, v9
	v_mul_f32_e32 v13, v5, v17
	global_store_dwordx2 v[18:19], v[0:1], off
	v_cvt_pk_bf16_f32 v0, v4, v5
	v_cvt_pk_bf16_f32 v1, v6, v7
	v_mul_f32_e32 v12, v4, v17
	v_mul_f32_e32 v14, v6, v17
	v_mul_f32_e32 v15, v7, v17
	v_cvt_pk_bf16_f32 v2, v22, v23
	v_cvt_pk_bf16_f32 v3, v20, v21
	global_store_dwordx4 v[90:91], v[0:3], off offset:256
	v_med3_f32 v12, v12, s52, v198
	v_mul_f32_e32 v8, v21, v17
	v_med3_f32 v1, v13, s52, v198
	v_rndne_f32_e32 v1, v1
	v_med3_f32 v2, v14, s52, v198
	v_med3_f32 v3, v15, s52, v198
	v_rndne_f32_e32 v0, v12
	v_cvt_i32_f32_e32 v1, v1
	v_rndne_f32_e32 v2, v2
	v_rndne_f32_e32 v3, v3
	v_cvt_i32_f32_e32 v0, v0
	v_cvt_i32_f32_sdwa v2, v2 dst_sel:WORD_1 dst_unused:UNUSED_PAD src0_sel:DWORD
	v_cvt_i32_f32_e32 v3, v3
	v_lshlrev_b32_e32 v1, 8, v1
	v_and_b32_e32 v1, 0xff00, v1
	v_and_b32_e32 v2, 0xff0000, v2
	v_perm_b32 v0, v3, v0, s53
	v_or3_b32 v2, v0, v1, v2
	v_mul_f32_e32 v1, v23, v17
	v_med3_f32 v1, v1, s52, v198
	v_rndne_f32_e32 v1, v1
	v_cvt_i32_f32_e32 v1, v1
	v_mul_f32_e32 v0, v22, v17
	v_med3_f32 v0, v0, s52, v198
	v_rndne_f32_e32 v0, v0
	v_mul_f32_e32 v3, v20, v17
	v_cvt_i32_f32_e32 v9, v0
	v_lshlrev_b32_e32 v0, 8, v1
	v_and_b32_e32 v10, 0xff00, v0
	v_med3_f32 v0, v3, s52, v198
	v_mul_f32_e32 v1, v5, v5
	v_mul_f32_e32 v3, v7, v7
	v_fmac_f32_e32 v1, v4, v4
	v_fmac_f32_e32 v3, v6, v6
	v_add_f32_e32 v1, v1, v3
	v_mul_f32_e32 v3, v23, v23
	v_fmac_f32_e32 v3, v22, v22
	v_add_f32_e32 v1, v3, v1
	v_mul_f32_e32 v3, v21, v21
	v_fmac_f32_e32 v3, v20, v20
	v_add_f32_e32 v1, v3, v1
	v_add_f32_e32 v1, v16, v1
	ds_bpermute_b32 v3, v116, v1
	v_rndne_f32_e32 v0, v0
	v_cvt_i32_f32_sdwa v4, v0 dst_sel:WORD_1 dst_unused:UNUSED_PAD src0_sel:DWORD
	v_med3_f32 v0, v8, s52, v198
	v_rndne_f32_e32 v0, v0
	v_cvt_i32_f32_e32 v5, v0
	s_waitcnt lgkmcnt(0)
	v_add_f32_e32 v0, v1, v3
	ds_bpermute_b32 v1, v117, v0
	v_and_b32_e32 v3, 0xff0000, v4
	v_perm_b32 v4, v5, v9, s53
	v_or3_b32 v3, v4, v10, v3
	global_store_dwordx2 v[18:19], v[2:3], off offset:128
	s_and_saveexec_b64 s[26:27], s[2:3]
	s_cbranch_execz .LBB0_654
	s_waitcnt lgkmcnt(0)
	v_add_f32_e32 v0, v0, v1
	v_fma_f32 v0, v0, s54, 0.5
	v_trunc_f32_e32 v0, v0
	v_mul_f32_e32 v1, 0x2f800000, v0
	v_floor_f32_e32 v1, v1
	v_fmac_f32_e32 v0, 0xcf800000, v1
	v_cvt_u32_f32_e32 v0, v0
	v_cvt_u32_f32_e32 v1, v1
	v_lshl_add_u64 v[2:3], v[88:89], 3, s[10:11]
	v_mov_b32_e32 v252, v0
	v_mov_b32_e32 v253, v1

.LBB0_1258:
	v_lshl_add_u32 v30, s28, 8, v190
	v_lshl_or_b32 v24, s30, 8, v192
	v_ashrrev_i32_e32 v25, 31, v24
	v_ashrrev_i32_e32 v31, 31, v30
	s_nop 7
	s_nop 7
	s_nop 7
	v_lshl_add_u64 v[28:29], v[24:25], 1, s[6:7]
	v_lshlrev_b64 v[0:1], 13, v[30:31]
	v_lshl_add_u64 v[26:27], v[30:31], 3, s[12:13]
	v_lshl_add_u64 v[188:189], v[28:29], 0, v[0:1]
	global_load_dwordx2 v[208:209], v[26:27], off
	global_load_dwordx2 v[232:233], v[26:27], off offset:128
	global_load_dwordx2 v[234:235], v[26:27], off offset:256
	global_load_dwordx2 v[236:237], v[26:27], off offset:384
	global_load_dwordx2 v[238:239], v[26:27], off offset:1024
	global_load_dwordx2 v[240:241], v[26:27], off offset:1152
	global_load_dwordx2 v[242:243], v[26:27], off offset:1280
	global_load_dwordx2 v[244:245], v[26:27], off offset:1408
	global_load_dwordx4 v[200:203], v[188:189], off
	v_or_b32_e32 v184, 16, v30
	v_or_b32_e32 v180, 32, v30
	v_or_b32_e32 v176, 48, v30
	v_ashrrev_i32_e32 v185, 31, v184
	v_ashrrev_i32_e32 v181, 31, v180
	v_ashrrev_i32_e32 v177, 31, v176
	v_lshlrev_b64 v[0:1], 12, v[30:31]
	v_lshlrev_b64 v[2:3], 13, v[184:185]
	v_lshlrev_b64 v[4:5], 13, v[180:181]
	v_lshlrev_b64 v[6:7], 13, v[176:177]
	v_lshl_add_u64 v[0:1], v[0:1], 0, v[24:25]
	v_lshl_add_u64 v[186:187], v[28:29], 0, v[2:3]
	v_lshl_add_u64 v[182:183], v[28:29], 0, v[4:5]
	v_lshl_add_u64 v[178:179], v[28:29], 0, v[6:7]
	v_lshl_add_u64 v[210:211], s[10:11], 0, v[0:1]
	global_load_dwordx4 v[204:207], v[188:189], off offset:256
	global_load_dwordx4 v[20:23], v[186:187], off
	global_load_dwordx4 v[16:19], v[186:187], off offset:256
	global_load_dwordx4 v[12:15], v[182:183], off
	global_load_dwordx4 v[8:11], v[182:183], off offset:256
	global_load_dwordx4 v[4:7], v[178:179], off
	global_load_dwordx4 v[0:3], v[178:179], off offset:256
	s_waitcnt vmcnt(0)
	v_ffbh_u32_e32 v216, v209
	v_min_u32_e32 v216, 32, v216
	v_lshlrev_b64 v[208:209], v216, v[208:209]
	v_min_u32_e32 v208, 1, v208
	v_or_b32_e32 v208, v209, v208
	v_cvt_f32_u32_e32 v208, v208
	v_lshlrev_b32_e32 v212, 16, v200
	v_and_b32_e32 v213, 0xffff0000, v200
	v_lshlrev_b32_e32 v200, 16, v201
	v_and_b32_e32 v201, 0xffff0000, v201
	v_lshlrev_b32_e32 v214, 16, v202
	v_and_b32_e32 v215, 0xffff0000, v202
	v_lshlrev_b32_e32 v202, 16, v203
	v_and_b32_e32 v203, 0xffff0000, v203
	v_pk_fma_f32 v[158:159], v[158:159], s[18:19], v[200:201] op_sel_hi:[1,0,1]
	v_pk_fma_f32 v[156:157], v[156:157], s[18:19], v[212:213] op_sel_hi:[1,0,1]
	v_pk_fma_f32 v[200:201], v[154:155], s[18:19], v[202:203] op_sel_hi:[1,0,1]
	v_pk_fma_f32 v[202:203], v[152:153], s[18:19], v[214:215] op_sel_hi:[1,0,1]
	v_sub_u32_e32 v212, 32, v216
	v_cvt_pk_bf16_f32 v152, v156, v157
	v_cvt_pk_bf16_f32 v153, v158, v159
	v_cvt_pk_bf16_f32 v154, v202, v203
	v_cvt_pk_bf16_f32 v155, v200, v201
	global_store_dwordx4 v[188:189], v[152:155], off
	v_mul_f32_e32 v213, v157, v157
	v_mul_f32_e32 v214, v159, v159
	v_ldexp_f32 v152, v208, v212
	v_fmamk_f32 v152, v152, 0x2f800000, v197
	v_rsq_f32_e32 v152, v152
	v_mul_f32_e32 v209, v203, v203
	v_fmac_f32_e32 v213, v156, v156
	v_fmac_f32_e32 v214, v158, v158
	v_mul_f32_e32 v208, 0x41fe0000, v152
	v_mul_f32_e32 v152, v208, v156
	v_mul_f32_e32 v153, v208, v157
	v_mul_f32_e32 v155, v208, v158
	v_mul_f32_e32 v156, v208, v159
	v_mul_f32_e32 v158, v208, v203
	v_fmac_f32_e32 v209, v202, v202
	v_mul_f32_e32 v157, v208, v202
	v_mul_f32_e32 v159, v208, v200
	v_mul_f32_e32 v202, v208, v201
	v_med3_f32 v152, v152, s53, v199
	v_med3_f32 v153, v153, s53, v199
	v_med3_f32 v156, v156, s53, v199
	v_med3_f32 v158, v158, s53, v199
	v_med3_f32 v155, v155, s53, v199
	v_med3_f32 v157, v157, s53, v199
	v_med3_f32 v159, v159, s53, v199
	v_med3_f32 v202, v202, s53, v199
	v_rndne_f32_e32 v152, v152
	v_rndne_f32_e32 v153, v153
	v_rndne_f32_e32 v156, v156
	v_rndne_f32_e32 v158, v158
	v_rndne_f32_e32 v155, v155
	v_rndne_f32_e32 v157, v157
	v_rndne_f32_e32 v159, v159
	v_rndne_f32_e32 v202, v202
	v_cvt_i32_f32_e32 v152, v152
	v_cvt_i32_f32_e32 v153, v153
	v_cvt_i32_f32_e32 v156, v156
	v_cvt_i32_f32_e32 v158, v158
	v_cvt_i32_f32_sdwa v155, v155 dst_sel:WORD_1 dst_unused:UNUSED_PAD src0_sel:DWORD
	v_cvt_i32_f32_e32 v157, v157
	v_cvt_i32_f32_sdwa v159, v159 dst_sel:WORD_1 dst_unused:UNUSED_PAD src0_sel:DWORD
	v_cvt_i32_f32_e32 v202, v202
	v_lshlrev_b32_e32 v153, 8, v153
	v_perm_b32 v152, v156, v152, s54
	v_lshlrev_b32_e32 v156, 8, v158
	v_and_b32_e32 v155, 0xff0000, v155
	v_and_b32_e32 v158, 0xff0000, v159
	v_perm_b32 v157, v202, v157, s54
	v_and_b32_e32 v153, 0xff00, v153
	v_and_b32_e32 v156, 0xff00, v156
	v_or3_b32 v152, v152, v153, v155
	v_or3_b32 v153, v157, v156, v158
	v_add_f32_e32 v154, v213, v214
	global_store_dwordx2 v[210:211], v[152:153], off
	v_mul_f32_e32 v153, v201, v201
	v_add_f32_e32 v152, v209, v154
	v_fmac_f32_e32 v153, v200, v200
	v_add_f32_e32 v200, v153, v152
	v_lshlrev_b32_e32 v152, 16, v204
	v_and_b32_e32 v153, 0xffff0000, v204
	v_lshlrev_b32_e32 v154, 16, v205
	v_and_b32_e32 v155, 0xffff0000, v205
	v_lshlrev_b32_e32 v156, 16, v206
	v_and_b32_e32 v157, 0xffff0000, v206
	v_lshlrev_b32_e32 v158, 16, v207
	v_and_b32_e32 v159, 0xffff0000, v207
	v_pk_fma_f32 v[150:151], v[150:151], s[18:19], v[154:155] op_sel_hi:[1,0,1]
	v_pk_fma_f32 v[148:149], v[148:149], s[18:19], v[152:153] op_sel_hi:[1,0,1]
	v_pk_fma_f32 v[154:155], v[144:145], s[18:19], v[156:157] op_sel_hi:[1,0,1]
	v_cvt_pk_bf16_f32 v144, v148, v149
	v_cvt_pk_bf16_f32 v145, v150, v151
	v_pk_fma_f32 v[152:153], v[146:147], s[18:19], v[158:159] op_sel_hi:[1,0,1]
	v_cvt_pk_bf16_f32 v146, v154, v155
	s_nop 0
	v_cvt_pk_bf16_f32 v147, v152, v153
	global_store_dwordx4 v[188:189], v[144:147], off offset:256
	s_nop 1
	v_mul_f32_e32 v145, v208, v149
	v_mul_f32_e32 v144, v208, v148
	v_mul_f32_e32 v146, v208, v150
	v_mul_f32_e32 v147, v208, v151
	v_med3_f32 v145, v145, s53, v199
	v_med3_f32 v144, v144, s53, v199
	v_rndne_f32_e32 v145, v145
	v_med3_f32 v146, v146, s53, v199
	v_med3_f32 v147, v147, s53, v199
	v_rndne_f32_e32 v144, v144
	v_cvt_i32_f32_e32 v145, v145
	v_rndne_f32_e32 v146, v146
	v_rndne_f32_e32 v147, v147
	v_cvt_i32_f32_e32 v144, v144
	v_cvt_i32_f32_sdwa v146, v146 dst_sel:WORD_1 dst_unused:UNUSED_PAD src0_sel:DWORD
	v_cvt_i32_f32_e32 v147, v147
	v_lshlrev_b32_e32 v145, 8, v145
	v_and_b32_e32 v145, 0xff00, v145
	v_and_b32_e32 v146, 0xff0000, v146
	v_perm_b32 v144, v147, v144, s54
	v_or3_b32 v156, v144, v145, v146
	v_mul_f32_e32 v145, v208, v155
	v_med3_f32 v145, v145, s53, v199
	v_rndne_f32_e32 v145, v145
	v_cvt_i32_f32_e32 v145, v145
	v_mul_f32_e32 v144, v208, v154
	v_med3_f32 v144, v144, s53, v199
	v_rndne_f32_e32 v144, v144
	v_mul_f32_e32 v146, v208, v152
	v_cvt_i32_f32_e32 v157, v144
	v_lshlrev_b32_e32 v144, 8, v145
	v_and_b32_e32 v158, 0xff00, v144
	v_med3_f32 v144, v146, s53, v199
	v_rndne_f32_e32 v145, v144
	v_mul_f32_e32 v144, v149, v149
	v_mul_f32_e32 v146, v151, v151
	v_fmac_f32_e32 v144, v148, v148
	v_fmac_f32_e32 v146, v150, v150
	v_add_f32_e32 v144, v144, v146
	v_mul_f32_e32 v146, v155, v155
	v_fmac_f32_e32 v146, v154, v154
	v_add_f32_e32 v144, v146, v144
	v_mul_f32_e32 v146, v153, v153
	v_fmac_f32_e32 v146, v152, v152
	v_add_f32_e32 v144, v146, v144
	v_and_b32_e32 v148, 64, v198
	v_add_f32_e32 v146, v200, v144
	v_xor_b32_e32 v144, 16, v198
	v_add_u32_e32 v148, 64, v148
	v_cmp_lt_i32_e32 vcc, v144, v148
	v_mul_f32_e32 v147, v208, v153
	v_cvt_i32_f32_sdwa v150, v145 dst_sel:WORD_1 dst_unused:UNUSED_PAD src0_sel:DWORD
	v_cndmask_b32_e32 v144, v198, v144, vcc
	v_lshlrev_b32_e32 v144, 2, v144
	ds_bpermute_b32 v149, v144, v146
	v_med3_f32 v145, v147, s53, v199
	v_rndne_f32_e32 v145, v145
	v_cvt_i32_f32_e32 v151, v145
	v_xor_b32_e32 v145, 32, v198
	v_cmp_lt_i32_e32 vcc, v145, v148
	s_waitcnt lgkmcnt(0)
	v_add_f32_e32 v146, v146, v149
	v_and_b32_e32 v148, 0xff0000, v150
	v_cndmask_b32_e32 v145, v198, v145, vcc
	v_lshlrev_b32_e32 v145, 2, v145
	ds_bpermute_b32 v147, v145, v146
	v_perm_b32 v149, v151, v157, s54
	v_or3_b32 v157, v149, v158, v148
	global_store_dwordx2 v[210:211], v[156:157], off offset:128
	s_and_saveexec_b64 s[28:29], s[2:3]
	s_cbranch_execz .LBB0_1260
	s_waitcnt lgkmcnt(0)
	v_add_f32_e32 v146, v146, v147
	v_fma_f32 v146, v146, s55, 0.5
	v_trunc_f32_e32 v146, v146
	v_mul_f32_e32 v147, 0x2f800000, v146
	v_floor_f32_e32 v147, v147
	v_fmac_f32_e32 v146, 0xcf800000, v147
	v_cvt_u32_f32_e32 v146, v146
	v_cvt_u32_f32_e32 v147, v147
	v_lshl_add_u64 v[148:149], v[30:31], 3, s[8:9]
	v_mov_b32_e32 v228, v148
	v_mov_b32_e32 v229, v149
	v_mov_b32_e32 v246, v146
	v_mov_b32_e32 v247, v147
.LBB0_1260:
	s_or_b64 exec, exec, s[28:29]
	s_waitcnt lgkmcnt(0)
	v_lshl_add_u64 v[146:147], v[184:185], 3, s[12:13]
	v_mov_b32_e32 v146, v232
	v_mov_b32_e32 v147, v233
	v_lshlrev_b32_e32 v150, 16, v20
	v_and_b32_e32 v151, 0xffff0000, v20
	v_lshlrev_b32_e32 v154, 16, v16
	v_and_b32_e32 v155, 0xffff0000, v16
	v_lshlrev_b32_e32 v16, 16, v17
	v_and_b32_e32 v17, 0xffff0000, v17
	v_lshlrev_b32_e32 v20, 16, v21
	v_and_b32_e32 v21, 0xffff0000, v21
	v_lshlrev_b32_e32 v152, 16, v22
	v_and_b32_e32 v153, 0xffff0000, v22
	v_lshlrev_b32_e32 v22, 16, v23
	v_and_b32_e32 v23, 0xffff0000, v23
	v_lshlrev_b32_e32 v156, 16, v18
	v_and_b32_e32 v157, 0xffff0000, v18
	v_lshlrev_b32_e32 v18, 16, v19
	v_and_b32_e32 v19, 0xffff0000, v19
	v_pk_fma_f32 v[140:141], v[140:141], s[18:19], v[150:151] op_sel_hi:[1,0,1]
	v_pk_fma_f32 v[134:135], v[134:135], s[18:19], v[16:17] op_sel_hi:[1,0,1]
	v_cvt_pk_bf16_f32 v16, v140, v141
	v_pk_fma_f32 v[20:21], v[142:143], s[18:19], v[20:21] op_sel_hi:[1,0,1]
	v_pk_fma_f32 v[22:23], v[138:139], s[18:19], v[22:23] op_sel_hi:[1,0,1]
	v_pk_fma_f32 v[136:137], v[136:137], s[18:19], v[152:153] op_sel_hi:[1,0,1]
	v_pk_fma_f32 v[130:131], v[130:131], s[18:19], v[18:19] op_sel_hi:[1,0,1]
	v_cvt_pk_bf16_f32 v17, v20, v21
	v_cvt_pk_bf16_f32 v18, v136, v137
	v_cvt_pk_bf16_f32 v19, v22, v23
	global_store_dwordx4 v[186:187], v[16:19], off
	v_lshlrev_b64 v[148:149], 12, v[184:185]
	v_mul_f32_e32 v31, v141, v141
	v_mul_f32_e32 v142, v21, v21
	v_lshl_add_u64 v[148:149], v[148:149], 0, v[24:25]
	v_mul_f32_e32 v143, v137, v137
	v_fmac_f32_e32 v31, v140, v140
	v_fmac_f32_e32 v142, v20, v20
	v_lshl_add_u64 v[138:139], s[10:11], 0, v[148:149]
	v_mul_f32_e32 v148, v23, v23
	v_fmac_f32_e32 v143, v136, v136
	v_fmac_f32_e32 v148, v22, v22
	v_pk_fma_f32 v[132:133], v[132:133], s[18:19], v[154:155] op_sel_hi:[1,0,1]
	v_pk_fma_f32 v[128:129], v[128:129], s[18:19], v[156:157] op_sel_hi:[1,0,1]
	v_ffbh_u32_e32 v16, v147
	v_min_u32_e32 v18, 32, v16
	v_lshlrev_b64 v[16:17], v18, v[146:147]
	v_min_u32_e32 v16, 1, v16
	v_or_b32_e32 v16, v17, v16
	v_cvt_f32_u32_e32 v16, v16
	v_sub_u32_e32 v17, 32, v18
	v_ldexp_f32 v16, v16, v17
	v_fmamk_f32 v16, v16, 0x2f800000, v197
	v_rsq_f32_e32 v16, v16
	v_add_f32_e32 v17, v31, v142
	v_add_f32_e32 v17, v143, v17
	v_add_f32_e32 v31, v148, v17
	v_mul_f32_e32 v142, 0x41fe0000, v16
	v_mul_f32_e32 v16, v140, v142
	v_mul_f32_e32 v17, v141, v142
	v_mul_f32_e32 v19, v21, v142
	v_mul_f32_e32 v21, v137, v142
	v_mul_f32_e32 v18, v20, v142
	v_mul_f32_e32 v20, v136, v142
	v_mul_f32_e32 v22, v22, v142
	v_mul_f32_e32 v23, v23, v142
	v_med3_f32 v16, v16, s53, v199
	v_med3_f32 v17, v17, s53, v199
	v_med3_f32 v19, v19, s53, v199
	v_med3_f32 v21, v21, s53, v199
	v_med3_f32 v18, v18, s53, v199
	v_med3_f32 v20, v20, s53, v199
	v_med3_f32 v22, v22, s53, v199
	v_med3_f32 v23, v23, s53, v199
	v_rndne_f32_e32 v16, v16
	v_rndne_f32_e32 v17, v17
	v_rndne_f32_e32 v19, v19
	v_rndne_f32_e32 v21, v21
	v_rndne_f32_e32 v18, v18
	v_rndne_f32_e32 v20, v20
	v_rndne_f32_e32 v22, v22
	v_rndne_f32_e32 v23, v23
	v_cvt_i32_f32_e32 v16, v16
	v_cvt_i32_f32_e32 v17, v17
	v_cvt_i32_f32_e32 v19, v19
	v_cvt_i32_f32_e32 v21, v21
	v_cvt_i32_f32_sdwa v18, v18 dst_sel:WORD_1 dst_unused:UNUSED_PAD src0_sel:DWORD
	v_cvt_i32_f32_e32 v20, v20
	v_cvt_i32_f32_sdwa v22, v22 dst_sel:WORD_1 dst_unused:UNUSED_PAD src0_sel:DWORD
	v_cvt_i32_f32_e32 v23, v23
	v_lshlrev_b32_e32 v17, 8, v17
	v_perm_b32 v16, v19, v16, s54
	v_lshlrev_b32_e32 v19, 8, v21
	v_and_b32_e32 v18, 0xff0000, v18
	v_and_b32_e32 v21, 0xff0000, v22
	v_perm_b32 v20, v23, v20, s54
	v_and_b32_e32 v17, 0xff00, v17
	v_and_b32_e32 v19, 0xff00, v19
	v_or3_b32 v16, v16, v17, v18
	v_or3_b32 v17, v20, v19, v21
	v_mul_f32_e32 v137, v133, v142
	global_store_dwordx2 v[138:139], v[16:17], off
	v_cvt_pk_bf16_f32 v16, v132, v133
	v_cvt_pk_bf16_f32 v17, v134, v135
	v_mul_f32_e32 v136, v132, v142
	v_mul_f32_e32 v140, v134, v142
	v_mul_f32_e32 v141, v135, v142
	v_cvt_pk_bf16_f32 v18, v128, v129
	v_cvt_pk_bf16_f32 v19, v130, v131
	global_store_dwordx4 v[186:187], v[16:19], off offset:256
	v_med3_f32 v136, v136, s53, v199
	v_mul_f32_e32 v20, v131, v142
	v_med3_f32 v17, v137, s53, v199
	v_rndne_f32_e32 v17, v17
	v_med3_f32 v18, v140, s53, v199
	v_med3_f32 v19, v141, s53, v199
	v_rndne_f32_e32 v16, v136
	v_cvt_i32_f32_e32 v17, v17
	v_rndne_f32_e32 v18, v18
	v_rndne_f32_e32 v19, v19
	v_cvt_i32_f32_e32 v16, v16
	v_cvt_i32_f32_sdwa v18, v18 dst_sel:WORD_1 dst_unused:UNUSED_PAD src0_sel:DWORD
	v_cvt_i32_f32_e32 v19, v19
	v_lshlrev_b32_e32 v17, 8, v17
	v_and_b32_e32 v17, 0xff00, v17
	v_and_b32_e32 v18, 0xff0000, v18
	v_perm_b32 v16, v19, v16, s54
	v_or3_b32 v18, v16, v17, v18
	v_mul_f32_e32 v17, v129, v142
	v_med3_f32 v17, v17, s53, v199
	v_rndne_f32_e32 v17, v17
	v_cvt_i32_f32_e32 v17, v17
	v_mul_f32_e32 v16, v128, v142
	v_med3_f32 v16, v16, s53, v199
	v_rndne_f32_e32 v16, v16
	v_mul_f32_e32 v19, v130, v142
	v_cvt_i32_f32_e32 v21, v16
	v_lshlrev_b32_e32 v16, 8, v17
	v_and_b32_e32 v22, 0xff00, v16
	v_med3_f32 v16, v19, s53, v199
	v_mul_f32_e32 v17, v133, v133
	v_mul_f32_e32 v19, v135, v135
	v_fmac_f32_e32 v17, v132, v132
	v_fmac_f32_e32 v19, v134, v134
	v_add_f32_e32 v17, v17, v19
	v_mul_f32_e32 v19, v129, v129
	v_fmac_f32_e32 v19, v128, v128
	v_add_f32_e32 v17, v19, v17
	v_mul_f32_e32 v19, v131, v131
	v_fmac_f32_e32 v19, v130, v130
	v_add_f32_e32 v17, v19, v17
	v_add_f32_e32 v17, v31, v17
	ds_bpermute_b32 v19, v144, v17
	v_rndne_f32_e32 v16, v16
	v_cvt_i32_f32_sdwa v23, v16 dst_sel:WORD_1 dst_unused:UNUSED_PAD src0_sel:DWORD
	v_med3_f32 v16, v20, s53, v199
	v_rndne_f32_e32 v16, v16
	v_cvt_i32_f32_e32 v20, v16
	s_waitcnt lgkmcnt(0)
	v_add_f32_e32 v16, v17, v19
	ds_bpermute_b32 v17, v145, v16
	v_and_b32_e32 v19, 0xff0000, v23
	v_perm_b32 v20, v20, v21, s54
	v_or3_b32 v19, v20, v22, v19
	global_store_dwordx2 v[138:139], v[18:19], off offset:128
	s_and_saveexec_b64 s[28:29], s[2:3]
	s_cbranch_execz .LBB0_1262
	s_waitcnt lgkmcnt(0)
	v_add_f32_e32 v16, v16, v17
	v_fma_f32 v16, v16, s55, 0.5
	v_trunc_f32_e32 v16, v16
	v_mul_f32_e32 v17, 0x2f800000, v16
	v_floor_f32_e32 v17, v17
	v_fmac_f32_e32 v16, 0xcf800000, v17
	v_cvt_u32_f32_e32 v16, v16
	v_cvt_u32_f32_e32 v17, v17
	v_lshl_add_u64 v[18:19], v[184:185], 3, s[8:9]
	v_mov_b32_e32 v248, v16
	v_mov_b32_e32 v249, v17
.LBB0_1262:
	s_or_b64 exec, exec, s[28:29]
	s_waitcnt lgkmcnt(0)
	v_lshl_add_u64 v[16:17], v[180:181], 3, s[12:13]
	v_mov_b32_e32 v16, v234
	v_mov_b32_e32 v17, v235
	v_lshlrev_b32_e32 v20, 16, v12
	v_and_b32_e32 v21, 0xffff0000, v12
	v_lshlrev_b32_e32 v128, 16, v8
	v_and_b32_e32 v129, 0xffff0000, v8
	v_lshlrev_b32_e32 v8, 16, v9
	v_and_b32_e32 v9, 0xffff0000, v9
	v_lshlrev_b32_e32 v12, 16, v13
	v_and_b32_e32 v13, 0xffff0000, v13
	v_lshlrev_b32_e32 v22, 16, v14
	v_and_b32_e32 v23, 0xffff0000, v14
	v_lshlrev_b32_e32 v14, 16, v15
	v_and_b32_e32 v15, 0xffff0000, v15
	v_lshlrev_b32_e32 v130, 16, v10
	v_and_b32_e32 v131, 0xffff0000, v10
	v_lshlrev_b32_e32 v10, 16, v11
	v_and_b32_e32 v11, 0xffff0000, v11
	v_pk_fma_f32 v[20:21], v[124:125], s[18:19], v[20:21] op_sel_hi:[1,0,1]
	v_pk_fma_f32 v[118:119], v[118:119], s[18:19], v[8:9] op_sel_hi:[1,0,1]
	v_cvt_pk_bf16_f32 v8, v20, v21
	v_pk_fma_f32 v[12:13], v[126:127], s[18:19], v[12:13] op_sel_hi:[1,0,1]
	v_pk_fma_f32 v[14:15], v[122:123], s[18:19], v[14:15] op_sel_hi:[1,0,1]
	v_pk_fma_f32 v[22:23], v[120:121], s[18:19], v[22:23] op_sel_hi:[1,0,1]
	v_pk_fma_f32 v[114:115], v[114:115], s[18:19], v[10:11] op_sel_hi:[1,0,1]
	v_cvt_pk_bf16_f32 v9, v12, v13
	v_cvt_pk_bf16_f32 v10, v22, v23
	v_cvt_pk_bf16_f32 v11, v14, v15
	global_store_dwordx4 v[182:183], v[8:11], off
	v_mul_f32_e32 v31, v21, v21
	v_mul_f32_e32 v120, v13, v13
	v_mul_f32_e32 v121, v23, v23
	v_fmac_f32_e32 v31, v20, v20
	v_fmac_f32_e32 v120, v12, v12
	v_mul_f32_e32 v122, v15, v15
	v_fmac_f32_e32 v121, v22, v22
	v_fmac_f32_e32 v122, v14, v14
	v_lshlrev_b64 v[18:19], 12, v[180:181]
	v_lshl_add_u64 v[18:19], v[18:19], 0, v[24:25]
	v_pk_fma_f32 v[116:117], v[116:117], s[18:19], v[128:129] op_sel_hi:[1,0,1]
	v_lshl_add_u64 v[18:19], s[10:11], 0, v[18:19]
	v_pk_fma_f32 v[112:113], v[112:113], s[18:19], v[130:131] op_sel_hi:[1,0,1]
	v_ffbh_u32_e32 v8, v17
	v_min_u32_e32 v10, 32, v8
	v_lshlrev_b64 v[8:9], v10, v[16:17]
	v_min_u32_e32 v8, 1, v8
	v_or_b32_e32 v8, v9, v8
	v_cvt_f32_u32_e32 v8, v8
	v_sub_u32_e32 v9, 32, v10
	v_ldexp_f32 v8, v8, v9
	v_fmamk_f32 v8, v8, 0x2f800000, v197
	v_rsq_f32_e32 v8, v8
	v_add_f32_e32 v9, v31, v120
	v_add_f32_e32 v9, v121, v9
	v_add_f32_e32 v16, v122, v9
	v_mul_f32_e32 v17, 0x41fe0000, v8
	v_mul_f32_e32 v8, v20, v17
	v_mul_f32_e32 v9, v21, v17
	v_mul_f32_e32 v11, v13, v17
	v_mul_f32_e32 v13, v23, v17
	v_mul_f32_e32 v10, v12, v17
	v_mul_f32_e32 v12, v22, v17
	v_mul_f32_e32 v14, v14, v17
	v_mul_f32_e32 v15, v15, v17
	v_med3_f32 v8, v8, s53, v199
	v_med3_f32 v9, v9, s53, v199
	v_med3_f32 v11, v11, s53, v199
	v_med3_f32 v13, v13, s53, v199
	v_med3_f32 v10, v10, s53, v199
	v_med3_f32 v12, v12, s53, v199
	v_med3_f32 v14, v14, s53, v199
	v_med3_f32 v15, v15, s53, v199
	v_rndne_f32_e32 v8, v8
	v_rndne_f32_e32 v9, v9
	v_rndne_f32_e32 v11, v11
	v_rndne_f32_e32 v13, v13
	v_rndne_f32_e32 v10, v10
	v_rndne_f32_e32 v12, v12
	v_rndne_f32_e32 v14, v14
	v_rndne_f32_e32 v15, v15
	v_cvt_i32_f32_e32 v8, v8
	v_cvt_i32_f32_e32 v9, v9
	v_cvt_i32_f32_e32 v11, v11
	v_cvt_i32_f32_e32 v13, v13
	v_cvt_i32_f32_sdwa v10, v10 dst_sel:WORD_1 dst_unused:UNUSED_PAD src0_sel:DWORD
	v_cvt_i32_f32_e32 v12, v12
	v_cvt_i32_f32_sdwa v14, v14 dst_sel:WORD_1 dst_unused:UNUSED_PAD src0_sel:DWORD
	v_cvt_i32_f32_e32 v15, v15
	v_lshlrev_b32_e32 v9, 8, v9
	v_perm_b32 v8, v11, v8, s54
	v_lshlrev_b32_e32 v11, 8, v13
	v_and_b32_e32 v10, 0xff0000, v10
	v_and_b32_e32 v13, 0xff0000, v14
	v_perm_b32 v12, v15, v12, s54
	v_and_b32_e32 v9, 0xff00, v9
	v_and_b32_e32 v11, 0xff00, v11
	v_or3_b32 v8, v8, v9, v10
	v_or3_b32 v9, v12, v11, v13
	v_mul_f32_e32 v21, v117, v17
	global_store_dwordx2 v[18:19], v[8:9], off
	v_cvt_pk_bf16_f32 v8, v116, v117
	v_cvt_pk_bf16_f32 v9, v118, v119
	v_mul_f32_e32 v20, v116, v17
	v_mul_f32_e32 v22, v118, v17
	v_mul_f32_e32 v23, v119, v17
	v_cvt_pk_bf16_f32 v10, v112, v113
	v_cvt_pk_bf16_f32 v11, v114, v115
	global_store_dwordx4 v[182:183], v[8:11], off offset:256
	v_med3_f32 v20, v20, s53, v199
	v_mul_f32_e32 v12, v115, v17
	v_med3_f32 v9, v21, s53, v199
	v_rndne_f32_e32 v9, v9
	v_med3_f32 v10, v22, s53, v199
	v_med3_f32 v11, v23, s53, v199
	v_rndne_f32_e32 v8, v20
	v_cvt_i32_f32_e32 v9, v9
	v_rndne_f32_e32 v10, v10
	v_rndne_f32_e32 v11, v11
	v_cvt_i32_f32_e32 v8, v8
	v_cvt_i32_f32_sdwa v10, v10 dst_sel:WORD_1 dst_unused:UNUSED_PAD src0_sel:DWORD
	v_cvt_i32_f32_e32 v11, v11
	v_lshlrev_b32_e32 v9, 8, v9
	v_and_b32_e32 v9, 0xff00, v9
	v_and_b32_e32 v10, 0xff0000, v10
	v_perm_b32 v8, v11, v8, s54
	v_or3_b32 v10, v8, v9, v10
	v_mul_f32_e32 v9, v113, v17
	v_med3_f32 v9, v9, s53, v199
	v_rndne_f32_e32 v9, v9
	v_cvt_i32_f32_e32 v9, v9
	v_mul_f32_e32 v8, v112, v17
	v_med3_f32 v8, v8, s53, v199
	v_rndne_f32_e32 v8, v8
	v_mul_f32_e32 v11, v114, v17
	v_cvt_i32_f32_e32 v13, v8
	v_lshlrev_b32_e32 v8, 8, v9
	v_and_b32_e32 v14, 0xff00, v8
	v_med3_f32 v8, v11, s53, v199
	v_mul_f32_e32 v9, v117, v117
	v_mul_f32_e32 v11, v119, v119
	v_fmac_f32_e32 v9, v116, v116
	v_fmac_f32_e32 v11, v118, v118
	v_add_f32_e32 v9, v9, v11
	v_mul_f32_e32 v11, v113, v113
	v_fmac_f32_e32 v11, v112, v112
	v_add_f32_e32 v9, v11, v9
	v_mul_f32_e32 v11, v115, v115
	v_fmac_f32_e32 v11, v114, v114
	v_add_f32_e32 v9, v11, v9
	v_add_f32_e32 v9, v16, v9
	ds_bpermute_b32 v11, v144, v9
	v_rndne_f32_e32 v8, v8
	v_cvt_i32_f32_sdwa v15, v8 dst_sel:WORD_1 dst_unused:UNUSED_PAD src0_sel:DWORD
	v_med3_f32 v8, v12, s53, v199
	v_rndne_f32_e32 v8, v8
	v_cvt_i32_f32_e32 v12, v8
	s_waitcnt lgkmcnt(0)
	v_add_f32_e32 v8, v9, v11
	ds_bpermute_b32 v9, v145, v8
	v_and_b32_e32 v11, 0xff0000, v15
	v_perm_b32 v12, v12, v13, s54
	v_or3_b32 v11, v12, v14, v11
	global_store_dwordx2 v[18:19], v[10:11], off offset:128
	s_and_saveexec_b64 s[28:29], s[2:3]
	s_cbranch_execz .LBB0_1264
	s_waitcnt lgkmcnt(0)
	v_add_f32_e32 v8, v8, v9
	v_fma_f32 v8, v8, s55, 0.5
	v_trunc_f32_e32 v8, v8
	v_mul_f32_e32 v9, 0x2f800000, v8
	v_floor_f32_e32 v9, v9
	v_fmac_f32_e32 v8, 0xcf800000, v9
	v_cvt_u32_f32_e32 v8, v8
	v_cvt_u32_f32_e32 v9, v9
	v_lshl_add_u64 v[10:11], v[180:181], 3, s[8:9]
	v_mov_b32_e32 v250, v8
	v_mov_b32_e32 v251, v9
.LBB0_1264:
	s_or_b64 exec, exec, s[28:29]
	s_waitcnt lgkmcnt(0)
	v_lshl_add_u64 v[8:9], v[176:177], 3, s[12:13]
	v_mov_b32_e32 v8, v236
	v_mov_b32_e32 v9, v237
	v_lshlrev_b32_e32 v12, 16, v4
	v_and_b32_e32 v13, 0xffff0000, v4
	v_lshlrev_b32_e32 v16, 16, v0
	v_and_b32_e32 v17, 0xffff0000, v0
	v_lshlrev_b32_e32 v0, 16, v1
	v_and_b32_e32 v1, 0xffff0000, v1
	v_lshlrev_b32_e32 v4, 16, v5
	v_and_b32_e32 v5, 0xffff0000, v5
	v_lshlrev_b32_e32 v14, 16, v6
	v_and_b32_e32 v15, 0xffff0000, v6
	v_lshlrev_b32_e32 v6, 16, v7
	v_and_b32_e32 v7, 0xffff0000, v7
	v_lshlrev_b32_e32 v18, 16, v2
	v_and_b32_e32 v19, 0xffff0000, v2
	v_lshlrev_b32_e32 v2, 16, v3
	v_and_b32_e32 v3, 0xffff0000, v3
	v_pk_fma_f32 v[12:13], v[108:109], s[18:19], v[12:13] op_sel_hi:[1,0,1]
	v_pk_fma_f32 v[20:21], v[102:103], s[18:19], v[0:1] op_sel_hi:[1,0,1]
	v_cvt_pk_bf16_f32 v0, v12, v13
	v_pk_fma_f32 v[4:5], v[110:111], s[18:19], v[4:5] op_sel_hi:[1,0,1]
	v_pk_fma_f32 v[6:7], v[106:107], s[18:19], v[6:7] op_sel_hi:[1,0,1]
	v_pk_fma_f32 v[14:15], v[104:105], s[18:19], v[14:15] op_sel_hi:[1,0,1]
	v_pk_fma_f32 v[22:23], v[98:99], s[18:19], v[2:3] op_sel_hi:[1,0,1]
	v_cvt_pk_bf16_f32 v1, v4, v5
	v_cvt_pk_bf16_f32 v2, v14, v15
	v_cvt_pk_bf16_f32 v3, v6, v7
	global_store_dwordx4 v[178:179], v[0:3], off
	v_pk_fma_f32 v[18:19], v[96:97], s[18:19], v[18:19] op_sel_hi:[1,0,1]
	v_mul_f32_e32 v31, v13, v13
	v_mul_f32_e32 v96, v5, v5
	v_mul_f32_e32 v97, v15, v15
	v_fmac_f32_e32 v31, v12, v12
	v_fmac_f32_e32 v96, v4, v4
	v_mul_f32_e32 v98, v7, v7
	v_fmac_f32_e32 v97, v14, v14
	v_fmac_f32_e32 v98, v6, v6
	v_lshlrev_b64 v[10:11], 12, v[176:177]
	v_lshl_add_u64 v[10:11], v[10:11], 0, v[24:25]
	v_pk_fma_f32 v[16:17], v[100:101], s[18:19], v[16:17] op_sel_hi:[1,0,1]
	v_lshl_add_u64 v[10:11], s[10:11], 0, v[10:11]
	v_ffbh_u32_e32 v0, v9
	v_min_u32_e32 v2, 32, v0
	v_lshlrev_b64 v[0:1], v2, v[8:9]
	v_min_u32_e32 v0, 1, v0
	v_or_b32_e32 v0, v1, v0
	v_cvt_f32_u32_e32 v0, v0
	v_sub_u32_e32 v1, 32, v2
	v_ldexp_f32 v0, v0, v1
	v_fmamk_f32 v0, v0, 0x2f800000, v197
	v_rsq_f32_e32 v0, v0
	v_add_f32_e32 v1, v31, v96
	v_add_f32_e32 v1, v97, v1
	v_add_f32_e32 v8, v98, v1
	v_mul_f32_e32 v9, 0x41fe0000, v0
	v_mul_f32_e32 v0, v12, v9
	v_mul_f32_e32 v1, v13, v9
	v_mul_f32_e32 v3, v5, v9
	v_mul_f32_e32 v5, v15, v9
	v_mul_f32_e32 v2, v4, v9
	v_mul_f32_e32 v4, v14, v9
	v_mul_f32_e32 v6, v6, v9
	v_mul_f32_e32 v7, v7, v9
	v_med3_f32 v0, v0, s53, v199
	v_med3_f32 v1, v1, s53, v199
	v_med3_f32 v3, v3, s53, v199
	v_med3_f32 v5, v5, s53, v199
	v_med3_f32 v2, v2, s53, v199
	v_med3_f32 v4, v4, s53, v199
	v_med3_f32 v6, v6, s53, v199
	v_med3_f32 v7, v7, s53, v199
	v_rndne_f32_e32 v0, v0
	v_rndne_f32_e32 v1, v1
	v_rndne_f32_e32 v3, v3
	v_rndne_f32_e32 v5, v5
	v_rndne_f32_e32 v2, v2
	v_rndne_f32_e32 v4, v4
	v_rndne_f32_e32 v6, v6
	v_rndne_f32_e32 v7, v7
	v_cvt_i32_f32_e32 v0, v0
	v_cvt_i32_f32_e32 v1, v1
	v_cvt_i32_f32_e32 v3, v3
	v_cvt_i32_f32_e32 v5, v5
	v_cvt_i32_f32_sdwa v2, v2 dst_sel:WORD_1 dst_unused:UNUSED_PAD src0_sel:DWORD
	v_cvt_i32_f32_e32 v4, v4
	v_cvt_i32_f32_sdwa v6, v6 dst_sel:WORD_1 dst_unused:UNUSED_PAD src0_sel:DWORD
	v_cvt_i32_f32_e32 v7, v7
	v_lshlrev_b32_e32 v1, 8, v1
	v_perm_b32 v0, v3, v0, s54
	v_lshlrev_b32_e32 v3, 8, v5
	v_and_b32_e32 v2, 0xff0000, v2
	v_and_b32_e32 v5, 0xff0000, v6
	v_perm_b32 v4, v7, v4, s54
	v_and_b32_e32 v1, 0xff00, v1
	v_and_b32_e32 v3, 0xff00, v3
	v_or3_b32 v0, v0, v1, v2
	v_or3_b32 v1, v4, v3, v5
	v_mul_f32_e32 v13, v17, v9
	global_store_dwordx2 v[10:11], v[0:1], off
	v_cvt_pk_bf16_f32 v0, v16, v17
	v_cvt_pk_bf16_f32 v1, v20, v21
	v_mul_f32_e32 v12, v16, v9
	v_mul_f32_e32 v14, v20, v9
	v_mul_f32_e32 v15, v21, v9
	v_cvt_pk_bf16_f32 v2, v18, v19
	v_cvt_pk_bf16_f32 v3, v22, v23
	global_store_dwordx4 v[178:179], v[0:3], off offset:256
	v_med3_f32 v12, v12, s53, v199
	v_mul_f32_e32 v4, v23, v9
	v_med3_f32 v1, v13, s53, v199
	v_rndne_f32_e32 v1, v1
	v_med3_f32 v2, v14, s53, v199
	v_med3_f32 v3, v15, s53, v199
	v_rndne_f32_e32 v0, v12
	v_cvt_i32_f32_e32 v1, v1
	v_rndne_f32_e32 v2, v2
	v_rndne_f32_e32 v3, v3
	v_cvt_i32_f32_e32 v0, v0
	v_cvt_i32_f32_sdwa v2, v2 dst_sel:WORD_1 dst_unused:UNUSED_PAD src0_sel:DWORD
	v_cvt_i32_f32_e32 v3, v3
	v_lshlrev_b32_e32 v1, 8, v1
	v_and_b32_e32 v1, 0xff00, v1
	v_and_b32_e32 v2, 0xff0000, v2
	v_perm_b32 v0, v3, v0, s54
	v_or3_b32 v2, v0, v1, v2
	v_mul_f32_e32 v1, v19, v9
	v_med3_f32 v1, v1, s53, v199
	v_rndne_f32_e32 v1, v1
	v_cvt_i32_f32_e32 v1, v1
	v_mul_f32_e32 v0, v18, v9
	v_med3_f32 v0, v0, s53, v199
	v_rndne_f32_e32 v0, v0
	v_mul_f32_e32 v3, v22, v9
	v_cvt_i32_f32_e32 v5, v0
	v_lshlrev_b32_e32 v0, 8, v1
	v_and_b32_e32 v6, 0xff00, v0
	v_med3_f32 v0, v3, s53, v199
	v_mul_f32_e32 v1, v17, v17
	v_mul_f32_e32 v3, v21, v21
	v_fmac_f32_e32 v1, v16, v16
	v_fmac_f32_e32 v3, v20, v20
	v_add_f32_e32 v1, v1, v3
	v_mul_f32_e32 v3, v19, v19
	v_fmac_f32_e32 v3, v18, v18
	v_add_f32_e32 v1, v3, v1
	v_mul_f32_e32 v3, v23, v23
	v_fmac_f32_e32 v3, v22, v22
	v_add_f32_e32 v1, v3, v1
	v_add_f32_e32 v1, v8, v1
	ds_bpermute_b32 v3, v144, v1
	v_rndne_f32_e32 v0, v0
	v_cvt_i32_f32_sdwa v7, v0 dst_sel:WORD_1 dst_unused:UNUSED_PAD src0_sel:DWORD
	v_med3_f32 v0, v4, s53, v199
	v_rndne_f32_e32 v0, v0
	v_cvt_i32_f32_e32 v4, v0
	s_waitcnt lgkmcnt(0)
	v_add_f32_e32 v0, v1, v3
	ds_bpermute_b32 v1, v145, v0
	v_and_b32_e32 v3, 0xff0000, v7
	v_perm_b32 v4, v4, v5, s54
	v_or3_b32 v3, v4, v6, v3
	global_store_dwordx2 v[10:11], v[2:3], off offset:128
	s_and_saveexec_b64 s[28:29], s[2:3]
	s_cbranch_execz .LBB0_1266
	s_waitcnt lgkmcnt(0)
	v_add_f32_e32 v0, v0, v1
	v_fma_f32 v0, v0, s55, 0.5
	v_trunc_f32_e32 v0, v0
	v_mul_f32_e32 v1, 0x2f800000, v0
	v_floor_f32_e32 v1, v1
	v_fmac_f32_e32 v0, 0xcf800000, v1
	v_cvt_u32_f32_e32 v0, v0
	v_cvt_u32_f32_e32 v1, v1
	v_lshl_add_u64 v[2:3], v[176:177], 3, s[8:9]
	v_mov_b32_e32 v252, v0
	v_mov_b32_e32 v253, v1
.LBB0_1266:
	s_or_b64 exec, exec, s[28:29]
	v_add_u32_e32 v104, 0x80, v30
	v_ashrrev_i32_e32 v105, 31, v104
	s_waitcnt lgkmcnt(0)
	v_lshlrev_b64 v[0:1], 13, v[104:105]
	v_lshl_add_u64 v[106:107], v[28:29], 0, v[0:1]
	v_mov_b32_e32 v116, v238
	v_mov_b32_e32 v117, v239
	global_load_dwordx4 v[108:111], v[106:107], off
	v_add_u32_e32 v100, 0x90, v30
	v_add_u32_e32 v96, 0xa0, v30
	v_add_u32_e32 v30, 0xb0, v30
	v_ashrrev_i32_e32 v101, 31, v100
	v_ashrrev_i32_e32 v97, 31, v96
	v_ashrrev_i32_e32 v31, 31, v30
	v_lshlrev_b64 v[0:1], 13, v[100:101]
	v_lshlrev_b64 v[2:3], 13, v[96:97]
	v_lshlrev_b64 v[4:5], 13, v[30:31]
	v_lshlrev_b64 v[6:7], 12, v[104:105]
	v_lshl_add_u64 v[102:103], v[28:29], 0, v[0:1]
	v_lshl_add_u64 v[98:99], v[28:29], 0, v[2:3]
	v_lshl_add_u64 v[28:29], v[28:29], 0, v[4:5]
	v_lshl_add_u64 v[118:119], v[6:7], 0, v[24:25]
	global_load_dwordx4 v[112:115], v[106:107], off offset:256
	global_load_dwordx4 v[20:23], v[102:103], off
	global_load_dwordx4 v[16:19], v[102:103], off offset:256
	global_load_dwordx4 v[12:15], v[98:99], off
	global_load_dwordx4 v[8:11], v[98:99], off offset:256
	global_load_dwordx4 v[4:7], v[28:29], off
	global_load_dwordx4 v[0:3], v[28:29], off offset:256
	s_and_saveexec_b64 s[96:97], s[2:3]
	global_atomic_add_x2 v[228:229], v[246:247], off
	global_atomic_add_x2 v[228:229], v[248:249], off offset:128
	global_atomic_add_x2 v[228:229], v[250:251], off offset:256
	global_atomic_add_x2 v[228:229], v[252:253], off offset:384
	s_mov_b64 exec, s[96:97]
	v_lshl_add_u64 v[118:119], s[10:11], 0, v[118:119]
	v_ffbh_u32_e32 v124, v117
	v_min_u32_e32 v124, 32, v124
	s_waitcnt vmcnt(11)
	v_lshlrev_b32_e32 v120, 16, v108
	v_and_b32_e32 v121, 0xffff0000, v108
	v_lshlrev_b32_e32 v108, 16, v109
	v_and_b32_e32 v109, 0xffff0000, v109
	v_lshlrev_b32_e32 v122, 16, v110
	v_and_b32_e32 v123, 0xffff0000, v110
	v_lshlrev_b32_e32 v110, 16, v111
	v_and_b32_e32 v111, 0xffff0000, v111
	v_lshlrev_b64 v[116:117], v124, v[116:117]
	v_pk_fma_f32 v[94:95], v[94:95], s[18:19], v[108:109] op_sel_hi:[1,0,1]
	v_pk_fma_f32 v[92:93], v[92:93], s[18:19], v[120:121] op_sel_hi:[1,0,1]
	v_pk_fma_f32 v[108:109], v[90:91], s[18:19], v[110:111] op_sel_hi:[1,0,1]
	v_pk_fma_f32 v[110:111], v[88:89], s[18:19], v[122:123] op_sel_hi:[1,0,1]
	v_cvt_pk_bf16_f32 v88, v92, v93
	v_min_u32_e32 v116, 1, v116
	v_cvt_pk_bf16_f32 v89, v94, v95
	v_cvt_pk_bf16_f32 v90, v110, v111
	v_cvt_pk_bf16_f32 v91, v108, v109
	global_store_dwordx4 v[106:107], v[88:91], off
	v_sub_u32_e32 v120, 32, v124
	v_mul_f32_e32 v121, v93, v93
	v_or_b32_e32 v88, v117, v116
	v_cvt_f32_u32_e32 v88, v88
	v_mul_f32_e32 v122, v95, v95
	v_mul_f32_e32 v123, v111, v111
	v_fmac_f32_e32 v121, v92, v92
	v_ldexp_f32 v88, v88, v120
	v_fmamk_f32 v88, v88, 0x2f800000, v197
	v_rsq_f32_e32 v88, v88
	v_fmac_f32_e32 v122, v94, v94
	v_mul_f32_e32 v124, v109, v109
	v_fmac_f32_e32 v123, v110, v110
	v_add_f32_e32 v89, v121, v122
	v_fmac_f32_e32 v124, v108, v108
	v_add_f32_e32 v89, v123, v89
	v_mul_f32_e32 v117, 0x41fe0000, v88
	v_add_f32_e32 v116, v124, v89
	v_mul_f32_e32 v88, v117, v92
	v_mul_f32_e32 v89, v117, v93
	v_mul_f32_e32 v91, v117, v95
	v_mul_f32_e32 v93, v117, v111
	v_mul_f32_e32 v90, v117, v94
	v_mul_f32_e32 v92, v117, v110
	v_mul_f32_e32 v94, v117, v108
	v_mul_f32_e32 v95, v117, v109
	v_med3_f32 v88, v88, s53, v199
	v_med3_f32 v89, v89, s53, v199
	v_med3_f32 v91, v91, s53, v199
	v_med3_f32 v93, v93, s53, v199
	v_med3_f32 v90, v90, s53, v199
	v_med3_f32 v92, v92, s53, v199
	v_med3_f32 v94, v94, s53, v199
	v_med3_f32 v95, v95, s53, v199
	v_rndne_f32_e32 v88, v88
	v_rndne_f32_e32 v89, v89
	v_rndne_f32_e32 v91, v91
	v_rndne_f32_e32 v93, v93
	v_rndne_f32_e32 v90, v90
	v_rndne_f32_e32 v92, v92
	v_rndne_f32_e32 v94, v94
	v_rndne_f32_e32 v95, v95
	v_cvt_i32_f32_e32 v88, v88
	v_cvt_i32_f32_e32 v89, v89
	v_cvt_i32_f32_e32 v91, v91
	v_cvt_i32_f32_e32 v93, v93
	v_cvt_i32_f32_sdwa v90, v90 dst_sel:WORD_1 dst_unused:UNUSED_PAD src0_sel:DWORD
	v_cvt_i32_f32_e32 v92, v92
	v_cvt_i32_f32_sdwa v94, v94 dst_sel:WORD_1 dst_unused:UNUSED_PAD src0_sel:DWORD
	v_cvt_i32_f32_e32 v95, v95
	v_lshlrev_b32_e32 v89, 8, v89
	v_perm_b32 v88, v91, v88, s54
	v_lshlrev_b32_e32 v91, 8, v93
	v_and_b32_e32 v90, 0xff0000, v90
	v_and_b32_e32 v93, 0xff0000, v94
	v_perm_b32 v92, v95, v92, s54
	v_and_b32_e32 v89, 0xff00, v89
	v_and_b32_e32 v91, 0xff00, v91
	v_or3_b32 v88, v88, v89, v90
	v_or3_b32 v89, v92, v91, v93
	global_store_dwordx2 v[118:119], v[88:89], off
	s_waitcnt vmcnt(12)
	v_lshlrev_b32_e32 v88, 16, v112
	v_and_b32_e32 v89, 0xffff0000, v112
	v_lshlrev_b32_e32 v90, 16, v113
	v_and_b32_e32 v91, 0xffff0000, v113
	v_lshlrev_b32_e32 v92, 16, v114
	v_and_b32_e32 v93, 0xffff0000, v114
	v_lshlrev_b32_e32 v94, 16, v115
	v_and_b32_e32 v95, 0xffff0000, v115
	v_pk_fma_f32 v[86:87], v[86:87], s[18:19], v[90:91] op_sel_hi:[1,0,1]
	v_pk_fma_f32 v[84:85], v[84:85], s[18:19], v[88:89] op_sel_hi:[1,0,1]
	v_pk_fma_f32 v[90:91], v[80:81], s[18:19], v[92:93] op_sel_hi:[1,0,1]
	v_cvt_pk_bf16_f32 v80, v84, v85
	v_cvt_pk_bf16_f32 v81, v86, v87
	v_pk_fma_f32 v[88:89], v[82:83], s[18:19], v[94:95] op_sel_hi:[1,0,1]
	v_cvt_pk_bf16_f32 v82, v90, v91
	s_nop 0
	v_cvt_pk_bf16_f32 v83, v88, v89
	global_store_dwordx4 v[106:107], v[80:83], off offset:256
	v_mul_f32_e32 v92, v117, v89
	s_nop 0
	v_mul_f32_e32 v81, v117, v85
	v_mul_f32_e32 v80, v117, v84
	v_mul_f32_e32 v82, v117, v86
	v_mul_f32_e32 v83, v117, v87
	v_med3_f32 v81, v81, s53, v199
	v_med3_f32 v80, v80, s53, v199
	v_rndne_f32_e32 v81, v81
	v_med3_f32 v82, v82, s53, v199
	v_med3_f32 v83, v83, s53, v199
	v_rndne_f32_e32 v80, v80
	v_cvt_i32_f32_e32 v81, v81
	v_rndne_f32_e32 v82, v82
	v_rndne_f32_e32 v83, v83
	v_cvt_i32_f32_e32 v80, v80
	v_cvt_i32_f32_sdwa v82, v82 dst_sel:WORD_1 dst_unused:UNUSED_PAD src0_sel:DWORD
	v_cvt_i32_f32_e32 v83, v83
	v_lshlrev_b32_e32 v81, 8, v81
	v_and_b32_e32 v81, 0xff00, v81
	v_and_b32_e32 v82, 0xff0000, v82
	v_perm_b32 v80, v83, v80, s54
	v_or3_b32 v82, v80, v81, v82
	v_mul_f32_e32 v81, v117, v91
	v_med3_f32 v81, v81, s53, v199
	v_rndne_f32_e32 v81, v81
	v_cvt_i32_f32_e32 v81, v81
	v_mul_f32_e32 v80, v117, v90
	v_med3_f32 v80, v80, s53, v199
	v_rndne_f32_e32 v80, v80
	v_mul_f32_e32 v83, v117, v88
	v_cvt_i32_f32_e32 v93, v80
	v_lshlrev_b32_e32 v80, 8, v81
	v_and_b32_e32 v94, 0xff00, v80
	v_med3_f32 v80, v83, s53, v199
	v_mul_f32_e32 v81, v85, v85
	v_mul_f32_e32 v83, v87, v87
	v_fmac_f32_e32 v81, v84, v84
	v_fmac_f32_e32 v83, v86, v86
	v_add_f32_e32 v81, v81, v83
	v_mul_f32_e32 v83, v91, v91
	v_fmac_f32_e32 v83, v90, v90
	v_add_f32_e32 v81, v83, v81
	v_mul_f32_e32 v83, v89, v89
	v_fmac_f32_e32 v83, v88, v88
	v_add_f32_e32 v81, v83, v81
	v_add_f32_e32 v81, v116, v81
	ds_bpermute_b32 v83, v144, v81
	v_rndne_f32_e32 v80, v80
	v_cvt_i32_f32_sdwa v84, v80 dst_sel:WORD_1 dst_unused:UNUSED_PAD src0_sel:DWORD
	v_med3_f32 v80, v92, s53, v199
	v_rndne_f32_e32 v80, v80
	v_cvt_i32_f32_e32 v85, v80
	s_waitcnt lgkmcnt(0)
	v_add_f32_e32 v80, v81, v83
	ds_bpermute_b32 v81, v145, v80
	v_and_b32_e32 v83, 0xff0000, v84
	v_perm_b32 v84, v85, v93, s54
	v_or3_b32 v83, v84, v94, v83
	global_store_dwordx2 v[118:119], v[82:83], off offset:128
	s_and_saveexec_b64 s[28:29], s[2:3]
	s_cbranch_execz .LBB0_1268
	s_waitcnt lgkmcnt(0)
	v_add_f32_e32 v80, v80, v81
	v_fma_f32 v80, v80, s55, 0.5
	v_trunc_f32_e32 v80, v80
	v_mul_f32_e32 v81, 0x2f800000, v80
	v_floor_f32_e32 v81, v81
	v_fmac_f32_e32 v80, 0xcf800000, v81
	v_cvt_u32_f32_e32 v80, v80
	v_cvt_u32_f32_e32 v81, v81
	v_lshl_add_u64 v[82:83], v[104:105], 3, s[8:9]
	v_mov_b32_e32 v228, v82
	v_mov_b32_e32 v229, v83
	v_mov_b32_e32 v246, v80
	v_mov_b32_e32 v247, v81
.LBB0_1268:
	s_or_b64 exec, exec, s[28:29]
	s_waitcnt lgkmcnt(0)
	v_mov_b32_e32 v80, v240
	v_mov_b32_e32 v81, v241
	s_waitcnt vmcnt(12)
	v_lshlrev_b32_e32 v84, 16, v20
	v_and_b32_e32 v85, 0xffff0000, v20
	s_waitcnt vmcnt(11)
	v_lshlrev_b32_e32 v88, 16, v16
	v_and_b32_e32 v89, 0xffff0000, v16
	v_lshlrev_b32_e32 v16, 16, v17
	v_and_b32_e32 v17, 0xffff0000, v17
	v_lshlrev_b32_e32 v20, 16, v21
	v_and_b32_e32 v21, 0xffff0000, v21
	v_lshlrev_b32_e32 v86, 16, v22
	v_and_b32_e32 v87, 0xffff0000, v22
	v_lshlrev_b32_e32 v22, 16, v23
	v_and_b32_e32 v23, 0xffff0000, v23
	v_lshlrev_b32_e32 v90, 16, v18
	v_and_b32_e32 v91, 0xffff0000, v18
	v_lshlrev_b32_e32 v18, 16, v19
	v_and_b32_e32 v19, 0xffff0000, v19
	v_pk_fma_f32 v[76:77], v[76:77], s[18:19], v[84:85] op_sel_hi:[1,0,1]
	v_pk_fma_f32 v[70:71], v[70:71], s[18:19], v[16:17] op_sel_hi:[1,0,1]
	v_cvt_pk_bf16_f32 v16, v76, v77
	v_pk_fma_f32 v[20:21], v[78:79], s[18:19], v[20:21] op_sel_hi:[1,0,1]
	v_pk_fma_f32 v[22:23], v[74:75], s[18:19], v[22:23] op_sel_hi:[1,0,1]
	v_pk_fma_f32 v[72:73], v[72:73], s[18:19], v[86:87] op_sel_hi:[1,0,1]
	v_pk_fma_f32 v[66:67], v[66:67], s[18:19], v[18:19] op_sel_hi:[1,0,1]
	v_cvt_pk_bf16_f32 v17, v20, v21
	v_cvt_pk_bf16_f32 v18, v72, v73
	v_cvt_pk_bf16_f32 v19, v22, v23
	global_store_dwordx4 v[102:103], v[16:19], off
	v_lshlrev_b64 v[82:83], 12, v[100:101]
	v_lshl_add_u64 v[82:83], v[82:83], 0, v[24:25]
	v_mul_f32_e32 v78, v77, v77
	v_mul_f32_e32 v79, v21, v21
	v_lshl_add_u64 v[74:75], s[10:11], 0, v[82:83]
	v_mul_f32_e32 v82, v73, v73
	v_fmac_f32_e32 v78, v76, v76
	v_fmac_f32_e32 v79, v20, v20
	v_mul_f32_e32 v83, v23, v23
	v_fmac_f32_e32 v82, v72, v72
	v_fmac_f32_e32 v83, v22, v22
	v_pk_fma_f32 v[68:69], v[68:69], s[18:19], v[88:89] op_sel_hi:[1,0,1]
	v_pk_fma_f32 v[64:65], v[64:65], s[18:19], v[90:91] op_sel_hi:[1,0,1]
	s_waitcnt vmcnt(9)
	v_ffbh_u32_e32 v16, v81
	v_min_u32_e32 v18, 32, v16
	v_lshlrev_b64 v[16:17], v18, v[80:81]
	v_min_u32_e32 v16, 1, v16
	v_or_b32_e32 v16, v17, v16
	v_cvt_f32_u32_e32 v16, v16
	v_sub_u32_e32 v17, 32, v18
	v_ldexp_f32 v16, v16, v17
	v_fmamk_f32 v16, v16, 0x2f800000, v197
	v_rsq_f32_e32 v16, v16
	v_add_f32_e32 v17, v78, v79
	v_add_f32_e32 v17, v82, v17
	v_add_f32_e32 v78, v83, v17
	v_mul_f32_e32 v79, 0x41fe0000, v16
	v_mul_f32_e32 v16, v76, v79
	v_mul_f32_e32 v17, v77, v79
	v_mul_f32_e32 v19, v21, v79
	v_mul_f32_e32 v21, v73, v79
	v_mul_f32_e32 v18, v20, v79
	v_mul_f32_e32 v20, v72, v79
	v_mul_f32_e32 v22, v22, v79
	v_mul_f32_e32 v23, v23, v79
	v_med3_f32 v16, v16, s53, v199
	v_med3_f32 v17, v17, s53, v199
	v_med3_f32 v19, v19, s53, v199
	v_med3_f32 v21, v21, s53, v199
	v_med3_f32 v18, v18, s53, v199
	v_med3_f32 v20, v20, s53, v199
	v_med3_f32 v22, v22, s53, v199
	v_med3_f32 v23, v23, s53, v199
	v_rndne_f32_e32 v16, v16
	v_rndne_f32_e32 v17, v17
	v_rndne_f32_e32 v19, v19
	v_rndne_f32_e32 v21, v21
	v_rndne_f32_e32 v18, v18
	v_rndne_f32_e32 v20, v20
	v_rndne_f32_e32 v22, v22
	v_rndne_f32_e32 v23, v23
	v_cvt_i32_f32_e32 v16, v16
	v_cvt_i32_f32_e32 v17, v17
	v_cvt_i32_f32_e32 v19, v19
	v_cvt_i32_f32_e32 v21, v21
	v_cvt_i32_f32_sdwa v18, v18 dst_sel:WORD_1 dst_unused:UNUSED_PAD src0_sel:DWORD
	v_cvt_i32_f32_e32 v20, v20
	v_cvt_i32_f32_sdwa v22, v22 dst_sel:WORD_1 dst_unused:UNUSED_PAD src0_sel:DWORD
	v_cvt_i32_f32_e32 v23, v23
	v_lshlrev_b32_e32 v17, 8, v17
	v_perm_b32 v16, v19, v16, s54
	v_lshlrev_b32_e32 v19, 8, v21
	v_and_b32_e32 v18, 0xff0000, v18
	v_and_b32_e32 v21, 0xff0000, v22
	v_perm_b32 v20, v23, v20, s54
	v_and_b32_e32 v17, 0xff00, v17
	v_and_b32_e32 v19, 0xff00, v19
	v_or3_b32 v16, v16, v17, v18
	v_or3_b32 v17, v20, v19, v21
	v_mul_f32_e32 v73, v69, v79
	global_store_dwordx2 v[74:75], v[16:17], off
	v_cvt_pk_bf16_f32 v16, v68, v69
	v_cvt_pk_bf16_f32 v17, v70, v71
	v_mul_f32_e32 v72, v68, v79
	v_mul_f32_e32 v76, v70, v79
	v_mul_f32_e32 v77, v71, v79
	v_cvt_pk_bf16_f32 v18, v64, v65
	v_cvt_pk_bf16_f32 v19, v66, v67
	global_store_dwordx4 v[102:103], v[16:19], off offset:256
	v_med3_f32 v72, v72, s53, v199
	v_mul_f32_e32 v20, v67, v79
	v_med3_f32 v17, v73, s53, v199
	v_rndne_f32_e32 v17, v17
	v_med3_f32 v18, v76, s53, v199
	v_med3_f32 v19, v77, s53, v199
	v_rndne_f32_e32 v16, v72
	v_cvt_i32_f32_e32 v17, v17
	v_rndne_f32_e32 v18, v18
	v_rndne_f32_e32 v19, v19
	v_cvt_i32_f32_e32 v16, v16
	v_cvt_i32_f32_sdwa v18, v18 dst_sel:WORD_1 dst_unused:UNUSED_PAD src0_sel:DWORD
	v_cvt_i32_f32_e32 v19, v19
	v_lshlrev_b32_e32 v17, 8, v17
	v_and_b32_e32 v17, 0xff00, v17
	v_and_b32_e32 v18, 0xff0000, v18
	v_perm_b32 v16, v19, v16, s54
	v_or3_b32 v18, v16, v17, v18
	v_mul_f32_e32 v17, v65, v79
	v_med3_f32 v17, v17, s53, v199
	v_rndne_f32_e32 v17, v17
	v_cvt_i32_f32_e32 v17, v17
	v_mul_f32_e32 v16, v64, v79
	v_med3_f32 v16, v16, s53, v199
	v_rndne_f32_e32 v16, v16
	v_mul_f32_e32 v19, v66, v79
	v_cvt_i32_f32_e32 v21, v16
	v_lshlrev_b32_e32 v16, 8, v17
	v_and_b32_e32 v22, 0xff00, v16
	v_med3_f32 v16, v19, s53, v199
	v_mul_f32_e32 v17, v69, v69
	v_mul_f32_e32 v19, v71, v71
	v_fmac_f32_e32 v17, v68, v68
	v_fmac_f32_e32 v19, v70, v70
	v_add_f32_e32 v17, v17, v19
	v_mul_f32_e32 v19, v65, v65
	v_fmac_f32_e32 v19, v64, v64
	v_add_f32_e32 v17, v19, v17
	v_mul_f32_e32 v19, v67, v67
	v_fmac_f32_e32 v19, v66, v66
	v_add_f32_e32 v17, v19, v17
	v_add_f32_e32 v17, v78, v17
	ds_bpermute_b32 v19, v144, v17
	v_rndne_f32_e32 v16, v16
	v_cvt_i32_f32_sdwa v23, v16 dst_sel:WORD_1 dst_unused:UNUSED_PAD src0_sel:DWORD
	v_med3_f32 v16, v20, s53, v199
	v_rndne_f32_e32 v16, v16
	v_cvt_i32_f32_e32 v20, v16
	s_waitcnt lgkmcnt(0)
	v_add_f32_e32 v16, v17, v19
	ds_bpermute_b32 v17, v145, v16
	v_and_b32_e32 v19, 0xff0000, v23
	v_perm_b32 v20, v20, v21, s54
	v_or3_b32 v19, v20, v22, v19
	global_store_dwordx2 v[74:75], v[18:19], off offset:128
	s_and_saveexec_b64 s[28:29], s[2:3]
	s_cbranch_execz .LBB0_1270
	s_waitcnt lgkmcnt(0)
	v_add_f32_e32 v16, v16, v17
	v_fma_f32 v16, v16, s55, 0.5
	v_trunc_f32_e32 v16, v16
	v_mul_f32_e32 v17, 0x2f800000, v16
	v_floor_f32_e32 v17, v17
	v_fmac_f32_e32 v16, 0xcf800000, v17
	v_cvt_u32_f32_e32 v16, v16
	v_cvt_u32_f32_e32 v17, v17
	v_lshl_add_u64 v[18:19], v[100:101], 3, s[8:9]
	v_mov_b32_e32 v248, v16
	v_mov_b32_e32 v249, v17
.LBB0_1270:
	s_or_b64 exec, exec, s[28:29]
	s_waitcnt lgkmcnt(0)
	v_mov_b32_e32 v16, v242
	v_mov_b32_e32 v17, v243
	v_lshlrev_b32_e32 v20, 16, v12
	v_and_b32_e32 v21, 0xffff0000, v12
	v_lshlrev_b32_e32 v64, 16, v8
	v_and_b32_e32 v65, 0xffff0000, v8
	v_lshlrev_b32_e32 v8, 16, v9
	v_and_b32_e32 v9, 0xffff0000, v9
	v_lshlrev_b32_e32 v12, 16, v13
	v_and_b32_e32 v13, 0xffff0000, v13
	v_lshlrev_b32_e32 v22, 16, v14
	v_and_b32_e32 v23, 0xffff0000, v14
	v_lshlrev_b32_e32 v14, 16, v15
	v_and_b32_e32 v15, 0xffff0000, v15
	v_lshlrev_b32_e32 v66, 16, v10
	v_and_b32_e32 v67, 0xffff0000, v10
	v_lshlrev_b32_e32 v10, 16, v11
	v_and_b32_e32 v11, 0xffff0000, v11
	v_pk_fma_f32 v[20:21], v[60:61], s[18:19], v[20:21] op_sel_hi:[1,0,1]
	v_pk_fma_f32 v[54:55], v[54:55], s[18:19], v[8:9] op_sel_hi:[1,0,1]
	v_cvt_pk_bf16_f32 v8, v20, v21
	v_pk_fma_f32 v[12:13], v[62:63], s[18:19], v[12:13] op_sel_hi:[1,0,1]
	v_pk_fma_f32 v[14:15], v[58:59], s[18:19], v[14:15] op_sel_hi:[1,0,1]
	v_pk_fma_f32 v[22:23], v[56:57], s[18:19], v[22:23] op_sel_hi:[1,0,1]
	v_pk_fma_f32 v[50:51], v[50:51], s[18:19], v[10:11] op_sel_hi:[1,0,1]
	v_cvt_pk_bf16_f32 v9, v12, v13
	v_cvt_pk_bf16_f32 v10, v22, v23
	v_cvt_pk_bf16_f32 v11, v14, v15
	global_store_dwordx4 v[98:99], v[8:11], off
	v_mul_f32_e32 v56, v21, v21
	v_mul_f32_e32 v57, v13, v13
	v_mul_f32_e32 v58, v23, v23
	v_fmac_f32_e32 v56, v20, v20
	v_fmac_f32_e32 v57, v12, v12
	v_mul_f32_e32 v59, v15, v15
	v_fmac_f32_e32 v58, v22, v22
	v_fmac_f32_e32 v59, v14, v14
	v_lshlrev_b64 v[18:19], 12, v[96:97]
	v_lshl_add_u64 v[18:19], v[18:19], 0, v[24:25]
	v_pk_fma_f32 v[52:53], v[52:53], s[18:19], v[64:65] op_sel_hi:[1,0,1]
	v_lshl_add_u64 v[18:19], s[10:11], 0, v[18:19]
	v_pk_fma_f32 v[48:49], v[48:49], s[18:19], v[66:67] op_sel_hi:[1,0,1]
	s_waitcnt vmcnt(13)
	v_ffbh_u32_e32 v8, v17
	v_min_u32_e32 v10, 32, v8
	v_lshlrev_b64 v[8:9], v10, v[16:17]
	v_min_u32_e32 v8, 1, v8
	v_or_b32_e32 v8, v9, v8
	v_cvt_f32_u32_e32 v8, v8
	v_sub_u32_e32 v9, 32, v10
	v_ldexp_f32 v8, v8, v9
	v_fmamk_f32 v8, v8, 0x2f800000, v197
	v_rsq_f32_e32 v8, v8
	v_add_f32_e32 v9, v56, v57
	v_add_f32_e32 v9, v58, v9
	v_add_f32_e32 v16, v59, v9
	v_mul_f32_e32 v17, 0x41fe0000, v8
	v_mul_f32_e32 v8, v20, v17
	v_mul_f32_e32 v9, v21, v17
	v_mul_f32_e32 v11, v13, v17
	v_mul_f32_e32 v13, v23, v17
	v_mul_f32_e32 v10, v12, v17
	v_mul_f32_e32 v12, v22, v17
	v_mul_f32_e32 v14, v14, v17
	v_mul_f32_e32 v15, v15, v17
	v_med3_f32 v8, v8, s53, v199
	v_med3_f32 v9, v9, s53, v199
	v_med3_f32 v11, v11, s53, v199
	v_med3_f32 v13, v13, s53, v199
	v_med3_f32 v10, v10, s53, v199
	v_med3_f32 v12, v12, s53, v199
	v_med3_f32 v14, v14, s53, v199
	v_med3_f32 v15, v15, s53, v199
	v_rndne_f32_e32 v8, v8
	v_rndne_f32_e32 v9, v9
	v_rndne_f32_e32 v11, v11
	v_rndne_f32_e32 v13, v13
	v_rndne_f32_e32 v10, v10
	v_rndne_f32_e32 v12, v12
	v_rndne_f32_e32 v14, v14
	v_rndne_f32_e32 v15, v15
	v_cvt_i32_f32_e32 v8, v8
	v_cvt_i32_f32_e32 v9, v9
	v_cvt_i32_f32_e32 v11, v11
	v_cvt_i32_f32_e32 v13, v13
	v_cvt_i32_f32_sdwa v10, v10 dst_sel:WORD_1 dst_unused:UNUSED_PAD src0_sel:DWORD
	v_cvt_i32_f32_e32 v12, v12
	v_cvt_i32_f32_sdwa v14, v14 dst_sel:WORD_1 dst_unused:UNUSED_PAD src0_sel:DWORD
	v_cvt_i32_f32_e32 v15, v15
	v_lshlrev_b32_e32 v9, 8, v9
	v_perm_b32 v8, v11, v8, s54
	v_lshlrev_b32_e32 v11, 8, v13
	v_and_b32_e32 v10, 0xff0000, v10
	v_and_b32_e32 v13, 0xff0000, v14
	v_perm_b32 v12, v15, v12, s54
	v_and_b32_e32 v9, 0xff00, v9
	v_and_b32_e32 v11, 0xff00, v11
	v_or3_b32 v8, v8, v9, v10
	v_or3_b32 v9, v12, v11, v13
	v_mul_f32_e32 v21, v53, v17
	global_store_dwordx2 v[18:19], v[8:9], off
	v_cvt_pk_bf16_f32 v8, v52, v53
	v_cvt_pk_bf16_f32 v9, v54, v55
	v_mul_f32_e32 v20, v52, v17
	v_mul_f32_e32 v22, v54, v17
	v_mul_f32_e32 v23, v55, v17
	v_cvt_pk_bf16_f32 v10, v48, v49
	v_cvt_pk_bf16_f32 v11, v50, v51
	global_store_dwordx4 v[98:99], v[8:11], off offset:256
	v_med3_f32 v20, v20, s53, v199
	v_mul_f32_e32 v12, v51, v17
	v_med3_f32 v9, v21, s53, v199
	v_rndne_f32_e32 v9, v9
	v_med3_f32 v10, v22, s53, v199
	v_med3_f32 v11, v23, s53, v199
	v_rndne_f32_e32 v8, v20
	v_cvt_i32_f32_e32 v9, v9
	v_rndne_f32_e32 v10, v10
	v_rndne_f32_e32 v11, v11
	v_cvt_i32_f32_e32 v8, v8
	v_cvt_i32_f32_sdwa v10, v10 dst_sel:WORD_1 dst_unused:UNUSED_PAD src0_sel:DWORD
	v_cvt_i32_f32_e32 v11, v11
	v_lshlrev_b32_e32 v9, 8, v9
	v_and_b32_e32 v9, 0xff00, v9
	v_and_b32_e32 v10, 0xff0000, v10
	v_perm_b32 v8, v11, v8, s54
	v_or3_b32 v10, v8, v9, v10
	v_mul_f32_e32 v9, v49, v17
	v_med3_f32 v9, v9, s53, v199
	v_rndne_f32_e32 v9, v9
	v_cvt_i32_f32_e32 v9, v9
	v_mul_f32_e32 v8, v48, v17
	v_med3_f32 v8, v8, s53, v199
	v_rndne_f32_e32 v8, v8
	v_mul_f32_e32 v11, v50, v17
	v_cvt_i32_f32_e32 v13, v8
	v_lshlrev_b32_e32 v8, 8, v9
	v_and_b32_e32 v14, 0xff00, v8
	v_med3_f32 v8, v11, s53, v199
	v_mul_f32_e32 v9, v53, v53
	v_mul_f32_e32 v11, v55, v55
	v_fmac_f32_e32 v9, v52, v52
	v_fmac_f32_e32 v11, v54, v54
	v_add_f32_e32 v9, v9, v11
	v_mul_f32_e32 v11, v49, v49
	v_fmac_f32_e32 v11, v48, v48
	v_add_f32_e32 v9, v11, v9
	v_mul_f32_e32 v11, v51, v51
	v_fmac_f32_e32 v11, v50, v50
	v_add_f32_e32 v9, v11, v9
	v_add_f32_e32 v9, v16, v9
	ds_bpermute_b32 v11, v144, v9
	v_rndne_f32_e32 v8, v8
	v_cvt_i32_f32_sdwa v15, v8 dst_sel:WORD_1 dst_unused:UNUSED_PAD src0_sel:DWORD
	v_med3_f32 v8, v12, s53, v199
	v_rndne_f32_e32 v8, v8
	v_cvt_i32_f32_e32 v12, v8
	s_waitcnt lgkmcnt(0)
	v_add_f32_e32 v8, v9, v11
	ds_bpermute_b32 v9, v145, v8
	v_and_b32_e32 v11, 0xff0000, v15
	v_perm_b32 v12, v12, v13, s54
	v_or3_b32 v11, v12, v14, v11
	global_store_dwordx2 v[18:19], v[10:11], off offset:128
	s_and_saveexec_b64 s[28:29], s[2:3]
	s_cbranch_execz .LBB0_1272
	s_waitcnt lgkmcnt(0)
	v_add_f32_e32 v8, v8, v9
	v_fma_f32 v8, v8, s55, 0.5
	v_trunc_f32_e32 v8, v8
	v_mul_f32_e32 v9, 0x2f800000, v8
	v_floor_f32_e32 v9, v9
	v_fmac_f32_e32 v8, 0xcf800000, v9
	v_cvt_u32_f32_e32 v8, v8
	v_cvt_u32_f32_e32 v9, v9
	v_lshl_add_u64 v[10:11], v[96:97], 3, s[8:9]
	v_mov_b32_e32 v250, v8
	v_mov_b32_e32 v251, v9
.LBB0_1272:
	s_or_b64 exec, exec, s[28:29]
	s_waitcnt lgkmcnt(0)
	v_mov_b32_e32 v8, v244
	v_mov_b32_e32 v9, v245
	v_lshlrev_b32_e32 v12, 16, v4
	v_and_b32_e32 v13, 0xffff0000, v4
	v_lshlrev_b32_e32 v16, 16, v0
	v_and_b32_e32 v17, 0xffff0000, v0
	v_lshlrev_b32_e32 v0, 16, v1
	v_and_b32_e32 v1, 0xffff0000, v1
	v_lshlrev_b32_e32 v4, 16, v5
	v_and_b32_e32 v5, 0xffff0000, v5
	v_lshlrev_b32_e32 v14, 16, v6
	v_and_b32_e32 v15, 0xffff0000, v6
	v_lshlrev_b32_e32 v6, 16, v7
	v_and_b32_e32 v7, 0xffff0000, v7
	v_lshlrev_b32_e32 v18, 16, v2
	v_and_b32_e32 v19, 0xffff0000, v2
	v_lshlrev_b32_e32 v2, 16, v3
	v_and_b32_e32 v3, 0xffff0000, v3
	v_pk_fma_f32 v[12:13], v[44:45], s[18:19], v[12:13] op_sel_hi:[1,0,1]
	v_pk_fma_f32 v[20:21], v[38:39], s[18:19], v[0:1] op_sel_hi:[1,0,1]
	v_cvt_pk_bf16_f32 v0, v12, v13
	v_pk_fma_f32 v[4:5], v[46:47], s[18:19], v[4:5] op_sel_hi:[1,0,1]
	v_pk_fma_f32 v[6:7], v[42:43], s[18:19], v[6:7] op_sel_hi:[1,0,1]
	v_pk_fma_f32 v[14:15], v[40:41], s[18:19], v[14:15] op_sel_hi:[1,0,1]
	v_pk_fma_f32 v[22:23], v[34:35], s[18:19], v[2:3] op_sel_hi:[1,0,1]
	v_cvt_pk_bf16_f32 v1, v4, v5
	v_cvt_pk_bf16_f32 v2, v14, v15
	v_cvt_pk_bf16_f32 v3, v6, v7
	global_store_dwordx4 v[28:29], v[0:3], off
	v_lshlrev_b64 v[10:11], 12, v[30:31]
	v_lshl_add_u64 v[10:11], v[10:11], 0, v[24:25]
	v_mul_f32_e32 v24, v13, v13
	v_mul_f32_e32 v25, v5, v5
	v_mul_f32_e32 v26, v15, v15
	v_fmac_f32_e32 v24, v12, v12
	v_fmac_f32_e32 v25, v4, v4
	v_mul_f32_e32 v27, v7, v7
	v_fmac_f32_e32 v26, v14, v14
	v_fmac_f32_e32 v27, v6, v6
	v_pk_fma_f32 v[16:17], v[36:37], s[18:19], v[16:17] op_sel_hi:[1,0,1]
	v_lshl_add_u64 v[10:11], s[10:11], 0, v[10:11]
	v_pk_fma_f32 v[18:19], v[32:33], s[18:19], v[18:19] op_sel_hi:[1,0,1]
	s_waitcnt vmcnt(17)
	v_ffbh_u32_e32 v0, v9
	v_min_u32_e32 v2, 32, v0
	v_lshlrev_b64 v[0:1], v2, v[8:9]
	v_min_u32_e32 v0, 1, v0
	v_or_b32_e32 v0, v1, v0
	v_cvt_f32_u32_e32 v0, v0
	v_sub_u32_e32 v1, 32, v2
	v_ldexp_f32 v0, v0, v1
	v_fmamk_f32 v0, v0, 0x2f800000, v197
	v_rsq_f32_e32 v0, v0
	v_add_f32_e32 v1, v24, v25
	v_add_f32_e32 v1, v26, v1
	v_add_f32_e32 v8, v27, v1
	v_mul_f32_e32 v9, 0x41fe0000, v0
	v_mul_f32_e32 v0, v12, v9
	v_mul_f32_e32 v1, v13, v9
	v_mul_f32_e32 v3, v5, v9
	v_mul_f32_e32 v5, v15, v9
	v_mul_f32_e32 v2, v4, v9
	v_mul_f32_e32 v4, v14, v9
	v_mul_f32_e32 v6, v6, v9
	v_mul_f32_e32 v7, v7, v9
	v_med3_f32 v0, v0, s53, v199
	v_med3_f32 v1, v1, s53, v199
	v_med3_f32 v3, v3, s53, v199
	v_med3_f32 v5, v5, s53, v199
	v_med3_f32 v2, v2, s53, v199
	v_med3_f32 v4, v4, s53, v199
	v_med3_f32 v6, v6, s53, v199
	v_med3_f32 v7, v7, s53, v199
	v_rndne_f32_e32 v0, v0
	v_rndne_f32_e32 v1, v1
	v_rndne_f32_e32 v3, v3
	v_rndne_f32_e32 v5, v5
	v_rndne_f32_e32 v2, v2
	v_rndne_f32_e32 v4, v4
	v_rndne_f32_e32 v6, v6
	v_rndne_f32_e32 v7, v7
	v_cvt_i32_f32_e32 v0, v0
	v_cvt_i32_f32_e32 v1, v1
	v_cvt_i32_f32_e32 v3, v3
	v_cvt_i32_f32_e32 v5, v5
	v_cvt_i32_f32_sdwa v2, v2 dst_sel:WORD_1 dst_unused:UNUSED_PAD src0_sel:DWORD
	v_cvt_i32_f32_e32 v4, v4
	v_cvt_i32_f32_sdwa v6, v6 dst_sel:WORD_1 dst_unused:UNUSED_PAD src0_sel:DWORD
	v_cvt_i32_f32_e32 v7, v7
	v_lshlrev_b32_e32 v1, 8, v1
	v_perm_b32 v0, v3, v0, s54
	v_lshlrev_b32_e32 v3, 8, v5
	v_and_b32_e32 v2, 0xff0000, v2
	v_and_b32_e32 v5, 0xff0000, v6
	v_perm_b32 v4, v7, v4, s54
	v_and_b32_e32 v1, 0xff00, v1
	v_and_b32_e32 v3, 0xff00, v3
	v_or3_b32 v0, v0, v1, v2
	v_or3_b32 v1, v4, v3, v5
	v_mul_f32_e32 v13, v17, v9
	global_store_dwordx2 v[10:11], v[0:1], off
	v_cvt_pk_bf16_f32 v0, v16, v17
	v_cvt_pk_bf16_f32 v1, v20, v21
	v_mul_f32_e32 v12, v16, v9
	v_mul_f32_e32 v14, v20, v9
	v_mul_f32_e32 v15, v21, v9
	v_cvt_pk_bf16_f32 v2, v18, v19
	v_cvt_pk_bf16_f32 v3, v22, v23
	global_store_dwordx4 v[28:29], v[0:3], off offset:256
	v_med3_f32 v12, v12, s53, v199
	v_mul_f32_e32 v4, v23, v9
	v_med3_f32 v1, v13, s53, v199
	v_rndne_f32_e32 v1, v1
	v_med3_f32 v2, v14, s53, v199
	v_med3_f32 v3, v15, s53, v199
	v_rndne_f32_e32 v0, v12
	v_cvt_i32_f32_e32 v1, v1
	v_rndne_f32_e32 v2, v2
	v_rndne_f32_e32 v3, v3
	v_cvt_i32_f32_e32 v0, v0
	v_cvt_i32_f32_sdwa v2, v2 dst_sel:WORD_1 dst_unused:UNUSED_PAD src0_sel:DWORD
	v_cvt_i32_f32_e32 v3, v3
	v_lshlrev_b32_e32 v1, 8, v1
	v_and_b32_e32 v1, 0xff00, v1
	v_and_b32_e32 v2, 0xff0000, v2
	v_perm_b32 v0, v3, v0, s54
	v_or3_b32 v2, v0, v1, v2
	v_mul_f32_e32 v1, v19, v9
	v_med3_f32 v1, v1, s53, v199
	v_rndne_f32_e32 v1, v1
	v_cvt_i32_f32_e32 v1, v1
	v_mul_f32_e32 v0, v18, v9
	v_med3_f32 v0, v0, s53, v199
	v_rndne_f32_e32 v0, v0
	v_mul_f32_e32 v3, v22, v9
	v_cvt_i32_f32_e32 v5, v0
	v_lshlrev_b32_e32 v0, 8, v1
	v_and_b32_e32 v6, 0xff00, v0
	v_med3_f32 v0, v3, s53, v199
	v_mul_f32_e32 v1, v17, v17
	v_mul_f32_e32 v3, v21, v21
	v_fmac_f32_e32 v1, v16, v16
	v_fmac_f32_e32 v3, v20, v20
	v_add_f32_e32 v1, v1, v3
	v_mul_f32_e32 v3, v19, v19
	v_fmac_f32_e32 v3, v18, v18
	v_add_f32_e32 v1, v3, v1
	v_mul_f32_e32 v3, v23, v23
	v_fmac_f32_e32 v3, v22, v22
	v_add_f32_e32 v1, v3, v1
	v_add_f32_e32 v1, v8, v1
	ds_bpermute_b32 v3, v144, v1
	v_rndne_f32_e32 v0, v0
	v_cvt_i32_f32_sdwa v7, v0 dst_sel:WORD_1 dst_unused:UNUSED_PAD src0_sel:DWORD
	v_med3_f32 v0, v4, s53, v199
	v_rndne_f32_e32 v0, v0
	v_cvt_i32_f32_e32 v4, v0
	s_waitcnt lgkmcnt(0)
	v_add_f32_e32 v0, v1, v3
	ds_bpermute_b32 v1, v145, v0
	v_and_b32_e32 v3, 0xff0000, v7
	v_perm_b32 v4, v4, v5, s54
	v_or3_b32 v3, v4, v6, v3
	global_store_dwordx2 v[10:11], v[2:3], off offset:128
	s_and_saveexec_b64 s[28:29], s[2:3]
	s_cbranch_execz .LBB0_1274
	s_waitcnt lgkmcnt(0)
	v_add_f32_e32 v0, v0, v1
	v_fma_f32 v0, v0, s55, 0.5
	v_trunc_f32_e32 v0, v0
	v_mul_f32_e32 v1, 0x2f800000, v0
	v_floor_f32_e32 v1, v1
	v_fmac_f32_e32 v0, 0xcf800000, v1
	v_cvt_u32_f32_e32 v0, v0
	v_cvt_u32_f32_e32 v1, v1
	v_lshl_add_u64 v[2:3], v[30:31], 3, s[8:9]
	v_mov_b32_e32 v252, v0
	v_mov_b32_e32 v253, v1
.LBB0_1274:
	s_or_b64 exec, exec, s[28:29]
	s_and_saveexec_b64 s[96:97], s[2:3]
	global_atomic_add_x2 v[228:229], v[246:247], off
	global_atomic_add_x2 v[228:229], v[248:249], off offset:128
	global_atomic_add_x2 v[228:229], v[250:251], off offset:256
	global_atomic_add_x2 v[228:229], v[252:253], off offset:384
	s_mov_b64 exec, s[96:97]
	s_andn2_b64 vcc, exec, s[4:5]
	s_mov_b64 s[4:5], -1
	s_cbranch_vccnz .LBB0_1247
	s_andn2_b64 vcc, exec, s[0:1]
	s_cbranch_vccnz .LBB0_1246
	s_barrier
	s_branch .LBB0_1246
